# v33 + first K-iteration peeled with C=0 MFMAs in 7 GEMM instances (accumulator zeroing v_movs removed)
# baseline (speedup 1.0000x reference)
; #define PG8_STAGE(bufoff, gbase, voff) do { _Pragma("unroll") for (int _i = 0; _i < 2; ++_i) glds16_s((gbase), (voff)[_i], ldsb + (unsigned)((bufoff) + _i * 8192)); } while (0)
; #define PG8_LDA(dst, b, h) do { _Pragma("unroll") for (int m = 0; m < 4; ++m) _Pragma("unroll") for (int k = 0; k < 2; ++k) dst[m][k] = *(const LAS h16x8*)(lds + PG8_SA(b, h) + aoff + m * 2048 + k * 1024); } while (0)
; #define PG8_LDB(dst, b, h) do { _Pragma("unroll") for (int n = 0; n < 2; ++n) _Pragma("unroll") for (int k = 0; k < 2; ++k) dst[n][k] = *(const LAS h16x8*)(lds + PG8_SB(b, h) + boff + n * 2048 + k * 1024); } while (0)
; #define PG8_WAIT_V(n) asm volatile("s_waitcnt vmcnt(" #n ")" ::: "memory")
; #define PG8_WAIT_L(n) asm volatile("s_waitcnt lgkmcnt(" #n ")" ::: "memory")
; #define PG8_BAR __builtin_amdgcn_s_barrier()
; #define PG8_SCHED __builtin_amdgcn_sched_barrier(0)
; template <class Prob, class Epi, bool I8 = false, bool ALIGN_EPI = true, bool SP2 = true>
; __device__ __forceinline__ void gemm_phase(LAS unsigned char* lds, int wave, const Prob& P, const Epi& E) {
;     ...
;     for (;;) {
;         const bool has_next = P.next(ui + 1, nxt);
;         const char* nA = has_next ? P.a_tile(nxt) : cA; const char* nB = has_next ? P.b_tile(nxt) : cB;
;         for (int t = 0; t < nt; t += 2) {
;             const bool last = (t == nt - 2);
;             const char* a1 = cA + (size_t)(t + 1) * kstep;
;             const char* a2 = last ? nA : cA + (size_t)(t + 2) * kstep; const char* b2 = last ? nB : cB + (size_t)(t + 2) * kstep;
;             const char* a3 = a2 + kstep; const char* b3 = b2 + kstep;
;             if constexpr (SP2) {
;             PG8_LDB(B0, 0, 0); PG8_LDB(B1, 0, 1); PG8_SCHED; PG8_LDA(At, 0, 0); PG8_STAGE(PG8_SA(1, 1), a1 + hstepA, voffA);
;             PG8_WAIT_V(8); PG8_WAIT_L(0); PG8_BAR; PG8_MMA(0, 0, At, B0); PG8_MMA(0, 1, At, B1); PG8_BAR; PG8_SCHED;
;             PG8_LDA(At, 0, 1); PG8_STAGE(PG8_SB(0, 0), b2, voffB); PG8_STAGE(PG8_SB(0, 1), b2 + hstepB, voffB); PG8_STAGE(PG8_SA(0, 0), a2, voffA);
;     ...
; #pragma unroll
;         for (int a = 0; a < 2; ++a)
; #pragma unroll
;             for (int b = 0; b < 2; ++b)
; #pragma unroll
;                 for (int m = 0; m < 4; ++m)
; #pragma unroll
;                     for (int n = 0; n < 2; ++n) acc[a][b][m][n] = (f32x4){0.f, 0.f, 0.f, 0.f};
.LBB0_463:
	s_ashr_i32 s27, s26, 31
	s_lshl_b64 s[0:1], s[26:27], 20
	s_add_u32 s28, s42, s0
	s_addc_u32 s29, s43, s1
	s_and_b64 s[0:1], s[36:37], exec
	s_cselect_b32 s27, s29, s45
	s_cselect_b32 s83, s28, s44
	s_ashr_i32 s23, s22, 31
	s_lshl_b64 s[0:1], s[22:23], 20
	s_add_u32 s38, s2, s0
	s_addc_u32 s39, s19, s1
	s_and_b64 s[0:1], s[36:37], exec
	s_cselect_b32 s23, s39, s41
	s_cselect_b32 s84, s38, s40
	s_add_u32 s85, s44, 0x100
	s_addc_u32 s86, s45, 0
	s_add_u32 s87, s40, 0x100
	s_addc_u32 s0, s41, 0
	s_add_u32 s40, s44, 0x80080
	s_addc_u32 s41, s45, 0
	s_mov_b32 s1, -2
.Lpeel_464:
	v_add_u32_e32 v140, 0x10000, v146
	ds_read_b128 v[128:131], v140
	ds_read_b128 v[132:135], v140 offset:1024
	ds_read_b128 v[136:139], v140 offset:2048
	ds_read_b128 v[148:151], v140 offset:3072
	v_add_u32_e32 v140, 0x14000, v146
	ds_read_b128 v[152:155], v140
	ds_read_b128 v[156:159], v140 offset:1024
	ds_read_b128 v[160:163], v140 offset:2048
	ds_read_b128 v[164:167], v140 offset:3072
	s_cmp_eq_u32 s1, 28
	s_cselect_b32 s48, s83, s85
	s_cselect_b32 s49, s27, s86
	s_cselect_b32 s46, s84, s87
	s_cselect_b32 s47, s23, s0
	s_add_u32 s44, s48, 0x80
	s_addc_u32 s45, s49, 0
	ds_read_b128 v[168:171], v147
	ds_read_b128 v[172:175], v147 offset:1024
	ds_read_b128 v[176:179], v147 offset:2048
	ds_read_b128 v[180:183], v147 offset:3072
	ds_read_b128 v[184:187], v147 offset:4096
	ds_read_b128 v[188:191], v147 offset:5120
	ds_read_b128 v[192:195], v147 offset:6144
	ds_read_b128 v[196:199], v147 offset:7168
	s_mov_b32 s4, m0
	s_mov_b32 m0, s77
	s_nop 0
	global_load_lds_dwordx4 v142, s[40:41]
	s_mov_b32 m0, s4
	s_nop 0
	s_mov_b32 s4, m0
	s_mov_b32 m0, s79
	s_nop 0
	global_load_lds_dwordx4 v144, s[40:41]
	s_mov_b32 m0, s4
	s_waitcnt vmcnt(8)
	s_waitcnt lgkmcnt(0)
	s_barrier
	s_setprio 1
	s_waitcnt lgkmcnt(7)
	v_mfma_f32_16x16x32_f16 v[124:127], v[128:131], v[168:171], 0
	v_mfma_f32_16x16x32_f16 v[120:123], v[136:139], v[168:171], 0
	s_waitcnt lgkmcnt(5)
	v_mfma_f32_16x16x32_f16 v[116:119], v[128:131], v[176:179], 0
	v_mfma_f32_16x16x32_f16 v[112:115], v[136:139], v[176:179], 0
	s_waitcnt lgkmcnt(3)
	v_mfma_f32_16x16x32_f16 v[108:111], v[128:131], v[184:187], 0
	v_mfma_f32_16x16x32_f16 v[104:107], v[136:139], v[184:187], 0
	s_waitcnt lgkmcnt(1)
	v_mfma_f32_16x16x32_f16 v[100:103], v[128:131], v[192:195], 0
	v_mfma_f32_16x16x32_f16 v[96:99], v[136:139], v[192:195], 0
	v_mfma_f32_16x16x32_f16 v[124:127], v[132:135], v[172:175], v[124:127]
	v_mfma_f32_16x16x32_f16 v[120:123], v[148:151], v[172:175], v[120:123]
	v_mfma_f32_16x16x32_f16 v[116:119], v[132:135], v[180:183], v[116:119]
	v_mfma_f32_16x16x32_f16 v[112:115], v[148:151], v[180:183], v[112:115]
	v_mfma_f32_16x16x32_f16 v[108:111], v[132:135], v[188:191], v[108:111]
	v_mfma_f32_16x16x32_f16 v[104:107], v[148:151], v[188:191], v[104:107]
	s_waitcnt lgkmcnt(0)
	v_mfma_f32_16x16x32_f16 v[100:103], v[132:135], v[196:199], v[100:103]
	v_mfma_f32_16x16x32_f16 v[96:99], v[148:151], v[196:199], v[96:99]
	s_setprio 0
	s_setprio 1
	v_mfma_f32_16x16x32_f16 v[64:67], v[152:155], v[168:171], 0
	v_mfma_f32_16x16x32_f16 v[56:59], v[160:163], v[168:171], 0
	v_mfma_f32_16x16x32_f16 v[52:55], v[152:155], v[176:179], 0
	v_mfma_f32_16x16x32_f16 v[48:51], v[160:163], v[176:179], 0
	v_mfma_f32_16x16x32_f16 v[44:47], v[152:155], v[184:187], 0
	v_mfma_f32_16x16x32_f16 v[40:43], v[160:163], v[184:187], 0
	v_mfma_f32_16x16x32_f16 v[36:39], v[152:155], v[192:195], 0
	v_mfma_f32_16x16x32_f16 v[32:35], v[160:163], v[192:195], 0
	v_mfma_f32_16x16x32_f16 v[64:67], v[156:159], v[172:175], v[64:67]
	v_mfma_f32_16x16x32_f16 v[56:59], v[164:167], v[172:175], v[56:59]
	v_mfma_f32_16x16x32_f16 v[52:55], v[156:159], v[180:183], v[52:55]
	v_mfma_f32_16x16x32_f16 v[48:51], v[164:167], v[180:183], v[48:51]
	v_mfma_f32_16x16x32_f16 v[44:47], v[156:159], v[188:191], v[44:47]
	v_mfma_f32_16x16x32_f16 v[40:43], v[164:167], v[188:191], v[40:43]
	v_mfma_f32_16x16x32_f16 v[36:39], v[156:159], v[196:199], v[36:39]
	v_mfma_f32_16x16x32_f16 v[32:35], v[164:167], v[196:199], v[32:35]
	s_setprio 0
	s_barrier
	ds_read_b128 v[168:171], v147 offset:16384
	ds_read_b128 v[172:175], v147 offset:17408
	ds_read_b128 v[176:179], v147 offset:18432
	ds_read_b128 v[180:183], v147 offset:19456
	ds_read_b128 v[184:187], v147 offset:20480
	ds_read_b128 v[188:191], v147 offset:21504
	ds_read_b128 v[192:195], v147 offset:22528
	ds_read_b128 v[196:199], v147 offset:23552
	s_mov_b32 s4, m0
	s_mov_b32 m0, s51
	s_nop 0
	global_load_lds_dwordx4 v143, s[46:47]
	s_mov_b32 m0, s4
	s_nop 0
	s_mov_b32 s4, m0
	s_mov_b32 m0, s56
	s_nop 0
	global_load_lds_dwordx4 v145, s[46:47]
	s_mov_b32 m0, s4
	s_add_u32 s4, s46, 0x80000
	s_addc_u32 s5, s47, 0
	s_mov_b32 s6, m0
	s_mov_b32 m0, s57
	s_nop 0
	global_load_lds_dwordx4 v143, s[4:5]
	s_mov_b32 m0, s6
	s_nop 0
	s_mov_b32 s6, m0
	s_mov_b32 m0, s60
	s_nop 0
	global_load_lds_dwordx4 v145, s[4:5]
	s_mov_b32 m0, s6
	s_mov_b32 s4, m0
	s_mov_b32 m0, s50
	s_nop 0
	global_load_lds_dwordx4 v142, s[48:49]
	s_mov_b32 m0, s4
	s_nop 0
	s_mov_b32 s4, m0
	s_mov_b32 m0, s61
	s_nop 0
	global_load_lds_dwordx4 v144, s[48:49]
	s_mov_b32 m0, s4
	s_waitcnt vmcnt(8)
	s_waitcnt lgkmcnt(0)
	s_barrier
; #define PG8_STAGE(bufoff, gbase, voff) do { _Pragma("unroll") for (int _i = 0; _i < 2; ++_i) glds16_s((gbase), (voff)[_i], ldsb + (unsigned)((bufoff) + _i * 8192)); } while (0)
; #define PG8_LDA(dst, b, h) do { _Pragma("unroll") for (int m = 0; m < 4; ++m) _Pragma("unroll") for (int k = 0; k < 2; ++k) dst[m][k] = *(const LAS h16x8*)(lds + PG8_SA(b, h) + aoff + m * 2048 + k * 1024); } while (0)
; #define PG8_LDB(dst, b, h) do { _Pragma("unroll") for (int n = 0; n < 2; ++n) _Pragma("unroll") for (int k = 0; k < 2; ++k) dst[n][k] = *(const LAS h16x8*)(lds + PG8_SB(b, h) + boff + n * 2048 + k * 1024); } while (0)
; #define PG8_MMA(ai, bj, At, Bt) do { __builtin_amdgcn_s_setprio(1); _Pragma("unroll") for (int m = 0; m < 4; ++m) _Pragma("unroll") for (int n = 0; n < 2; ++n) _Pragma("unroll") for (int k = 0; k < 2; ++k) \
;         acc[ai][bj][m][n] = mma_step<I8>(Bt[n][k], At[m][k], acc[ai][bj][m][n]); __builtin_amdgcn_s_setprio(0); } while (0)
; #define PG8_WAIT_V(n) asm volatile("s_waitcnt vmcnt(" #n ")" ::: "memory")
; #define PG8_WAIT_L(n) asm volatile("s_waitcnt lgkmcnt(" #n ")" ::: "memory")
; #define PG8_BAR __builtin_amdgcn_s_barrier()
; #define PG8_SCHED __builtin_amdgcn_sched_barrier(0)
; template <class Prob, class Epi, bool I8 = false, bool ALIGN_EPI = true, bool SP2 = true>
; __device__ __forceinline__ void gemm_phase(LAS unsigned char* lds, int wave, const Prob& P, const Epi& E) {
;     ...
;             PG8_WAIT_V(8); PG8_WAIT_L(0); PG8_BAR; PG8_MMA(1, 0, At, B0); PG8_MMA(1, 1, At, B1); PG8_BAR; PG8_SCHED;
;             PG8_LDB(B0, 1, 0); PG8_LDB(B1, 1, 1); PG8_SCHED; PG8_LDA(At, 1, 0); PG8_STAGE(PG8_SA(0, 1), a2 + hstepA, voffA);
;             PG8_WAIT_V(8); PG8_WAIT_L(0); PG8_BAR; PG8_MMA(0, 0, At, B0); PG8_MMA(0, 1, At, B1); PG8_BAR; PG8_SCHED;
	s_setprio 1
	s_waitcnt lgkmcnt(7)
	v_mfma_f32_16x16x32_f16 v[92:95], v[128:131], v[168:171], 0
	v_mfma_f32_16x16x32_f16 v[88:91], v[136:139], v[168:171], 0
	s_waitcnt lgkmcnt(5)
	v_mfma_f32_16x16x32_f16 v[84:87], v[128:131], v[176:179], 0
	v_mfma_f32_16x16x32_f16 v[80:83], v[136:139], v[176:179], 0
	s_waitcnt lgkmcnt(3)
	v_mfma_f32_16x16x32_f16 v[76:79], v[128:131], v[184:187], 0
	v_mfma_f32_16x16x32_f16 v[72:75], v[136:139], v[184:187], 0
	s_waitcnt lgkmcnt(1)
	v_mfma_f32_16x16x32_f16 v[68:71], v[128:131], v[192:195], 0
	v_mfma_f32_16x16x32_f16 v[60:63], v[136:139], v[192:195], 0
	v_mfma_f32_16x16x32_f16 v[92:95], v[132:135], v[172:175], v[92:95]
	v_mfma_f32_16x16x32_f16 v[88:91], v[148:151], v[172:175], v[88:91]
	v_mfma_f32_16x16x32_f16 v[84:87], v[132:135], v[180:183], v[84:87]
	v_mfma_f32_16x16x32_f16 v[80:83], v[148:151], v[180:183], v[80:83]
	v_mfma_f32_16x16x32_f16 v[76:79], v[132:135], v[188:191], v[76:79]
	v_mfma_f32_16x16x32_f16 v[72:75], v[148:151], v[188:191], v[72:75]
	s_waitcnt lgkmcnt(0)
	v_mfma_f32_16x16x32_f16 v[68:71], v[132:135], v[196:199], v[68:71]
	v_mfma_f32_16x16x32_f16 v[60:63], v[148:151], v[196:199], v[60:63]
	s_setprio 0
	s_setprio 1
	v_mfma_f32_16x16x32_f16 v[28:31], v[152:155], v[168:171], 0
	v_mfma_f32_16x16x32_f16 v[24:27], v[160:163], v[168:171], 0
	v_mfma_f32_16x16x32_f16 v[20:23], v[152:155], v[176:179], 0
	v_mfma_f32_16x16x32_f16 v[16:19], v[160:163], v[176:179], 0
	v_mfma_f32_16x16x32_f16 v[12:15], v[152:155], v[184:187], 0
	v_mfma_f32_16x16x32_f16 v[8:11], v[160:163], v[184:187], 0
	v_mfma_f32_16x16x32_f16 v[4:7], v[152:155], v[192:195], 0
	v_mfma_f32_16x16x32_f16 v[0:3], v[160:163], v[192:195], 0
	v_mfma_f32_16x16x32_f16 v[28:31], v[156:159], v[172:175], v[28:31]
	v_mfma_f32_16x16x32_f16 v[24:27], v[164:167], v[172:175], v[24:27]
	v_mfma_f32_16x16x32_f16 v[20:23], v[156:159], v[180:183], v[20:23]
	v_mfma_f32_16x16x32_f16 v[16:19], v[164:167], v[180:183], v[16:19]
	v_mfma_f32_16x16x32_f16 v[12:15], v[156:159], v[188:191], v[12:15]
	v_mfma_f32_16x16x32_f16 v[8:11], v[164:167], v[188:191], v[8:11]
	v_mfma_f32_16x16x32_f16 v[4:7], v[156:159], v[196:199], v[4:7]
	v_mfma_f32_16x16x32_f16 v[0:3], v[164:167], v[196:199], v[0:3]
	s_setprio 0
	s_barrier
	v_add_u32_e32 v140, 0x18000, v146
	ds_read_b128 v[128:131], v140
	ds_read_b128 v[132:135], v140 offset:1024
	ds_read_b128 v[136:139], v140 offset:2048
	ds_read_b128 v[148:151], v140 offset:3072
	v_add_u32_e32 v140, 0x1c000, v146
	ds_read_b128 v[152:155], v140
	ds_read_b128 v[156:159], v140 offset:1024
	ds_read_b128 v[160:163], v140 offset:2048
	ds_read_b128 v[164:167], v140 offset:3072
	ds_read_b128 v[168:171], v147 offset:32768
	ds_read_b128 v[172:175], v147 offset:33792
	ds_read_b128 v[176:179], v147 offset:34816
	ds_read_b128 v[180:183], v147 offset:35840
	ds_read_b128 v[184:187], v147 offset:36864
	ds_read_b128 v[188:191], v147 offset:37888
	ds_read_b128 v[192:195], v147 offset:38912
	ds_read_b128 v[196:199], v147 offset:39936
	s_add_u32 s4, s48, 0x80000
	s_addc_u32 s5, s49, 0
	s_mov_b32 s6, m0
	s_mov_b32 m0, s62
	s_nop 0
	global_load_lds_dwordx4 v142, s[4:5]
	s_mov_b32 m0, s6
	s_nop 0
	s_mov_b32 s6, m0
	s_mov_b32 m0, s63
	s_nop 0
	global_load_lds_dwordx4 v144, s[4:5]
	s_mov_b32 m0, s6
	s_waitcnt vmcnt(8)
	s_waitcnt lgkmcnt(0)
	s_barrier
	s_setprio 1
	s_waitcnt lgkmcnt(7)
	v_mfma_f32_16x16x32_f16 v[124:127], v[128:131], v[168:171], v[124:127]
	v_mfma_f32_16x16x32_f16 v[120:123], v[136:139], v[168:171], v[120:123]
	s_waitcnt lgkmcnt(5)
	v_mfma_f32_16x16x32_f16 v[116:119], v[128:131], v[176:179], v[116:119]
	v_mfma_f32_16x16x32_f16 v[112:115], v[136:139], v[176:179], v[112:115]
	s_waitcnt lgkmcnt(3)
	v_mfma_f32_16x16x32_f16 v[108:111], v[128:131], v[184:187], v[108:111]
	v_mfma_f32_16x16x32_f16 v[104:107], v[136:139], v[184:187], v[104:107]
	s_waitcnt lgkmcnt(1)
	v_mfma_f32_16x16x32_f16 v[100:103], v[128:131], v[192:195], v[100:103]
	v_mfma_f32_16x16x32_f16 v[96:99], v[136:139], v[192:195], v[96:99]
	v_mfma_f32_16x16x32_f16 v[124:127], v[132:135], v[172:175], v[124:127]
	v_mfma_f32_16x16x32_f16 v[120:123], v[148:151], v[172:175], v[120:123]
	v_mfma_f32_16x16x32_f16 v[116:119], v[132:135], v[180:183], v[116:119]
	v_mfma_f32_16x16x32_f16 v[112:115], v[148:151], v[180:183], v[112:115]
	v_mfma_f32_16x16x32_f16 v[108:111], v[132:135], v[188:191], v[108:111]
	v_mfma_f32_16x16x32_f16 v[104:107], v[148:151], v[188:191], v[104:107]
	s_waitcnt lgkmcnt(0)
	v_mfma_f32_16x16x32_f16 v[100:103], v[132:135], v[196:199], v[100:103]
	v_mfma_f32_16x16x32_f16 v[96:99], v[148:151], v[196:199], v[96:99]
	s_setprio 0
	s_setprio 1
	v_mfma_f32_16x16x32_f16 v[64:67], v[152:155], v[168:171], v[64:67]
	v_mfma_f32_16x16x32_f16 v[56:59], v[160:163], v[168:171], v[56:59]
	v_mfma_f32_16x16x32_f16 v[52:55], v[152:155], v[176:179], v[52:55]
	v_mfma_f32_16x16x32_f16 v[48:51], v[160:163], v[176:179], v[48:51]
	v_mfma_f32_16x16x32_f16 v[44:47], v[152:155], v[184:187], v[44:47]
	v_mfma_f32_16x16x32_f16 v[40:43], v[160:163], v[184:187], v[40:43]
	v_mfma_f32_16x16x32_f16 v[36:39], v[152:155], v[192:195], v[36:39]
	v_mfma_f32_16x16x32_f16 v[32:35], v[160:163], v[192:195], v[32:35]
	v_mfma_f32_16x16x32_f16 v[64:67], v[156:159], v[172:175], v[64:67]
	v_mfma_f32_16x16x32_f16 v[56:59], v[164:167], v[172:175], v[56:59]
	v_mfma_f32_16x16x32_f16 v[52:55], v[156:159], v[180:183], v[52:55]
	v_mfma_f32_16x16x32_f16 v[48:51], v[164:167], v[180:183], v[48:51]
	v_mfma_f32_16x16x32_f16 v[44:47], v[156:159], v[188:191], v[44:47]
	v_mfma_f32_16x16x32_f16 v[40:43], v[164:167], v[188:191], v[40:43]
	v_mfma_f32_16x16x32_f16 v[36:39], v[156:159], v[196:199], v[36:39]
	v_mfma_f32_16x16x32_f16 v[32:35], v[164:167], v[196:199], v[32:35]
	s_setprio 0
	s_barrier
; #define PG8_STAGE(bufoff, gbase, voff) do { _Pragma("unroll") for (int _i = 0; _i < 2; ++_i) glds16_s((gbase), (voff)[_i], ldsb + (unsigned)((bufoff) + _i * 8192)); } while (0)
; #define PG8_LDA(dst, b, h) do { _Pragma("unroll") for (int m = 0; m < 4; ++m) _Pragma("unroll") for (int k = 0; k < 2; ++k) dst[m][k] = *(const LAS h16x8*)(lds + PG8_SA(b, h) + aoff + m * 2048 + k * 1024); } while (0)
; #define PG8_LDB(dst, b, h) do { _Pragma("unroll") for (int n = 0; n < 2; ++n) _Pragma("unroll") for (int k = 0; k < 2; ++k) dst[n][k] = *(const LAS h16x8*)(lds + PG8_SB(b, h) + boff + n * 2048 + k * 1024); } while (0)
; #define PG8_WAIT_V(n) asm volatile("s_waitcnt vmcnt(" #n ")" ::: "memory")
; #define PG8_WAIT_L(n) asm volatile("s_waitcnt lgkmcnt(" #n ")" ::: "memory")
; template <class Prob, class Epi, bool I8 = false, bool ALIGN_EPI = true, bool SP2 = true>
; __device__ __forceinline__ void gemm_phase(LAS unsigned char* lds, int wave, const Prob& P, const Epi& E) {
;     ...
;         for (int t = 0; t < nt; t += 2) {
;             const bool last = (t == nt - 2);
;             const char* a1 = cA + (size_t)(t + 1) * kstep;
;             const char* a2 = last ? nA : cA + (size_t)(t + 2) * kstep; const char* b2 = last ? nB : cB + (size_t)(t + 2) * kstep;
;             const char* a3 = a2 + kstep; const char* b3 = b2 + kstep;
;             if constexpr (SP2) {
;             PG8_LDB(B0, 0, 0); PG8_LDB(B1, 0, 1); PG8_SCHED; PG8_LDA(At, 0, 0); PG8_STAGE(PG8_SA(1, 1), a1 + hstepA, voffA);
;             PG8_WAIT_V(8); PG8_WAIT_L(0); PG8_BAR; PG8_MMA(0, 0, At, B0); PG8_MMA(0, 1, At, B1); PG8_BAR; PG8_SCHED;
;             PG8_LDA(At, 0, 1); PG8_STAGE(PG8_SB(0, 0), b2, voffB); PG8_STAGE(PG8_SB(0, 1), b2 + hstepB, voffB); PG8_STAGE(PG8_SA(0, 0), a2, voffA);
;             PG8_WAIT_V(8); PG8_WAIT_L(0); PG8_BAR; PG8_MMA(1, 0, At, B0); PG8_MMA(1, 1, At, B1); PG8_BAR; PG8_SCHED;
;             PG8_LDB(B0, 1, 0); PG8_LDB(B1, 1, 1); PG8_SCHED; PG8_LDA(At, 1, 0); PG8_STAGE(PG8_SA(0, 1), a2 + hstepA, voffA);
;             PG8_WAIT_V(8); PG8_WAIT_L(0); PG8_BAR; PG8_MMA(0, 0, At, B0); PG8_MMA(0, 1, At, B1); PG8_BAR; PG8_SCHED;
;             PG8_LDA(At, 1, 1); PG8_STAGE(PG8_SB(1, 0), b3, voffB); PG8_STAGE(PG8_SB(1, 1), b3 + hstepB, voffB); PG8_STAGE(PG8_SA(1, 0), a3, voffA);
;             PG8_WAIT_V(8); PG8_WAIT_L(0); PG8_BAR; PG8_MMA(1, 0, At, B0); PG8_MMA(1, 1, At, B1); PG8_BAR; PG8_SCHED;
	ds_read_b128 v[168:171], v147 offset:49152
	ds_read_b128 v[172:175], v147 offset:50176
	ds_read_b128 v[176:179], v147 offset:51200
	ds_read_b128 v[180:183], v147 offset:52224
	ds_read_b128 v[184:187], v147 offset:53248
	ds_read_b128 v[188:191], v147 offset:54272
	ds_read_b128 v[192:195], v147 offset:55296
	ds_read_b128 v[196:199], v147 offset:56320
	s_add_u32 s4, s46, 0x80
	s_addc_u32 s5, s47, 0
	s_mov_b32 s6, m0
	s_mov_b32 m0, s69
	s_nop 0
	global_load_lds_dwordx4 v143, s[4:5]
	s_mov_b32 m0, s6
	s_nop 0
	s_mov_b32 s6, m0
	s_mov_b32 m0, s72
	s_nop 0
	global_load_lds_dwordx4 v145, s[4:5]
	s_mov_b32 m0, s6
	s_add_u32 s4, s46, 0x80080
	s_addc_u32 s5, s47, 0
	s_mov_b32 s6, m0
	s_mov_b32 m0, s75
	s_nop 0
	global_load_lds_dwordx4 v143, s[4:5]
	s_mov_b32 m0, s6
	s_nop 0
	s_mov_b32 s6, m0
	s_mov_b32 m0, s76
	s_nop 0
	global_load_lds_dwordx4 v145, s[4:5]
	s_mov_b32 m0, s6
	s_mov_b32 s4, m0
	s_mov_b32 m0, s73
	s_nop 0
	global_load_lds_dwordx4 v142, s[44:45]
	s_mov_b32 m0, s4
	s_nop 0
	s_mov_b32 s4, m0
	s_mov_b32 m0, s74
	s_nop 0
	global_load_lds_dwordx4 v144, s[44:45]
	s_mov_b32 m0, s4
	s_waitcnt vmcnt(8)
	s_waitcnt lgkmcnt(0)
	s_barrier
	s_setprio 1
	s_waitcnt lgkmcnt(7)
	v_mfma_f32_16x16x32_f16 v[92:95], v[128:131], v[168:171], v[92:95]
	v_mfma_f32_16x16x32_f16 v[88:91], v[136:139], v[168:171], v[88:91]
	s_waitcnt lgkmcnt(5)
	v_mfma_f32_16x16x32_f16 v[84:87], v[128:131], v[176:179], v[84:87]
	v_mfma_f32_16x16x32_f16 v[80:83], v[136:139], v[176:179], v[80:83]
	s_waitcnt lgkmcnt(3)
	v_mfma_f32_16x16x32_f16 v[76:79], v[128:131], v[184:187], v[76:79]
	v_mfma_f32_16x16x32_f16 v[72:75], v[136:139], v[184:187], v[72:75]
	s_waitcnt lgkmcnt(1)
	v_mfma_f32_16x16x32_f16 v[68:71], v[128:131], v[192:195], v[68:71]
	v_mfma_f32_16x16x32_f16 v[60:63], v[136:139], v[192:195], v[60:63]
	v_mfma_f32_16x16x32_f16 v[92:95], v[132:135], v[172:175], v[92:95]
	v_mfma_f32_16x16x32_f16 v[88:91], v[148:151], v[172:175], v[88:91]
	v_mfma_f32_16x16x32_f16 v[84:87], v[132:135], v[180:183], v[84:87]
	v_mfma_f32_16x16x32_f16 v[80:83], v[148:151], v[180:183], v[80:83]
	v_mfma_f32_16x16x32_f16 v[76:79], v[132:135], v[188:191], v[76:79]
	v_mfma_f32_16x16x32_f16 v[72:75], v[148:151], v[188:191], v[72:75]
	s_waitcnt lgkmcnt(0)
	v_mfma_f32_16x16x32_f16 v[68:71], v[132:135], v[196:199], v[68:71]
	v_mfma_f32_16x16x32_f16 v[60:63], v[148:151], v[196:199], v[60:63]
	s_setprio 0
	s_setprio 1
	v_mfma_f32_16x16x32_f16 v[28:31], v[152:155], v[168:171], v[28:31]
	v_mfma_f32_16x16x32_f16 v[24:27], v[160:163], v[168:171], v[24:27]
	v_mfma_f32_16x16x32_f16 v[20:23], v[152:155], v[176:179], v[20:23]
	v_mfma_f32_16x16x32_f16 v[16:19], v[160:163], v[176:179], v[16:19]
	v_mfma_f32_16x16x32_f16 v[12:15], v[152:155], v[184:187], v[12:15]
	v_mfma_f32_16x16x32_f16 v[8:11], v[160:163], v[184:187], v[8:11]
	v_mfma_f32_16x16x32_f16 v[4:7], v[152:155], v[192:195], v[4:7]
	v_mfma_f32_16x16x32_f16 v[0:3], v[160:163], v[192:195], v[0:3]
	v_mfma_f32_16x16x32_f16 v[28:31], v[156:159], v[172:175], v[28:31]
	v_mfma_f32_16x16x32_f16 v[24:27], v[164:167], v[172:175], v[24:27]
	v_mfma_f32_16x16x32_f16 v[20:23], v[156:159], v[180:183], v[20:23]
	v_mfma_f32_16x16x32_f16 v[16:19], v[164:167], v[180:183], v[16:19]
	v_mfma_f32_16x16x32_f16 v[12:15], v[156:159], v[188:191], v[12:15]
	v_mfma_f32_16x16x32_f16 v[8:11], v[164:167], v[188:191], v[8:11]
	v_mfma_f32_16x16x32_f16 v[4:7], v[156:159], v[196:199], v[4:7]
	v_mfma_f32_16x16x32_f16 v[0:3], v[164:167], v[196:199], v[0:3]
	s_setprio 0
	s_barrier
	s_add_i32 s1, s1, 2
	s_add_u32 s85, s85, 0x100
	s_addc_u32 s86, s86, 0
	s_add_u32 s87, s87, 0x100
	s_addc_u32 s0, s0, 0
	s_add_u32 s40, s40, 0x100
	s_addc_u32 s41, s41, 0
	s_cmp_gt_u32 s1, 29

; #define PG8_STAGE(bufoff, gbase, voff) do { _Pragma("unroll") for (int _i = 0; _i < 2; ++_i) glds16_s((gbase), (voff)[_i], ldsb + (unsigned)((bufoff) + _i * 8192)); } while (0)
; #define PG8_LDA(dst, b, h) do { _Pragma("unroll") for (int m = 0; m < 4; ++m) _Pragma("unroll") for (int k = 0; k < 2; ++k) dst[m][k] = *(const LAS h16x8*)(lds + PG8_SA(b, h) + aoff + m * 2048 + k * 1024); } while (0)
; #define PG8_LDB(dst, b, h) do { _Pragma("unroll") for (int n = 0; n < 2; ++n) _Pragma("unroll") for (int k = 0; k < 2; ++k) dst[n][k] = *(const LAS h16x8*)(lds + PG8_SB(b, h) + boff + n * 2048 + k * 1024); } while (0)
; #define PG8_WAIT_V(n) asm volatile("s_waitcnt vmcnt(" #n ")" ::: "memory")
; #define PG8_WAIT_L(n) asm volatile("s_waitcnt lgkmcnt(" #n ")" ::: "memory")
; #define PG8_BAR __builtin_amdgcn_s_barrier()
; #define PG8_SCHED __builtin_amdgcn_sched_barrier(0)
; template <class Prob, class Epi, bool I8 = false, bool ALIGN_EPI = true, bool SP2 = true>
; __device__ __forceinline__ void gemm_phase(LAS unsigned char* lds, int wave, const Prob& P, const Epi& E) {
;     ...
;     for (;;) {
;         const bool has_next = P.next(ui + 1, nxt);
;         const char* nA = has_next ? P.a_tile(nxt) : cA; const char* nB = has_next ? P.b_tile(nxt) : cB;
;         for (int t = 0; t < nt; t += 2) {
;             const bool last = (t == nt - 2);
;             const char* a1 = cA + (size_t)(t + 1) * kstep;
;             const char* a2 = last ? nA : cA + (size_t)(t + 2) * kstep; const char* b2 = last ? nB : cB + (size_t)(t + 2) * kstep;
;             const char* a3 = a2 + kstep; const char* b3 = b2 + kstep;
;             if constexpr (SP2) {
;             PG8_LDB(B0, 0, 0); PG8_LDB(B1, 0, 1); PG8_SCHED; PG8_LDA(At, 0, 0); PG8_STAGE(PG8_SA(1, 1), a1 + hstepA, voffA);
;             PG8_WAIT_V(8); PG8_WAIT_L(0); PG8_BAR; PG8_MMA(0, 0, At, B0); PG8_MMA(0, 1, At, B1); PG8_BAR; PG8_SCHED;
;             PG8_LDA(At, 0, 1); PG8_STAGE(PG8_SB(0, 0), b2, voffB); PG8_STAGE(PG8_SB(0, 1), b2 + hstepB, voffB); PG8_STAGE(PG8_SA(0, 0), a2, voffA);
;     ...
; #pragma unroll
;         for (int a = 0; a < 2; ++a)
; #pragma unroll
;             for (int b = 0; b < 2; ++b)
; #pragma unroll
;                 for (int m = 0; m < 4; ++m)
; #pragma unroll
;                     for (int n = 0; n < 2; ++n) acc[a][b][m][n] = (f32x4){0.f, 0.f, 0.f, 0.f};
.LBB0_535:
	s_ashr_i32 s51, s50, 31
	s_lshl_b64 s[0:1], s[50:51], 20
	s_add_u32 s14, s54, s0
	s_addc_u32 s15, s55, s1
	s_and_b64 s[0:1], s[36:37], exec
	s_cselect_b32 s51, s15, s41
	s_cselect_b32 s57, s14, s40
	s_ashr_i32 s49, s48, 31
	s_lshl_b64 s[0:1], s[48:49], 20
	s_add_u32 s60, s19, s0
	s_addc_u32 s61, s62, s1
	s_and_b64 s[0:1], s[36:37], exec
	s_cselect_b32 s49, s61, s39
	s_cselect_b32 s72, s60, s38
	s_add_u32 s73, s40, 0x100
	s_addc_u32 s74, s41, 0
	s_add_u32 s75, s38, 0x100
	s_addc_u32 s0, s39, 0
	s_add_u32 s38, s40, 0x80080
	s_addc_u32 s39, s41, 0
	s_mov_b32 s1, -2
.Lpeel_536:
	v_add_u32_e32 v146, 0x10000, v136
	v_add_u32_e32 v162, 0x14000, v136
	ds_read_b128 v[128:131], v146
	ds_read_b128 v[138:141], v146 offset:1024
	ds_read_b128 v[142:145], v146 offset:2048
	ds_read_b128 v[146:149], v146 offset:3072
	ds_read_b128 v[150:153], v162
	ds_read_b128 v[154:157], v162 offset:1024
	ds_read_b128 v[158:161], v162 offset:2048
	ds_read_b128 v[162:165], v162 offset:3072
	s_cmp_eq_u32 s1, 28
	s_cselect_b32 s44, s57, s73
	s_cselect_b32 s45, s51, s74
	s_cselect_b32 s42, s72, s75
	s_cselect_b32 s43, s49, s0
	s_add_u32 s40, s44, 0x80
	s_addc_u32 s41, s45, 0
	ds_read_b128 v[166:169], v137
	ds_read_b128 v[170:173], v137 offset:1024
	ds_read_b128 v[174:177], v137 offset:2048
	ds_read_b128 v[178:181], v137 offset:3072
	ds_read_b128 v[182:185], v137 offset:4096
	ds_read_b128 v[186:189], v137 offset:5120
	ds_read_b128 v[190:193], v137 offset:6144
	ds_read_b128 v[194:197], v137 offset:7168
	s_mov_b32 s4, m0
	s_mov_b32 m0, s91
	s_nop 0
	global_load_lds_dwordx4 v132, s[38:39]
	s_mov_b32 m0, s4
	s_nop 0
	s_mov_b32 s4, m0
	s_mov_b32 m0, s94
	s_nop 0
	global_load_lds_dwordx4 v134, s[38:39]
	s_mov_b32 m0, s4
	s_waitcnt vmcnt(8)
	s_waitcnt lgkmcnt(0)
	s_barrier
	s_setprio 1
	s_waitcnt lgkmcnt(7)
	v_mfma_f32_16x16x32_f16 v[124:127], v[128:131], v[166:169], 0
	v_mfma_f32_16x16x32_f16 v[120:123], v[142:145], v[166:169], 0
	s_waitcnt lgkmcnt(5)
	v_mfma_f32_16x16x32_f16 v[108:111], v[128:131], v[174:177], 0
	v_mfma_f32_16x16x32_f16 v[104:107], v[142:145], v[174:177], 0
	s_waitcnt lgkmcnt(3)
	v_mfma_f32_16x16x32_f16 v[92:95], v[128:131], v[182:185], 0
	v_mfma_f32_16x16x32_f16 v[88:91], v[142:145], v[182:185], 0
	s_waitcnt lgkmcnt(1)
	v_mfma_f32_16x16x32_f16 v[76:79], v[128:131], v[190:193], 0
	v_mfma_f32_16x16x32_f16 v[72:75], v[142:145], v[190:193], 0
	v_mfma_f32_16x16x32_f16 v[124:127], v[138:141], v[170:173], v[124:127]
	v_mfma_f32_16x16x32_f16 v[120:123], v[146:149], v[170:173], v[120:123]
	v_mfma_f32_16x16x32_f16 v[108:111], v[138:141], v[178:181], v[108:111]
	v_mfma_f32_16x16x32_f16 v[104:107], v[146:149], v[178:181], v[104:107]
	v_mfma_f32_16x16x32_f16 v[92:95], v[138:141], v[186:189], v[92:95]
	v_mfma_f32_16x16x32_f16 v[88:91], v[146:149], v[186:189], v[88:91]
	s_waitcnt lgkmcnt(0)
	v_mfma_f32_16x16x32_f16 v[76:79], v[138:141], v[194:197], v[76:79]
	v_mfma_f32_16x16x32_f16 v[72:75], v[146:149], v[194:197], v[72:75]
	s_setprio 0
	s_setprio 1
	v_mfma_f32_16x16x32_f16 v[116:119], v[150:153], v[166:169], 0
	v_mfma_f32_16x16x32_f16 v[112:115], v[158:161], v[166:169], 0
	v_mfma_f32_16x16x32_f16 v[100:103], v[150:153], v[174:177], 0
	v_mfma_f32_16x16x32_f16 v[96:99], v[158:161], v[174:177], 0
	v_mfma_f32_16x16x32_f16 v[84:87], v[150:153], v[182:185], 0
	v_mfma_f32_16x16x32_f16 v[80:83], v[158:161], v[182:185], 0
	v_mfma_f32_16x16x32_f16 v[68:71], v[150:153], v[190:193], 0
	v_mfma_f32_16x16x32_f16 v[64:67], v[158:161], v[190:193], 0
	v_mfma_f32_16x16x32_f16 v[116:119], v[154:157], v[170:173], v[116:119]
	v_mfma_f32_16x16x32_f16 v[112:115], v[162:165], v[170:173], v[112:115]
	v_mfma_f32_16x16x32_f16 v[100:103], v[154:157], v[178:181], v[100:103]
	v_mfma_f32_16x16x32_f16 v[96:99], v[162:165], v[178:181], v[96:99]
	v_mfma_f32_16x16x32_f16 v[84:87], v[154:157], v[186:189], v[84:87]
	v_mfma_f32_16x16x32_f16 v[80:83], v[162:165], v[186:189], v[80:83]
	v_mfma_f32_16x16x32_f16 v[68:71], v[154:157], v[194:197], v[68:71]
	v_mfma_f32_16x16x32_f16 v[64:67], v[162:165], v[194:197], v[64:67]
	s_setprio 0
	s_barrier
	ds_read_b128 v[166:169], v137 offset:16384
	ds_read_b128 v[170:173], v137 offset:17408
	ds_read_b128 v[174:177], v137 offset:18432
	ds_read_b128 v[178:181], v137 offset:19456
	ds_read_b128 v[182:185], v137 offset:20480
	ds_read_b128 v[186:189], v137 offset:21504
	ds_read_b128 v[190:193], v137 offset:22528
	ds_read_b128 v[194:197], v137 offset:23552
	s_mov_b32 s4, m0
	s_mov_b32 m0, s64
	s_nop 0
	global_load_lds_dwordx4 v133, s[42:43]
	s_mov_b32 m0, s4
	s_nop 0
	s_mov_b32 s4, m0
	s_mov_b32 m0, s68
	s_nop 0
	global_load_lds_dwordx4 v135, s[42:43]
	s_mov_b32 m0, s4
	s_add_u32 s4, s42, 0x80000
	s_addc_u32 s5, s43, 0
	s_mov_b32 s6, m0
	s_mov_b32 m0, s69
	s_nop 0
	global_load_lds_dwordx4 v133, s[4:5]
	s_mov_b32 m0, s6
	s_nop 0
	s_mov_b32 s6, m0
	s_mov_b32 m0, s79
	s_nop 0
	global_load_lds_dwordx4 v135, s[4:5]
	s_mov_b32 m0, s6
	s_mov_b32 s4, m0
	s_mov_b32 m0, s63
	s_nop 0
	global_load_lds_dwordx4 v132, s[44:45]
	s_mov_b32 m0, s4
	s_nop 0
	s_mov_b32 s4, m0
	s_mov_b32 m0, s80
	s_nop 0
	global_load_lds_dwordx4 v134, s[44:45]
	s_mov_b32 m0, s4
	s_waitcnt vmcnt(8)
	s_waitcnt lgkmcnt(0)
	s_barrier
; #define PG8_STAGE(bufoff, gbase, voff) do { _Pragma("unroll") for (int _i = 0; _i < 2; ++_i) glds16_s((gbase), (voff)[_i], ldsb + (unsigned)((bufoff) + _i * 8192)); } while (0)
; #define PG8_LDA(dst, b, h) do { _Pragma("unroll") for (int m = 0; m < 4; ++m) _Pragma("unroll") for (int k = 0; k < 2; ++k) dst[m][k] = *(const LAS h16x8*)(lds + PG8_SA(b, h) + aoff + m * 2048 + k * 1024); } while (0)
; #define PG8_LDB(dst, b, h) do { _Pragma("unroll") for (int n = 0; n < 2; ++n) _Pragma("unroll") for (int k = 0; k < 2; ++k) dst[n][k] = *(const LAS h16x8*)(lds + PG8_SB(b, h) + boff + n * 2048 + k * 1024); } while (0)
; #define PG8_MMA(ai, bj, At, Bt) do { __builtin_amdgcn_s_setprio(1); _Pragma("unroll") for (int m = 0; m < 4; ++m) _Pragma("unroll") for (int n = 0; n < 2; ++n) _Pragma("unroll") for (int k = 0; k < 2; ++k) \
;         acc[ai][bj][m][n] = mma_step<I8>(Bt[n][k], At[m][k], acc[ai][bj][m][n]); __builtin_amdgcn_s_setprio(0); } while (0)
; #define PG8_WAIT_V(n) asm volatile("s_waitcnt vmcnt(" #n ")" ::: "memory")
; #define PG8_WAIT_L(n) asm volatile("s_waitcnt lgkmcnt(" #n ")" ::: "memory")
; #define PG8_BAR __builtin_amdgcn_s_barrier()
; #define PG8_SCHED __builtin_amdgcn_sched_barrier(0)
; template <class Prob, class Epi, bool I8 = false, bool ALIGN_EPI = true, bool SP2 = true>
; __device__ __forceinline__ void gemm_phase(LAS unsigned char* lds, int wave, const Prob& P, const Epi& E) {
;     ...
;             PG8_WAIT_V(8); PG8_WAIT_L(0); PG8_BAR; PG8_MMA(1, 0, At, B0); PG8_MMA(1, 1, At, B1); PG8_BAR; PG8_SCHED;
;             PG8_LDB(B0, 1, 0); PG8_LDB(B1, 1, 1); PG8_SCHED; PG8_LDA(At, 1, 0); PG8_STAGE(PG8_SA(0, 1), a2 + hstepA, voffA);
;             PG8_WAIT_V(8); PG8_WAIT_L(0); PG8_BAR; PG8_MMA(0, 0, At, B0); PG8_MMA(0, 1, At, B1); PG8_BAR; PG8_SCHED;
	s_setprio 1
	s_waitcnt lgkmcnt(7)
	v_mfma_f32_16x16x32_f16 v[60:63], v[128:131], v[166:169], 0
	v_mfma_f32_16x16x32_f16 v[56:59], v[142:145], v[166:169], 0
	s_waitcnt lgkmcnt(5)
	v_mfma_f32_16x16x32_f16 v[44:47], v[128:131], v[174:177], 0
	v_mfma_f32_16x16x32_f16 v[40:43], v[142:145], v[174:177], 0
	s_waitcnt lgkmcnt(3)
	v_mfma_f32_16x16x32_f16 v[28:31], v[128:131], v[182:185], 0
	v_mfma_f32_16x16x32_f16 v[24:27], v[142:145], v[182:185], 0
	s_waitcnt lgkmcnt(1)
	v_mfma_f32_16x16x32_f16 v[12:15], v[128:131], v[190:193], 0
	v_mfma_f32_16x16x32_f16 v[8:11], v[142:145], v[190:193], 0
	v_mfma_f32_16x16x32_f16 v[60:63], v[138:141], v[170:173], v[60:63]
	v_mfma_f32_16x16x32_f16 v[56:59], v[146:149], v[170:173], v[56:59]
	v_mfma_f32_16x16x32_f16 v[44:47], v[138:141], v[178:181], v[44:47]
	v_mfma_f32_16x16x32_f16 v[40:43], v[146:149], v[178:181], v[40:43]
	v_mfma_f32_16x16x32_f16 v[28:31], v[138:141], v[186:189], v[28:31]
	v_mfma_f32_16x16x32_f16 v[24:27], v[146:149], v[186:189], v[24:27]
	s_waitcnt lgkmcnt(0)
	v_mfma_f32_16x16x32_f16 v[12:15], v[138:141], v[194:197], v[12:15]
	v_mfma_f32_16x16x32_f16 v[8:11], v[146:149], v[194:197], v[8:11]
	s_setprio 0
	s_setprio 1
	v_mfma_f32_16x16x32_f16 v[52:55], v[150:153], v[166:169], 0
	v_mfma_f32_16x16x32_f16 v[48:51], v[158:161], v[166:169], 0
	v_mfma_f32_16x16x32_f16 v[36:39], v[150:153], v[174:177], 0
	v_mfma_f32_16x16x32_f16 v[32:35], v[158:161], v[174:177], 0
	v_mfma_f32_16x16x32_f16 v[20:23], v[150:153], v[182:185], 0
	v_mfma_f32_16x16x32_f16 v[16:19], v[158:161], v[182:185], 0
	v_mfma_f32_16x16x32_f16 v[4:7], v[150:153], v[190:193], 0
	v_mfma_f32_16x16x32_f16 v[0:3], v[158:161], v[190:193], 0
	v_mfma_f32_16x16x32_f16 v[52:55], v[154:157], v[170:173], v[52:55]
	v_mfma_f32_16x16x32_f16 v[48:51], v[162:165], v[170:173], v[48:51]
	v_mfma_f32_16x16x32_f16 v[36:39], v[154:157], v[178:181], v[36:39]
	v_mfma_f32_16x16x32_f16 v[32:35], v[162:165], v[178:181], v[32:35]
	v_mfma_f32_16x16x32_f16 v[20:23], v[154:157], v[186:189], v[20:23]
	v_mfma_f32_16x16x32_f16 v[16:19], v[162:165], v[186:189], v[16:19]
	v_mfma_f32_16x16x32_f16 v[4:7], v[154:157], v[194:197], v[4:7]
	v_mfma_f32_16x16x32_f16 v[0:3], v[162:165], v[194:197], v[0:3]
	s_setprio 0
	s_barrier
	v_add_u32_e32 v146, 0x18000, v136
	v_add_u32_e32 v162, 0x1c000, v136
	ds_read_b128 v[128:131], v146
	ds_read_b128 v[138:141], v146 offset:1024
	ds_read_b128 v[142:145], v146 offset:2048
	ds_read_b128 v[146:149], v146 offset:3072
	ds_read_b128 v[150:153], v162
	ds_read_b128 v[154:157], v162 offset:1024
	ds_read_b128 v[158:161], v162 offset:2048
	ds_read_b128 v[162:165], v162 offset:3072
	ds_read_b128 v[166:169], v137 offset:32768
	ds_read_b128 v[170:173], v137 offset:33792
	ds_read_b128 v[174:177], v137 offset:34816
	ds_read_b128 v[178:181], v137 offset:35840
	ds_read_b128 v[182:185], v137 offset:36864
	ds_read_b128 v[186:189], v137 offset:37888
	ds_read_b128 v[190:193], v137 offset:38912
	ds_read_b128 v[194:197], v137 offset:39936
	s_add_u32 s4, s44, 0x80000
	s_addc_u32 s5, s45, 0
	s_mov_b32 s6, m0
	s_mov_b32 m0, s81
	s_nop 0
	global_load_lds_dwordx4 v132, s[4:5]
	s_mov_b32 m0, s6
	s_nop 0
	s_mov_b32 s6, m0
	s_mov_b32 m0, s82
	s_nop 0
	global_load_lds_dwordx4 v134, s[4:5]
	s_mov_b32 m0, s6
	s_waitcnt vmcnt(8)
	s_waitcnt lgkmcnt(0)
	s_barrier
	s_setprio 1
	s_waitcnt lgkmcnt(7)
	v_mfma_f32_16x16x32_f16 v[124:127], v[128:131], v[166:169], v[124:127]
	v_mfma_f32_16x16x32_f16 v[120:123], v[142:145], v[166:169], v[120:123]
	s_waitcnt lgkmcnt(5)
	v_mfma_f32_16x16x32_f16 v[108:111], v[128:131], v[174:177], v[108:111]
	v_mfma_f32_16x16x32_f16 v[104:107], v[142:145], v[174:177], v[104:107]
	s_waitcnt lgkmcnt(3)
	v_mfma_f32_16x16x32_f16 v[92:95], v[128:131], v[182:185], v[92:95]
	v_mfma_f32_16x16x32_f16 v[88:91], v[142:145], v[182:185], v[88:91]
	s_waitcnt lgkmcnt(1)
	v_mfma_f32_16x16x32_f16 v[76:79], v[128:131], v[190:193], v[76:79]
	v_mfma_f32_16x16x32_f16 v[72:75], v[142:145], v[190:193], v[72:75]
	v_mfma_f32_16x16x32_f16 v[124:127], v[138:141], v[170:173], v[124:127]
	v_mfma_f32_16x16x32_f16 v[120:123], v[146:149], v[170:173], v[120:123]
	v_mfma_f32_16x16x32_f16 v[108:111], v[138:141], v[178:181], v[108:111]
	v_mfma_f32_16x16x32_f16 v[104:107], v[146:149], v[178:181], v[104:107]
	v_mfma_f32_16x16x32_f16 v[92:95], v[138:141], v[186:189], v[92:95]
	v_mfma_f32_16x16x32_f16 v[88:91], v[146:149], v[186:189], v[88:91]
	s_waitcnt lgkmcnt(0)
	v_mfma_f32_16x16x32_f16 v[76:79], v[138:141], v[194:197], v[76:79]
	v_mfma_f32_16x16x32_f16 v[72:75], v[146:149], v[194:197], v[72:75]
	s_setprio 0
	s_setprio 1
	v_mfma_f32_16x16x32_f16 v[116:119], v[150:153], v[166:169], v[116:119]
	v_mfma_f32_16x16x32_f16 v[112:115], v[158:161], v[166:169], v[112:115]
	v_mfma_f32_16x16x32_f16 v[100:103], v[150:153], v[174:177], v[100:103]
	v_mfma_f32_16x16x32_f16 v[96:99], v[158:161], v[174:177], v[96:99]
	v_mfma_f32_16x16x32_f16 v[84:87], v[150:153], v[182:185], v[84:87]
	v_mfma_f32_16x16x32_f16 v[80:83], v[158:161], v[182:185], v[80:83]
	v_mfma_f32_16x16x32_f16 v[68:71], v[150:153], v[190:193], v[68:71]
	v_mfma_f32_16x16x32_f16 v[64:67], v[158:161], v[190:193], v[64:67]
	v_mfma_f32_16x16x32_f16 v[116:119], v[154:157], v[170:173], v[116:119]
	v_mfma_f32_16x16x32_f16 v[112:115], v[162:165], v[170:173], v[112:115]
	v_mfma_f32_16x16x32_f16 v[100:103], v[154:157], v[178:181], v[100:103]
	v_mfma_f32_16x16x32_f16 v[96:99], v[162:165], v[178:181], v[96:99]
	v_mfma_f32_16x16x32_f16 v[84:87], v[154:157], v[186:189], v[84:87]
	v_mfma_f32_16x16x32_f16 v[80:83], v[162:165], v[186:189], v[80:83]
	v_mfma_f32_16x16x32_f16 v[68:71], v[154:157], v[194:197], v[68:71]
	v_mfma_f32_16x16x32_f16 v[64:67], v[162:165], v[194:197], v[64:67]
	s_setprio 0
	s_barrier
; #define PG8_STAGE(bufoff, gbase, voff) do { _Pragma("unroll") for (int _i = 0; _i < 2; ++_i) glds16_s((gbase), (voff)[_i], ldsb + (unsigned)((bufoff) + _i * 8192)); } while (0)
; #define PG8_LDA(dst, b, h) do { _Pragma("unroll") for (int m = 0; m < 4; ++m) _Pragma("unroll") for (int k = 0; k < 2; ++k) dst[m][k] = *(const LAS h16x8*)(lds + PG8_SA(b, h) + aoff + m * 2048 + k * 1024); } while (0)
; #define PG8_MMA(ai, bj, At, Bt) do { __builtin_amdgcn_s_setprio(1); _Pragma("unroll") for (int m = 0; m < 4; ++m) _Pragma("unroll") for (int n = 0; n < 2; ++n) _Pragma("unroll") for (int k = 0; k < 2; ++k) \
;         acc[ai][bj][m][n] = mma_step<I8>(Bt[n][k], At[m][k], acc[ai][bj][m][n]); __builtin_amdgcn_s_setprio(0); } while (0)
; #define PG8_WAIT_V(n) asm volatile("s_waitcnt vmcnt(" #n ")" ::: "memory")
; #define PG8_WAIT_L(n) asm volatile("s_waitcnt lgkmcnt(" #n ")" ::: "memory")
; #define PG8_BAR __builtin_amdgcn_s_barrier()
; #define PG8_SCHED __builtin_amdgcn_sched_barrier(0)
; template <class Prob, class Epi, bool I8 = false, bool ALIGN_EPI = true, bool SP2 = true>
; __device__ __forceinline__ void gemm_phase(LAS unsigned char* lds, int wave, const Prob& P, const Epi& E) {
;     ...
;         for (int t = 0; t < nt; t += 2) {
;             const bool last = (t == nt - 2);
;             const char* a1 = cA + (size_t)(t + 1) * kstep;
;             const char* a2 = last ? nA : cA + (size_t)(t + 2) * kstep; const char* b2 = last ? nB : cB + (size_t)(t + 2) * kstep;
;             const char* a3 = a2 + kstep; const char* b3 = b2 + kstep;
;     ...
;             PG8_LDA(At, 1, 1); PG8_STAGE(PG8_SB(1, 0), b3, voffB); PG8_STAGE(PG8_SB(1, 1), b3 + hstepB, voffB); PG8_STAGE(PG8_SA(1, 0), a3, voffA);
;             PG8_WAIT_V(8); PG8_WAIT_L(0); PG8_BAR; PG8_MMA(1, 0, At, B0); PG8_MMA(1, 1, At, B1); PG8_BAR; PG8_SCHED;
	ds_read_b128 v[166:169], v137 offset:49152
	ds_read_b128 v[170:173], v137 offset:50176
	ds_read_b128 v[174:177], v137 offset:51200
	ds_read_b128 v[178:181], v137 offset:52224
	ds_read_b128 v[182:185], v137 offset:53248
	ds_read_b128 v[186:189], v137 offset:54272
	ds_read_b128 v[190:193], v137 offset:55296
	ds_read_b128 v[194:197], v137 offset:56320
	s_add_u32 s4, s42, 0x80
	s_addc_u32 s5, s43, 0
	s_mov_b32 s6, m0
	s_mov_b32 m0, s85
	s_nop 0
	global_load_lds_dwordx4 v133, s[4:5]
	s_mov_b32 m0, s6
	s_nop 0
	s_mov_b32 s6, m0
	s_mov_b32 m0, s86
	s_nop 0
	global_load_lds_dwordx4 v135, s[4:5]
	s_mov_b32 m0, s6
	s_add_u32 s4, s42, 0x80080
	s_addc_u32 s5, s43, 0
	s_mov_b32 s6, m0
	s_mov_b32 m0, s89
	s_nop 0
	global_load_lds_dwordx4 v133, s[4:5]
	s_mov_b32 m0, s6
	s_nop 0
	s_mov_b32 s6, m0
	s_mov_b32 m0, s90
	s_nop 0
	global_load_lds_dwordx4 v135, s[4:5]
	s_mov_b32 m0, s6
	s_mov_b32 s4, m0
	s_mov_b32 m0, s87
	s_nop 0
	global_load_lds_dwordx4 v132, s[40:41]
	s_mov_b32 m0, s4
	s_nop 0
	s_mov_b32 s4, m0
	s_mov_b32 m0, s88
	s_nop 0
	global_load_lds_dwordx4 v134, s[40:41]
	s_mov_b32 m0, s4
	s_waitcnt vmcnt(8)
	s_waitcnt lgkmcnt(0)
	s_barrier
	s_setprio 1
	s_waitcnt lgkmcnt(7)
	v_mfma_f32_16x16x32_f16 v[60:63], v[128:131], v[166:169], v[60:63]
	v_mfma_f32_16x16x32_f16 v[56:59], v[142:145], v[166:169], v[56:59]
	s_waitcnt lgkmcnt(5)
	v_mfma_f32_16x16x32_f16 v[44:47], v[128:131], v[174:177], v[44:47]
	v_mfma_f32_16x16x32_f16 v[40:43], v[142:145], v[174:177], v[40:43]
	s_waitcnt lgkmcnt(3)
	v_mfma_f32_16x16x32_f16 v[28:31], v[128:131], v[182:185], v[28:31]
	v_mfma_f32_16x16x32_f16 v[24:27], v[142:145], v[182:185], v[24:27]
	s_waitcnt lgkmcnt(1)
	v_mfma_f32_16x16x32_f16 v[12:15], v[128:131], v[190:193], v[12:15]
	v_mfma_f32_16x16x32_f16 v[8:11], v[142:145], v[190:193], v[8:11]
	v_mfma_f32_16x16x32_f16 v[60:63], v[138:141], v[170:173], v[60:63]
	v_mfma_f32_16x16x32_f16 v[56:59], v[146:149], v[170:173], v[56:59]
	v_mfma_f32_16x16x32_f16 v[44:47], v[138:141], v[178:181], v[44:47]
	v_mfma_f32_16x16x32_f16 v[40:43], v[146:149], v[178:181], v[40:43]
	v_mfma_f32_16x16x32_f16 v[28:31], v[138:141], v[186:189], v[28:31]
	v_mfma_f32_16x16x32_f16 v[24:27], v[146:149], v[186:189], v[24:27]
	s_waitcnt lgkmcnt(0)
	v_mfma_f32_16x16x32_f16 v[12:15], v[138:141], v[194:197], v[12:15]
	v_mfma_f32_16x16x32_f16 v[8:11], v[146:149], v[194:197], v[8:11]
	s_setprio 0
	s_setprio 1
	v_mfma_f32_16x16x32_f16 v[52:55], v[150:153], v[166:169], v[52:55]
	v_mfma_f32_16x16x32_f16 v[48:51], v[158:161], v[166:169], v[48:51]
	v_mfma_f32_16x16x32_f16 v[36:39], v[150:153], v[174:177], v[36:39]
	v_mfma_f32_16x16x32_f16 v[32:35], v[158:161], v[174:177], v[32:35]
	v_mfma_f32_16x16x32_f16 v[20:23], v[150:153], v[182:185], v[20:23]
	v_mfma_f32_16x16x32_f16 v[16:19], v[158:161], v[182:185], v[16:19]
	v_mfma_f32_16x16x32_f16 v[4:7], v[150:153], v[190:193], v[4:7]
	v_mfma_f32_16x16x32_f16 v[0:3], v[158:161], v[190:193], v[0:3]
	v_mfma_f32_16x16x32_f16 v[52:55], v[154:157], v[170:173], v[52:55]
	v_mfma_f32_16x16x32_f16 v[48:51], v[162:165], v[170:173], v[48:51]
	v_mfma_f32_16x16x32_f16 v[36:39], v[154:157], v[178:181], v[36:39]
	v_mfma_f32_16x16x32_f16 v[32:35], v[162:165], v[178:181], v[32:35]
	v_mfma_f32_16x16x32_f16 v[20:23], v[154:157], v[186:189], v[20:23]
	v_mfma_f32_16x16x32_f16 v[16:19], v[162:165], v[186:189], v[16:19]
	v_mfma_f32_16x16x32_f16 v[4:7], v[154:157], v[194:197], v[4:7]
	v_mfma_f32_16x16x32_f16 v[0:3], v[162:165], v[194:197], v[0:3]
	s_setprio 0
	s_barrier
	s_add_i32 s1, s1, 2
	s_add_u32 s73, s73, 0x100
	s_addc_u32 s74, s74, 0
	s_add_u32 s75, s75, 0x100
	s_addc_u32 s0, s0, 0
	s_add_u32 s38, s38, 0x100
	s_addc_u32 s39, s39, 0
	s_cmp_gt_u32 s1, 29

; #define PG8_STAGE(bufoff, gbase, voff) do { _Pragma("unroll") for (int _i = 0; _i < 2; ++_i) glds16_s((gbase), (voff)[_i], ldsb + (unsigned)((bufoff) + _i * 8192)); } while (0)
; #define PG8_LDA(dst, b, h) do { _Pragma("unroll") for (int m = 0; m < 4; ++m) _Pragma("unroll") for (int k = 0; k < 2; ++k) dst[m][k] = *(const LAS h16x8*)(lds + PG8_SA(b, h) + aoff + m * 2048 + k * 1024); } while (0)
; #define PG8_LDB(dst, b, h) do { _Pragma("unroll") for (int n = 0; n < 2; ++n) _Pragma("unroll") for (int k = 0; k < 2; ++k) dst[n][k] = *(const LAS h16x8*)(lds + PG8_SB(b, h) + boff + n * 2048 + k * 1024); } while (0)
; #define PG8_MMA(ai, bj, At, Bt) do { __builtin_amdgcn_s_setprio(1); _Pragma("unroll") for (int m = 0; m < 4; ++m) _Pragma("unroll") for (int n = 0; n < 2; ++n) _Pragma("unroll") for (int k = 0; k < 2; ++k) \
;         acc[ai][bj][m][n] = mma_step<I8>(Bt[n][k], At[m][k], acc[ai][bj][m][n]); __builtin_amdgcn_s_setprio(0); } while (0)
; #define PG8_WAIT_V(n) asm volatile("s_waitcnt vmcnt(" #n ")" ::: "memory")
; #define PG8_WAIT_L(n) asm volatile("s_waitcnt lgkmcnt(" #n ")" ::: "memory")
; template <class Prob, class Epi, bool I8 = false, bool ALIGN_EPI = true, bool SP2 = true>
; __device__ __forceinline__ void gemm_phase(LAS unsigned char* lds, int wave, const Prob& P, const Epi& E) {
;     ...
;     for (;;) {
;         const bool has_next = P.next(ui + 1, nxt);
;         const char* nA = has_next ? P.a_tile(nxt) : cA; const char* nB = has_next ? P.b_tile(nxt) : cB;
;         for (int t = 0; t < nt; t += 2) {
;             const bool last = (t == nt - 2);
;             const char* a1 = cA + (size_t)(t + 1) * kstep;
;             const char* a2 = last ? nA : cA + (size_t)(t + 2) * kstep; const char* b2 = last ? nB : cB + (size_t)(t + 2) * kstep;
;             const char* a3 = a2 + kstep; const char* b3 = b2 + kstep;
;             if constexpr (SP2) {
;             PG8_LDB(B0, 0, 0); PG8_LDB(B1, 0, 1); PG8_SCHED; PG8_LDA(At, 0, 0); PG8_STAGE(PG8_SA(1, 1), a1 + hstepA, voffA);
;             PG8_WAIT_V(8); PG8_WAIT_L(0); PG8_BAR; PG8_MMA(0, 0, At, B0); PG8_MMA(0, 1, At, B1); PG8_BAR; PG8_SCHED;
;             PG8_LDA(At, 0, 1); PG8_STAGE(PG8_SB(0, 0), b2, voffB); PG8_STAGE(PG8_SB(0, 1), b2 + hstepB, voffB); PG8_STAGE(PG8_SA(0, 0), a2, voffA);
;             PG8_WAIT_V(8); PG8_WAIT_L(0); PG8_BAR; PG8_MMA(1, 0, At, B0); PG8_MMA(1, 1, At, B1); PG8_BAR; PG8_SCHED;
.LBB0_615:
	s_ashr_i32 s43, s42, 31
	s_lshl_b64 s[0:1], s[42:43], 19
	s_add_u32 s48, s19, s0
	s_addc_u32 s49, s64, s1
	s_and_b64 s[0:1], s[36:37], exec
	s_cselect_b32 s39, s49, s57
	s_cselect_b32 s43, s48, s56
	s_ashr_i32 s41, s40, 31
	s_lshl_b64 s[0:1], s[40:41], 19
	s_add_u32 s50, s79, s0
	s_addc_u32 s51, s80, s1
	s_and_b64 s[0:1], s[36:37], exec
	s_cselect_b32 s41, s51, s45
	s_cselect_b32 s61, s50, s44
	s_add_u32 s73, s56, 0x100
	s_addc_u32 vcc_lo, s57, 0
	s_add_u32 vcc_hi, s44, 0x100
	s_addc_u32 s0, s45, 0
	s_add_u32 s44, s56, 0x40080
	s_addc_u32 s45, s57, 0
	s_mov_b32 s1, -2
.Lpeel_616:
	v_add_u32_e32 v140, 0x10000, v152
	v_add_u32_e32 v162, 0x14000, v152
	ds_read_b128 v[128:131], v140
	ds_read_b128 v[132:135], v140 offset:1024
	ds_read_b128 v[136:139], v140 offset:2048
	ds_read_b128 v[140:143], v140 offset:3072
	ds_read_b128 v[144:147], v162
	ds_read_b128 v[154:157], v162 offset:1024
	ds_read_b128 v[158:161], v162 offset:2048
	ds_read_b128 v[162:165], v162 offset:3072
	s_cmp_eq_u32 s1, 12
	s_cselect_b32 s62, s43, s73
	s_cselect_b32 s63, s39, vcc_lo
	s_cselect_b32 s68, s61, vcc_hi
	s_cselect_b32 s69, s41, s0
	s_add_u32 s56, s62, 0x80
	s_addc_u32 s57, s63, 0
	ds_read_b128 v[166:169], v153
	ds_read_b128 v[170:173], v153 offset:1024
	ds_read_b128 v[174:177], v153 offset:2048
	ds_read_b128 v[178:181], v153 offset:3072
	ds_read_b128 v[182:185], v153 offset:4096
	ds_read_b128 v[186:189], v153 offset:5120
	ds_read_b128 v[190:193], v153 offset:6144
	ds_read_b128 v[194:197], v153 offset:7168
	s_mov_b32 s4, m0
	s_mov_b32 m0, s96
	s_nop 0
	global_load_lds_dwordx4 v148, s[44:45]
	s_mov_b32 m0, s4
	s_nop 0
	s_mov_b32 s4, m0
	s_mov_b32 m0, s75
	s_nop 0
	global_load_lds_dwordx4 v150, s[44:45]
	s_mov_b32 m0, s4
	s_waitcnt vmcnt(8)
	s_waitcnt lgkmcnt(0)
	s_barrier
	s_setprio 1
	s_waitcnt lgkmcnt(7)
	v_mfma_i32_16x16x64_i8 v[124:127], v[128:131], v[166:169], 0
	v_mfma_i32_16x16x64_i8 v[120:123], v[136:139], v[166:169], 0
	s_waitcnt lgkmcnt(5)
	v_mfma_i32_16x16x64_i8 v[108:111], v[128:131], v[174:177], 0
	v_mfma_i32_16x16x64_i8 v[104:107], v[136:139], v[174:177], 0
	s_waitcnt lgkmcnt(3)
	v_mfma_i32_16x16x64_i8 v[92:95], v[128:131], v[182:185], 0
	v_mfma_i32_16x16x64_i8 v[88:91], v[136:139], v[182:185], 0
	s_waitcnt lgkmcnt(1)
	v_mfma_i32_16x16x64_i8 v[76:79], v[128:131], v[190:193], 0
	v_mfma_i32_16x16x64_i8 v[72:75], v[136:139], v[190:193], 0
	v_mfma_i32_16x16x64_i8 v[124:127], v[132:135], v[170:173], v[124:127]
	v_mfma_i32_16x16x64_i8 v[120:123], v[140:143], v[170:173], v[120:123]
	v_mfma_i32_16x16x64_i8 v[108:111], v[132:135], v[178:181], v[108:111]
	v_mfma_i32_16x16x64_i8 v[104:107], v[140:143], v[178:181], v[104:107]
	v_mfma_i32_16x16x64_i8 v[92:95], v[132:135], v[186:189], v[92:95]
	v_mfma_i32_16x16x64_i8 v[88:91], v[140:143], v[186:189], v[88:91]
	s_waitcnt lgkmcnt(0)
	v_mfma_i32_16x16x64_i8 v[76:79], v[132:135], v[194:197], v[76:79]
	v_mfma_i32_16x16x64_i8 v[72:75], v[140:143], v[194:197], v[72:75]
	s_setprio 0
	s_setprio 1
	v_mfma_i32_16x16x64_i8 v[116:119], v[144:147], v[166:169], 0
	v_mfma_i32_16x16x64_i8 v[112:115], v[158:161], v[166:169], 0
	v_mfma_i32_16x16x64_i8 v[100:103], v[144:147], v[174:177], 0
	v_mfma_i32_16x16x64_i8 v[96:99], v[158:161], v[174:177], 0
	v_mfma_i32_16x16x64_i8 v[84:87], v[144:147], v[182:185], 0
	v_mfma_i32_16x16x64_i8 v[80:83], v[158:161], v[182:185], 0
	v_mfma_i32_16x16x64_i8 v[68:71], v[144:147], v[190:193], 0
	v_mfma_i32_16x16x64_i8 v[64:67], v[158:161], v[190:193], 0
	v_mfma_i32_16x16x64_i8 v[116:119], v[154:157], v[170:173], v[116:119]
	v_mfma_i32_16x16x64_i8 v[112:115], v[162:165], v[170:173], v[112:115]
	v_mfma_i32_16x16x64_i8 v[100:103], v[154:157], v[178:181], v[100:103]
	v_mfma_i32_16x16x64_i8 v[96:99], v[162:165], v[178:181], v[96:99]
	v_mfma_i32_16x16x64_i8 v[84:87], v[154:157], v[186:189], v[84:87]
	v_mfma_i32_16x16x64_i8 v[80:83], v[162:165], v[186:189], v[80:83]
	v_mfma_i32_16x16x64_i8 v[68:71], v[154:157], v[194:197], v[68:71]
	v_mfma_i32_16x16x64_i8 v[64:67], v[162:165], v[194:197], v[64:67]
	s_setprio 0
	s_barrier
	ds_read_b128 v[166:169], v153 offset:16384
	ds_read_b128 v[170:173], v153 offset:17408
	ds_read_b128 v[174:177], v153 offset:18432
	ds_read_b128 v[178:181], v153 offset:19456
	ds_read_b128 v[182:185], v153 offset:20480
	ds_read_b128 v[186:189], v153 offset:21504
	ds_read_b128 v[190:193], v153 offset:22528
	ds_read_b128 v[194:197], v153 offset:23552
	s_mov_b32 s4, m0
	s_mov_b32 m0, s81
	s_nop 0
	global_load_lds_dwordx4 v149, s[68:69]
	s_mov_b32 m0, s4
	s_nop 0
	s_mov_b32 s4, m0
	s_mov_b32 m0, s82
	s_nop 0
	global_load_lds_dwordx4 v151, s[68:69]
	s_mov_b32 m0, s4
	s_add_u32 s4, s68, 0x40000
	s_addc_u32 s5, s69, 0
	s_mov_b32 s6, m0
	s_mov_b32 m0, s83
	s_nop 0
	global_load_lds_dwordx4 v149, s[4:5]
	s_mov_b32 m0, s6
	s_nop 0
	s_mov_b32 s6, m0
	s_mov_b32 m0, s84
	s_nop 0
	global_load_lds_dwordx4 v151, s[4:5]
	s_mov_b32 m0, s6
	s_mov_b32 s4, m0
	s_mov_b32 m0, s2
	s_nop 0
	global_load_lds_dwordx4 v148, s[62:63]
	s_mov_b32 m0, s4
	s_nop 0
	s_mov_b32 s4, m0
	s_mov_b32 m0, s85
	s_nop 0
	global_load_lds_dwordx4 v150, s[62:63]
	s_mov_b32 m0, s4
	s_waitcnt vmcnt(8)
	s_waitcnt lgkmcnt(0)
	s_barrier
; #define PG8_STAGE(bufoff, gbase, voff) do { _Pragma("unroll") for (int _i = 0; _i < 2; ++_i) glds16_s((gbase), (voff)[_i], ldsb + (unsigned)((bufoff) + _i * 8192)); } while (0)
; #define PG8_LDA(dst, b, h) do { _Pragma("unroll") for (int m = 0; m < 4; ++m) _Pragma("unroll") for (int k = 0; k < 2; ++k) dst[m][k] = *(const LAS h16x8*)(lds + PG8_SA(b, h) + aoff + m * 2048 + k * 1024); } while (0)
; #define PG8_LDB(dst, b, h) do { _Pragma("unroll") for (int n = 0; n < 2; ++n) _Pragma("unroll") for (int k = 0; k < 2; ++k) dst[n][k] = *(const LAS h16x8*)(lds + PG8_SB(b, h) + boff + n * 2048 + k * 1024); } while (0)
; #define PG8_MMA(ai, bj, At, Bt) do { __builtin_amdgcn_s_setprio(1); _Pragma("unroll") for (int m = 0; m < 4; ++m) _Pragma("unroll") for (int n = 0; n < 2; ++n) _Pragma("unroll") for (int k = 0; k < 2; ++k) \
;         acc[ai][bj][m][n] = mma_step<I8>(Bt[n][k], At[m][k], acc[ai][bj][m][n]); __builtin_amdgcn_s_setprio(0); } while (0)
; #define PG8_WAIT_V(n) asm volatile("s_waitcnt vmcnt(" #n ")" ::: "memory")
; #define PG8_WAIT_L(n) asm volatile("s_waitcnt lgkmcnt(" #n ")" ::: "memory")
; #define PG8_BAR __builtin_amdgcn_s_barrier()
; #define PG8_SCHED __builtin_amdgcn_sched_barrier(0)
; template <class Prob, class Epi, bool I8 = false, bool ALIGN_EPI = true, bool SP2 = true>
; __device__ __forceinline__ void gemm_phase(LAS unsigned char* lds, int wave, const Prob& P, const Epi& E) {
;     ...
;             PG8_WAIT_V(8); PG8_WAIT_L(0); PG8_BAR; PG8_MMA(1, 0, At, B0); PG8_MMA(1, 1, At, B1); PG8_BAR; PG8_SCHED;
;             PG8_LDB(B0, 1, 0); PG8_LDB(B1, 1, 1); PG8_SCHED; PG8_LDA(At, 1, 0); PG8_STAGE(PG8_SA(0, 1), a2 + hstepA, voffA);
;             PG8_WAIT_V(8); PG8_WAIT_L(0); PG8_BAR; PG8_MMA(0, 0, At, B0); PG8_MMA(0, 1, At, B1); PG8_BAR; PG8_SCHED;
;             PG8_LDA(At, 1, 1); PG8_STAGE(PG8_SB(1, 0), b3, voffB); PG8_STAGE(PG8_SB(1, 1), b3 + hstepB, voffB); PG8_STAGE(PG8_SA(1, 0), a3, voffA);
	s_setprio 1
	s_waitcnt lgkmcnt(7)
	v_mfma_i32_16x16x64_i8 v[60:63], v[128:131], v[166:169], 0
	v_mfma_i32_16x16x64_i8 v[56:59], v[136:139], v[166:169], 0
	s_waitcnt lgkmcnt(5)
	v_mfma_i32_16x16x64_i8 v[44:47], v[128:131], v[174:177], 0
	v_mfma_i32_16x16x64_i8 v[40:43], v[136:139], v[174:177], 0
	s_waitcnt lgkmcnt(3)
	v_mfma_i32_16x16x64_i8 v[28:31], v[128:131], v[182:185], 0
	v_mfma_i32_16x16x64_i8 v[24:27], v[136:139], v[182:185], 0
	s_waitcnt lgkmcnt(1)
	v_mfma_i32_16x16x64_i8 v[12:15], v[128:131], v[190:193], 0
	v_mfma_i32_16x16x64_i8 v[8:11], v[136:139], v[190:193], 0
	v_mfma_i32_16x16x64_i8 v[60:63], v[132:135], v[170:173], v[60:63]
	v_mfma_i32_16x16x64_i8 v[56:59], v[140:143], v[170:173], v[56:59]
	v_mfma_i32_16x16x64_i8 v[44:47], v[132:135], v[178:181], v[44:47]
	v_mfma_i32_16x16x64_i8 v[40:43], v[140:143], v[178:181], v[40:43]
	v_mfma_i32_16x16x64_i8 v[28:31], v[132:135], v[186:189], v[28:31]
	v_mfma_i32_16x16x64_i8 v[24:27], v[140:143], v[186:189], v[24:27]
	s_waitcnt lgkmcnt(0)
	v_mfma_i32_16x16x64_i8 v[12:15], v[132:135], v[194:197], v[12:15]
	v_mfma_i32_16x16x64_i8 v[8:11], v[140:143], v[194:197], v[8:11]
	s_setprio 0
	s_setprio 1
	v_mfma_i32_16x16x64_i8 v[52:55], v[144:147], v[166:169], 0
	v_mfma_i32_16x16x64_i8 v[48:51], v[158:161], v[166:169], 0
	v_mfma_i32_16x16x64_i8 v[36:39], v[144:147], v[174:177], 0
	v_mfma_i32_16x16x64_i8 v[32:35], v[158:161], v[174:177], 0
	v_mfma_i32_16x16x64_i8 v[20:23], v[144:147], v[182:185], 0
	v_mfma_i32_16x16x64_i8 v[16:19], v[158:161], v[182:185], 0
	v_mfma_i32_16x16x64_i8 v[4:7], v[144:147], v[190:193], 0
	v_mfma_i32_16x16x64_i8 v[0:3], v[158:161], v[190:193], 0
	v_mfma_i32_16x16x64_i8 v[52:55], v[154:157], v[170:173], v[52:55]
	v_mfma_i32_16x16x64_i8 v[48:51], v[162:165], v[170:173], v[48:51]
	v_mfma_i32_16x16x64_i8 v[36:39], v[154:157], v[178:181], v[36:39]
	v_mfma_i32_16x16x64_i8 v[32:35], v[162:165], v[178:181], v[32:35]
	v_mfma_i32_16x16x64_i8 v[20:23], v[154:157], v[186:189], v[20:23]
	v_mfma_i32_16x16x64_i8 v[16:19], v[162:165], v[186:189], v[16:19]
	v_mfma_i32_16x16x64_i8 v[4:7], v[154:157], v[194:197], v[4:7]
	v_mfma_i32_16x16x64_i8 v[0:3], v[162:165], v[194:197], v[0:3]
	s_setprio 0
	s_barrier
	v_add_u32_e32 v140, 0x18000, v152
	v_add_u32_e32 v162, 0x1c000, v152
	ds_read_b128 v[128:131], v140
	ds_read_b128 v[132:135], v140 offset:1024
	ds_read_b128 v[136:139], v140 offset:2048
	ds_read_b128 v[140:143], v140 offset:3072
	ds_read_b128 v[144:147], v162
	ds_read_b128 v[154:157], v162 offset:1024
	ds_read_b128 v[158:161], v162 offset:2048
	ds_read_b128 v[162:165], v162 offset:3072
	ds_read_b128 v[166:169], v153 offset:32768
	ds_read_b128 v[170:173], v153 offset:33792
	ds_read_b128 v[174:177], v153 offset:34816
	ds_read_b128 v[178:181], v153 offset:35840
	ds_read_b128 v[182:185], v153 offset:36864
	ds_read_b128 v[186:189], v153 offset:37888
	ds_read_b128 v[190:193], v153 offset:38912
	ds_read_b128 v[194:197], v153 offset:39936
	s_add_u32 s4, s62, 0x40000
	s_addc_u32 s5, s63, 0
	s_mov_b32 s6, m0
	s_mov_b32 m0, s86
	s_nop 0
	global_load_lds_dwordx4 v148, s[4:5]
	s_mov_b32 m0, s6
	s_nop 0
	s_mov_b32 s6, m0
	s_mov_b32 m0, s87
	s_nop 0
	global_load_lds_dwordx4 v150, s[4:5]
	s_mov_b32 m0, s6
	s_waitcnt vmcnt(8)
	s_waitcnt lgkmcnt(0)
	s_barrier
	s_setprio 1
	s_waitcnt lgkmcnt(7)
	v_mfma_i32_16x16x64_i8 v[124:127], v[128:131], v[166:169], v[124:127]
	v_mfma_i32_16x16x64_i8 v[120:123], v[136:139], v[166:169], v[120:123]
	s_waitcnt lgkmcnt(5)
	v_mfma_i32_16x16x64_i8 v[108:111], v[128:131], v[174:177], v[108:111]
	v_mfma_i32_16x16x64_i8 v[104:107], v[136:139], v[174:177], v[104:107]
	s_waitcnt lgkmcnt(3)
	v_mfma_i32_16x16x64_i8 v[92:95], v[128:131], v[182:185], v[92:95]
	v_mfma_i32_16x16x64_i8 v[88:91], v[136:139], v[182:185], v[88:91]
	s_waitcnt lgkmcnt(1)
	v_mfma_i32_16x16x64_i8 v[76:79], v[128:131], v[190:193], v[76:79]
	v_mfma_i32_16x16x64_i8 v[72:75], v[136:139], v[190:193], v[72:75]
	v_mfma_i32_16x16x64_i8 v[124:127], v[132:135], v[170:173], v[124:127]
	v_mfma_i32_16x16x64_i8 v[120:123], v[140:143], v[170:173], v[120:123]
	v_mfma_i32_16x16x64_i8 v[108:111], v[132:135], v[178:181], v[108:111]
	v_mfma_i32_16x16x64_i8 v[104:107], v[140:143], v[178:181], v[104:107]
	v_mfma_i32_16x16x64_i8 v[92:95], v[132:135], v[186:189], v[92:95]
	v_mfma_i32_16x16x64_i8 v[88:91], v[140:143], v[186:189], v[88:91]
	s_waitcnt lgkmcnt(0)
	v_mfma_i32_16x16x64_i8 v[76:79], v[132:135], v[194:197], v[76:79]
	v_mfma_i32_16x16x64_i8 v[72:75], v[140:143], v[194:197], v[72:75]
	s_setprio 0
	s_setprio 1
	v_mfma_i32_16x16x64_i8 v[116:119], v[144:147], v[166:169], v[116:119]
	v_mfma_i32_16x16x64_i8 v[112:115], v[158:161], v[166:169], v[112:115]
	v_mfma_i32_16x16x64_i8 v[100:103], v[144:147], v[174:177], v[100:103]
	v_mfma_i32_16x16x64_i8 v[96:99], v[158:161], v[174:177], v[96:99]
	v_mfma_i32_16x16x64_i8 v[84:87], v[144:147], v[182:185], v[84:87]
	v_mfma_i32_16x16x64_i8 v[80:83], v[158:161], v[182:185], v[80:83]
	v_mfma_i32_16x16x64_i8 v[68:71], v[144:147], v[190:193], v[68:71]
	v_mfma_i32_16x16x64_i8 v[64:67], v[158:161], v[190:193], v[64:67]
	v_mfma_i32_16x16x64_i8 v[116:119], v[154:157], v[170:173], v[116:119]
	v_mfma_i32_16x16x64_i8 v[112:115], v[162:165], v[170:173], v[112:115]
	v_mfma_i32_16x16x64_i8 v[100:103], v[154:157], v[178:181], v[100:103]
	v_mfma_i32_16x16x64_i8 v[96:99], v[162:165], v[178:181], v[96:99]
	v_mfma_i32_16x16x64_i8 v[84:87], v[154:157], v[186:189], v[84:87]
	v_mfma_i32_16x16x64_i8 v[80:83], v[162:165], v[186:189], v[80:83]
	v_mfma_i32_16x16x64_i8 v[68:71], v[154:157], v[194:197], v[68:71]
	v_mfma_i32_16x16x64_i8 v[64:67], v[162:165], v[194:197], v[64:67]
	s_setprio 0
	s_barrier
; #define PG8_STAGE(bufoff, gbase, voff) do { _Pragma("unroll") for (int _i = 0; _i < 2; ++_i) glds16_s((gbase), (voff)[_i], ldsb + (unsigned)((bufoff) + _i * 8192)); } while (0)
; #define PG8_LDA(dst, b, h) do { _Pragma("unroll") for (int m = 0; m < 4; ++m) _Pragma("unroll") for (int k = 0; k < 2; ++k) dst[m][k] = *(const LAS h16x8*)(lds + PG8_SA(b, h) + aoff + m * 2048 + k * 1024); } while (0)
; #define PG8_MMA(ai, bj, At, Bt) do { __builtin_amdgcn_s_setprio(1); _Pragma("unroll") for (int m = 0; m < 4; ++m) _Pragma("unroll") for (int n = 0; n < 2; ++n) _Pragma("unroll") for (int k = 0; k < 2; ++k) \
;         acc[ai][bj][m][n] = mma_step<I8>(Bt[n][k], At[m][k], acc[ai][bj][m][n]); __builtin_amdgcn_s_setprio(0); } while (0)
; #define PG8_WAIT_V(n) asm volatile("s_waitcnt vmcnt(" #n ")" ::: "memory")
; #define PG8_WAIT_L(n) asm volatile("s_waitcnt lgkmcnt(" #n ")" ::: "memory")
; #define PG8_BAR __builtin_amdgcn_s_barrier()
; #define PG8_SCHED __builtin_amdgcn_sched_barrier(0)
; template <class Prob, class Epi, bool I8 = false, bool ALIGN_EPI = true, bool SP2 = true>
; __device__ __forceinline__ void gemm_phase(LAS unsigned char* lds, int wave, const Prob& P, const Epi& E) {
;     ...
;         for (int t = 0; t < nt; t += 2) {
;             const bool last = (t == nt - 2);
;             const char* a1 = cA + (size_t)(t + 1) * kstep;
;             const char* a2 = last ? nA : cA + (size_t)(t + 2) * kstep; const char* b2 = last ? nB : cB + (size_t)(t + 2) * kstep;
;             const char* a3 = a2 + kstep; const char* b3 = b2 + kstep;
;     ...
;             PG8_LDA(At, 1, 1); PG8_STAGE(PG8_SB(1, 0), b3, voffB); PG8_STAGE(PG8_SB(1, 1), b3 + hstepB, voffB); PG8_STAGE(PG8_SA(1, 0), a3, voffA);
;             PG8_WAIT_V(8); PG8_WAIT_L(0); PG8_BAR; PG8_MMA(1, 0, At, B0); PG8_MMA(1, 1, At, B1); PG8_BAR; PG8_SCHED;
	ds_read_b128 v[166:169], v153 offset:49152
	ds_read_b128 v[170:173], v153 offset:50176
	ds_read_b128 v[174:177], v153 offset:51200
	ds_read_b128 v[178:181], v153 offset:52224
	ds_read_b128 v[182:185], v153 offset:53248
	ds_read_b128 v[186:189], v153 offset:54272
	ds_read_b128 v[190:193], v153 offset:55296
	ds_read_b128 v[194:197], v153 offset:56320
	s_add_u32 s4, s68, 0x80
	s_addc_u32 s5, s69, 0
	s_mov_b32 s6, m0
	s_mov_b32 m0, s90
	s_nop 0
	global_load_lds_dwordx4 v149, s[4:5]
	s_mov_b32 m0, s6
	s_nop 0
	s_mov_b32 s6, m0
	s_mov_b32 m0, s91
	s_nop 0
	global_load_lds_dwordx4 v151, s[4:5]
	s_mov_b32 m0, s6
	s_add_u32 s4, s68, 0x40080
	s_addc_u32 s5, s69, 0
	s_mov_b32 s6, m0
	s_mov_b32 m0, s94
	s_nop 0
	global_load_lds_dwordx4 v149, s[4:5]
	s_mov_b32 m0, s6
	s_nop 0
	s_mov_b32 s6, m0
	s_mov_b32 m0, s95
	s_nop 0
	global_load_lds_dwordx4 v151, s[4:5]
	s_mov_b32 m0, s6
	s_mov_b32 s4, m0
	s_mov_b32 m0, s92
	s_nop 0
	global_load_lds_dwordx4 v148, s[56:57]
	s_mov_b32 m0, s4
	s_nop 0
	s_mov_b32 s4, m0
	s_mov_b32 m0, s93
	s_nop 0
	global_load_lds_dwordx4 v150, s[56:57]
	s_mov_b32 m0, s4
	s_waitcnt vmcnt(8)
	s_waitcnt lgkmcnt(0)
	s_barrier
	s_setprio 1
	s_waitcnt lgkmcnt(7)
	v_mfma_i32_16x16x64_i8 v[60:63], v[128:131], v[166:169], v[60:63]
	v_mfma_i32_16x16x64_i8 v[56:59], v[136:139], v[166:169], v[56:59]
	s_waitcnt lgkmcnt(5)
	v_mfma_i32_16x16x64_i8 v[44:47], v[128:131], v[174:177], v[44:47]
	v_mfma_i32_16x16x64_i8 v[40:43], v[136:139], v[174:177], v[40:43]
	s_waitcnt lgkmcnt(3)
	v_mfma_i32_16x16x64_i8 v[28:31], v[128:131], v[182:185], v[28:31]
	v_mfma_i32_16x16x64_i8 v[24:27], v[136:139], v[182:185], v[24:27]
	s_waitcnt lgkmcnt(1)
	v_mfma_i32_16x16x64_i8 v[12:15], v[128:131], v[190:193], v[12:15]
	v_mfma_i32_16x16x64_i8 v[8:11], v[136:139], v[190:193], v[8:11]
	v_mfma_i32_16x16x64_i8 v[60:63], v[132:135], v[170:173], v[60:63]
	v_mfma_i32_16x16x64_i8 v[56:59], v[140:143], v[170:173], v[56:59]
	v_mfma_i32_16x16x64_i8 v[44:47], v[132:135], v[178:181], v[44:47]
	v_mfma_i32_16x16x64_i8 v[40:43], v[140:143], v[178:181], v[40:43]
	v_mfma_i32_16x16x64_i8 v[28:31], v[132:135], v[186:189], v[28:31]
	v_mfma_i32_16x16x64_i8 v[24:27], v[140:143], v[186:189], v[24:27]
	s_waitcnt lgkmcnt(0)
	v_mfma_i32_16x16x64_i8 v[12:15], v[132:135], v[194:197], v[12:15]
	v_mfma_i32_16x16x64_i8 v[8:11], v[140:143], v[194:197], v[8:11]
	s_setprio 0
	s_setprio 1
	v_mfma_i32_16x16x64_i8 v[52:55], v[144:147], v[166:169], v[52:55]
	v_mfma_i32_16x16x64_i8 v[48:51], v[158:161], v[166:169], v[48:51]
	v_mfma_i32_16x16x64_i8 v[36:39], v[144:147], v[174:177], v[36:39]
	v_mfma_i32_16x16x64_i8 v[32:35], v[158:161], v[174:177], v[32:35]
	v_mfma_i32_16x16x64_i8 v[20:23], v[144:147], v[182:185], v[20:23]
	v_mfma_i32_16x16x64_i8 v[16:19], v[158:161], v[182:185], v[16:19]
	v_mfma_i32_16x16x64_i8 v[4:7], v[144:147], v[190:193], v[4:7]
	v_mfma_i32_16x16x64_i8 v[0:3], v[158:161], v[190:193], v[0:3]
	v_mfma_i32_16x16x64_i8 v[52:55], v[154:157], v[170:173], v[52:55]
	v_mfma_i32_16x16x64_i8 v[48:51], v[162:165], v[170:173], v[48:51]
	v_mfma_i32_16x16x64_i8 v[36:39], v[154:157], v[178:181], v[36:39]
	v_mfma_i32_16x16x64_i8 v[32:35], v[162:165], v[178:181], v[32:35]
	v_mfma_i32_16x16x64_i8 v[20:23], v[154:157], v[186:189], v[20:23]
	v_mfma_i32_16x16x64_i8 v[16:19], v[162:165], v[186:189], v[16:19]
	v_mfma_i32_16x16x64_i8 v[4:7], v[154:157], v[194:197], v[4:7]
	v_mfma_i32_16x16x64_i8 v[0:3], v[162:165], v[194:197], v[0:3]
	s_setprio 0
	s_barrier
	s_add_i32 s1, s1, 2
	s_add_u32 s73, s73, 0x100
	s_addc_u32 vcc_lo, vcc_lo, 0
	s_add_u32 vcc_hi, vcc_hi, 0x100
	s_addc_u32 s0, s0, 0
	s_add_u32 s44, s44, 0x100
	s_addc_u32 s45, s45, 0
	s_cmp_gt_u32 s1, 13

; #define PG8_STAGE(bufoff, gbase, voff) do { _Pragma("unroll") for (int _i = 0; _i < 2; ++_i) glds16_s((gbase), (voff)[_i], ldsb + (unsigned)((bufoff) + _i * 8192)); } while (0)
; #define PG8_LDA(dst, b, h) do { _Pragma("unroll") for (int m = 0; m < 4; ++m) _Pragma("unroll") for (int k = 0; k < 2; ++k) dst[m][k] = *(const LAS h16x8*)(lds + PG8_SA(b, h) + aoff + m * 2048 + k * 1024); } while (0)
; #define PG8_LDB(dst, b, h) do { _Pragma("unroll") for (int n = 0; n < 2; ++n) _Pragma("unroll") for (int k = 0; k < 2; ++k) dst[n][k] = *(const LAS h16x8*)(lds + PG8_SB(b, h) + boff + n * 2048 + k * 1024); } while (0)
; #define PG8_MMA(ai, bj, At, Bt) do { __builtin_amdgcn_s_setprio(1); _Pragma("unroll") for (int m = 0; m < 4; ++m) _Pragma("unroll") for (int n = 0; n < 2; ++n) _Pragma("unroll") for (int k = 0; k < 2; ++k) \
;         acc[ai][bj][m][n] = mma_step<I8>(Bt[n][k], At[m][k], acc[ai][bj][m][n]); __builtin_amdgcn_s_setprio(0); } while (0)
; #define PG8_WAIT_V(n) asm volatile("s_waitcnt vmcnt(" #n ")" ::: "memory")
; #define PG8_WAIT_L(n) asm volatile("s_waitcnt lgkmcnt(" #n ")" ::: "memory")
; template <class Prob, class Epi, bool I8 = false, bool ALIGN_EPI = true, bool SP2 = true>
; __device__ __forceinline__ void gemm_phase(LAS unsigned char* lds, int wave, const Prob& P, const Epi& E) {
;     ...
;     for (;;) {
;         const bool has_next = P.next(ui + 1, nxt);
;         const char* nA = has_next ? P.a_tile(nxt) : cA; const char* nB = has_next ? P.b_tile(nxt) : cB;
;         for (int t = 0; t < nt; t += 2) {
;             const bool last = (t == nt - 2);
;             const char* a1 = cA + (size_t)(t + 1) * kstep;
;             const char* a2 = last ? nA : cA + (size_t)(t + 2) * kstep; const char* b2 = last ? nB : cB + (size_t)(t + 2) * kstep;
;             const char* a3 = a2 + kstep; const char* b3 = b2 + kstep;
;             if constexpr (SP2) {
;             PG8_LDB(B0, 0, 0); PG8_LDB(B1, 0, 1); PG8_SCHED; PG8_LDA(At, 0, 0); PG8_STAGE(PG8_SA(1, 1), a1 + hstepA, voffA);
;             PG8_WAIT_V(8); PG8_WAIT_L(0); PG8_BAR; PG8_MMA(0, 0, At, B0); PG8_MMA(0, 1, At, B1); PG8_BAR; PG8_SCHED;
;             PG8_LDA(At, 0, 1); PG8_STAGE(PG8_SB(0, 0), b2, voffB); PG8_STAGE(PG8_SB(0, 1), b2 + hstepB, voffB); PG8_STAGE(PG8_SA(0, 0), a2, voffA);
;             PG8_WAIT_V(8); PG8_WAIT_L(0); PG8_BAR; PG8_MMA(1, 0, At, B0); PG8_MMA(1, 1, At, B1); PG8_BAR; PG8_SCHED;
.LBB0_862:
	s_ashr_i32 s27, s26, 31
	s_lshl_b64 s[0:1], s[26:27], 20
	s_add_u32 s28, s76, s0
	s_addc_u32 s29, s77, s1
	s_and_b64 s[0:1], s[36:37], exec
	s_cselect_b32 s27, s29, s43
	s_cselect_b32 s83, s28, s42
	s_ashr_i32 s23, s22, 31
	s_lshl_b64 s[0:1], s[22:23], 20
	s_add_u32 s38, s2, s0
	s_addc_u32 s39, s19, s1
	s_and_b64 s[0:1], s[36:37], exec
	s_cselect_b32 s23, s39, s41
	s_cselect_b32 s84, s38, s40
	s_add_u32 s85, s42, 0x100
	s_addc_u32 s86, s43, 0
	s_add_u32 s87, s40, 0x100
	s_addc_u32 s0, s41, 0
	s_add_u32 s40, s42, 0x80080
	s_addc_u32 s41, s43, 0
	s_mov_b32 s1, -2
.Lpeel_863:
	v_add_u32_e32 v140, 0x10000, v146
	ds_read_b128 v[128:131], v140
	ds_read_b128 v[132:135], v140 offset:1024
	ds_read_b128 v[136:139], v140 offset:2048
	ds_read_b128 v[148:151], v140 offset:3072
	v_add_u32_e32 v140, 0x14000, v146
	ds_read_b128 v[152:155], v140
	ds_read_b128 v[156:159], v140 offset:1024
	ds_read_b128 v[160:163], v140 offset:2048
	ds_read_b128 v[164:167], v140 offset:3072
	s_cmp_eq_u32 s1, 28
	s_cselect_b32 s46, s83, s85
	s_cselect_b32 s47, s27, s86
	s_cselect_b32 s44, s84, s87
	s_cselect_b32 s45, s23, s0
	s_add_u32 s42, s46, 0x80
	s_addc_u32 s43, s47, 0
	ds_read_b128 v[168:171], v147
	ds_read_b128 v[172:175], v147 offset:1024
	ds_read_b128 v[176:179], v147 offset:2048
	ds_read_b128 v[180:183], v147 offset:3072
	ds_read_b128 v[184:187], v147 offset:4096
	ds_read_b128 v[188:191], v147 offset:5120
	ds_read_b128 v[192:195], v147 offset:6144
	ds_read_b128 v[196:199], v147 offset:7168
	s_mov_b32 s4, m0
	s_mov_b32 m0, s75
	s_nop 0
	global_load_lds_dwordx4 v142, s[40:41]
	s_mov_b32 m0, s4
	s_nop 0
	s_mov_b32 s4, m0
	s_mov_b32 m0, s79
	s_nop 0
	global_load_lds_dwordx4 v144, s[40:41]
	s_mov_b32 m0, s4
	s_waitcnt vmcnt(8)
	s_waitcnt lgkmcnt(0)
	s_barrier
	s_setprio 1
	s_waitcnt lgkmcnt(7)
	v_mfma_f32_16x16x32_f16 v[124:127], v[128:131], v[168:171], 0
	v_mfma_f32_16x16x32_f16 v[120:123], v[136:139], v[168:171], 0
	s_waitcnt lgkmcnt(5)
	v_mfma_f32_16x16x32_f16 v[116:119], v[128:131], v[176:179], 0
	v_mfma_f32_16x16x32_f16 v[112:115], v[136:139], v[176:179], 0
	s_waitcnt lgkmcnt(3)
	v_mfma_f32_16x16x32_f16 v[108:111], v[128:131], v[184:187], 0
	v_mfma_f32_16x16x32_f16 v[104:107], v[136:139], v[184:187], 0
	s_waitcnt lgkmcnt(1)
	v_mfma_f32_16x16x32_f16 v[100:103], v[128:131], v[192:195], 0
	v_mfma_f32_16x16x32_f16 v[96:99], v[136:139], v[192:195], 0
	v_mfma_f32_16x16x32_f16 v[124:127], v[132:135], v[172:175], v[124:127]
	v_mfma_f32_16x16x32_f16 v[120:123], v[148:151], v[172:175], v[120:123]
	v_mfma_f32_16x16x32_f16 v[116:119], v[132:135], v[180:183], v[116:119]
	v_mfma_f32_16x16x32_f16 v[112:115], v[148:151], v[180:183], v[112:115]
	v_mfma_f32_16x16x32_f16 v[108:111], v[132:135], v[188:191], v[108:111]
	v_mfma_f32_16x16x32_f16 v[104:107], v[148:151], v[188:191], v[104:107]
	s_waitcnt lgkmcnt(0)
	v_mfma_f32_16x16x32_f16 v[100:103], v[132:135], v[196:199], v[100:103]
	v_mfma_f32_16x16x32_f16 v[96:99], v[148:151], v[196:199], v[96:99]
	s_setprio 0
	s_setprio 1
	v_mfma_f32_16x16x32_f16 v[64:67], v[152:155], v[168:171], 0
	v_mfma_f32_16x16x32_f16 v[56:59], v[160:163], v[168:171], 0
	v_mfma_f32_16x16x32_f16 v[52:55], v[152:155], v[176:179], 0
	v_mfma_f32_16x16x32_f16 v[48:51], v[160:163], v[176:179], 0
	v_mfma_f32_16x16x32_f16 v[44:47], v[152:155], v[184:187], 0
	v_mfma_f32_16x16x32_f16 v[40:43], v[160:163], v[184:187], 0
	v_mfma_f32_16x16x32_f16 v[36:39], v[152:155], v[192:195], 0
	v_mfma_f32_16x16x32_f16 v[32:35], v[160:163], v[192:195], 0
	v_mfma_f32_16x16x32_f16 v[64:67], v[156:159], v[172:175], v[64:67]
	v_mfma_f32_16x16x32_f16 v[56:59], v[164:167], v[172:175], v[56:59]
	v_mfma_f32_16x16x32_f16 v[52:55], v[156:159], v[180:183], v[52:55]
	v_mfma_f32_16x16x32_f16 v[48:51], v[164:167], v[180:183], v[48:51]
	v_mfma_f32_16x16x32_f16 v[44:47], v[156:159], v[188:191], v[44:47]
	v_mfma_f32_16x16x32_f16 v[40:43], v[164:167], v[188:191], v[40:43]
	v_mfma_f32_16x16x32_f16 v[36:39], v[156:159], v[196:199], v[36:39]
	v_mfma_f32_16x16x32_f16 v[32:35], v[164:167], v[196:199], v[32:35]
	s_setprio 0
	s_barrier
	ds_read_b128 v[168:171], v147 offset:16384
	ds_read_b128 v[172:175], v147 offset:17408
	ds_read_b128 v[176:179], v147 offset:18432
	ds_read_b128 v[180:183], v147 offset:19456
	ds_read_b128 v[184:187], v147 offset:20480
	ds_read_b128 v[188:191], v147 offset:21504
	ds_read_b128 v[192:195], v147 offset:22528
	ds_read_b128 v[196:199], v147 offset:23552
	s_mov_b32 s4, m0
	s_mov_b32 m0, s49
	s_nop 0
	global_load_lds_dwordx4 v143, s[44:45]
	s_mov_b32 m0, s4
	s_nop 0
	s_mov_b32 s4, m0
	s_mov_b32 m0, s50
	s_nop 0
	global_load_lds_dwordx4 v145, s[44:45]
	s_mov_b32 m0, s4
	s_add_u32 s4, s44, 0x80000
	s_addc_u32 s5, s45, 0
	s_mov_b32 s6, m0
	s_mov_b32 m0, s51
	s_nop 0
	global_load_lds_dwordx4 v143, s[4:5]
	s_mov_b32 m0, s6
	s_nop 0
	s_mov_b32 s6, m0
	s_mov_b32 m0, s56
	s_nop 0
	global_load_lds_dwordx4 v145, s[4:5]
	s_mov_b32 m0, s6
	s_mov_b32 s4, m0
	s_mov_b32 m0, s48
	s_nop 0
	global_load_lds_dwordx4 v142, s[46:47]
	s_mov_b32 m0, s4
	s_nop 0
	s_mov_b32 s4, m0
	s_mov_b32 m0, s57
	s_nop 0
	global_load_lds_dwordx4 v144, s[46:47]
	s_mov_b32 m0, s4
	s_waitcnt vmcnt(8)
	s_waitcnt lgkmcnt(0)
	s_barrier
; #define PG8_STAGE(bufoff, gbase, voff) do { _Pragma("unroll") for (int _i = 0; _i < 2; ++_i) glds16_s((gbase), (voff)[_i], ldsb + (unsigned)((bufoff) + _i * 8192)); } while (0)
; #define PG8_LDA(dst, b, h) do { _Pragma("unroll") for (int m = 0; m < 4; ++m) _Pragma("unroll") for (int k = 0; k < 2; ++k) dst[m][k] = *(const LAS h16x8*)(lds + PG8_SA(b, h) + aoff + m * 2048 + k * 1024); } while (0)
; #define PG8_LDB(dst, b, h) do { _Pragma("unroll") for (int n = 0; n < 2; ++n) _Pragma("unroll") for (int k = 0; k < 2; ++k) dst[n][k] = *(const LAS h16x8*)(lds + PG8_SB(b, h) + boff + n * 2048 + k * 1024); } while (0)
; #define PG8_MMA(ai, bj, At, Bt) do { __builtin_amdgcn_s_setprio(1); _Pragma("unroll") for (int m = 0; m < 4; ++m) _Pragma("unroll") for (int n = 0; n < 2; ++n) _Pragma("unroll") for (int k = 0; k < 2; ++k) \
;         acc[ai][bj][m][n] = mma_step<I8>(Bt[n][k], At[m][k], acc[ai][bj][m][n]); __builtin_amdgcn_s_setprio(0); } while (0)
; #define PG8_WAIT_V(n) asm volatile("s_waitcnt vmcnt(" #n ")" ::: "memory")
; #define PG8_WAIT_L(n) asm volatile("s_waitcnt lgkmcnt(" #n ")" ::: "memory")
; #define PG8_BAR __builtin_amdgcn_s_barrier()
; #define PG8_SCHED __builtin_amdgcn_sched_barrier(0)
; template <class Prob, class Epi, bool I8 = false, bool ALIGN_EPI = true, bool SP2 = true>
; __device__ __forceinline__ void gemm_phase(LAS unsigned char* lds, int wave, const Prob& P, const Epi& E) {
;     ...
;             PG8_WAIT_V(8); PG8_WAIT_L(0); PG8_BAR; PG8_MMA(1, 0, At, B0); PG8_MMA(1, 1, At, B1); PG8_BAR; PG8_SCHED;
;             PG8_LDB(B0, 1, 0); PG8_LDB(B1, 1, 1); PG8_SCHED; PG8_LDA(At, 1, 0); PG8_STAGE(PG8_SA(0, 1), a2 + hstepA, voffA);
;             PG8_WAIT_V(8); PG8_WAIT_L(0); PG8_BAR; PG8_MMA(0, 0, At, B0); PG8_MMA(0, 1, At, B1); PG8_BAR; PG8_SCHED;
;             PG8_LDA(At, 1, 1); PG8_STAGE(PG8_SB(1, 0), b3, voffB); PG8_STAGE(PG8_SB(1, 1), b3 + hstepB, voffB); PG8_STAGE(PG8_SA(1, 0), a3, voffA);
	s_setprio 1
	s_waitcnt lgkmcnt(7)
	v_mfma_f32_16x16x32_f16 v[92:95], v[128:131], v[168:171], 0
	v_mfma_f32_16x16x32_f16 v[88:91], v[136:139], v[168:171], 0
	s_waitcnt lgkmcnt(5)
	v_mfma_f32_16x16x32_f16 v[84:87], v[128:131], v[176:179], 0
	v_mfma_f32_16x16x32_f16 v[80:83], v[136:139], v[176:179], 0
	s_waitcnt lgkmcnt(3)
	v_mfma_f32_16x16x32_f16 v[76:79], v[128:131], v[184:187], 0
	v_mfma_f32_16x16x32_f16 v[72:75], v[136:139], v[184:187], 0
	s_waitcnt lgkmcnt(1)
	v_mfma_f32_16x16x32_f16 v[68:71], v[128:131], v[192:195], 0
	v_mfma_f32_16x16x32_f16 v[60:63], v[136:139], v[192:195], 0
	v_mfma_f32_16x16x32_f16 v[92:95], v[132:135], v[172:175], v[92:95]
	v_mfma_f32_16x16x32_f16 v[88:91], v[148:151], v[172:175], v[88:91]
	v_mfma_f32_16x16x32_f16 v[84:87], v[132:135], v[180:183], v[84:87]
	v_mfma_f32_16x16x32_f16 v[80:83], v[148:151], v[180:183], v[80:83]
	v_mfma_f32_16x16x32_f16 v[76:79], v[132:135], v[188:191], v[76:79]
	v_mfma_f32_16x16x32_f16 v[72:75], v[148:151], v[188:191], v[72:75]
	s_waitcnt lgkmcnt(0)
	v_mfma_f32_16x16x32_f16 v[68:71], v[132:135], v[196:199], v[68:71]
	v_mfma_f32_16x16x32_f16 v[60:63], v[148:151], v[196:199], v[60:63]
	s_setprio 0
	s_setprio 1
	v_mfma_f32_16x16x32_f16 v[28:31], v[152:155], v[168:171], 0
	v_mfma_f32_16x16x32_f16 v[24:27], v[160:163], v[168:171], 0
	v_mfma_f32_16x16x32_f16 v[20:23], v[152:155], v[176:179], 0
	v_mfma_f32_16x16x32_f16 v[16:19], v[160:163], v[176:179], 0
	v_mfma_f32_16x16x32_f16 v[12:15], v[152:155], v[184:187], 0
	v_mfma_f32_16x16x32_f16 v[8:11], v[160:163], v[184:187], 0
	v_mfma_f32_16x16x32_f16 v[4:7], v[152:155], v[192:195], 0
	v_mfma_f32_16x16x32_f16 v[0:3], v[160:163], v[192:195], 0
	v_mfma_f32_16x16x32_f16 v[28:31], v[156:159], v[172:175], v[28:31]
	v_mfma_f32_16x16x32_f16 v[24:27], v[164:167], v[172:175], v[24:27]
	v_mfma_f32_16x16x32_f16 v[20:23], v[156:159], v[180:183], v[20:23]
	v_mfma_f32_16x16x32_f16 v[16:19], v[164:167], v[180:183], v[16:19]
	v_mfma_f32_16x16x32_f16 v[12:15], v[156:159], v[188:191], v[12:15]
	v_mfma_f32_16x16x32_f16 v[8:11], v[164:167], v[188:191], v[8:11]
	v_mfma_f32_16x16x32_f16 v[4:7], v[156:159], v[196:199], v[4:7]
	v_mfma_f32_16x16x32_f16 v[0:3], v[164:167], v[196:199], v[0:3]
	s_setprio 0
	s_barrier
	v_add_u32_e32 v140, 0x18000, v146
	ds_read_b128 v[128:131], v140
	ds_read_b128 v[132:135], v140 offset:1024
	ds_read_b128 v[136:139], v140 offset:2048
	ds_read_b128 v[148:151], v140 offset:3072
	v_add_u32_e32 v140, 0x1c000, v146
	ds_read_b128 v[152:155], v140
	ds_read_b128 v[156:159], v140 offset:1024
	ds_read_b128 v[160:163], v140 offset:2048
	ds_read_b128 v[164:167], v140 offset:3072
	ds_read_b128 v[168:171], v147 offset:32768
	ds_read_b128 v[172:175], v147 offset:33792
	ds_read_b128 v[176:179], v147 offset:34816
	ds_read_b128 v[180:183], v147 offset:35840
	ds_read_b128 v[184:187], v147 offset:36864
	ds_read_b128 v[188:191], v147 offset:37888
	ds_read_b128 v[192:195], v147 offset:38912
	ds_read_b128 v[196:199], v147 offset:39936
	s_add_u32 s4, s46, 0x80000
	s_addc_u32 s5, s47, 0
	s_mov_b32 s6, m0
	s_mov_b32 m0, s60
	s_nop 0
	global_load_lds_dwordx4 v142, s[4:5]
	s_mov_b32 m0, s6
	s_nop 0
	s_mov_b32 s6, m0
	s_mov_b32 m0, s61
	s_nop 0
	global_load_lds_dwordx4 v144, s[4:5]
	s_mov_b32 m0, s6
	s_waitcnt vmcnt(8)
	s_waitcnt lgkmcnt(0)
	s_barrier
	s_setprio 1
	s_waitcnt lgkmcnt(7)
	v_mfma_f32_16x16x32_f16 v[124:127], v[128:131], v[168:171], v[124:127]
	v_mfma_f32_16x16x32_f16 v[120:123], v[136:139], v[168:171], v[120:123]
	s_waitcnt lgkmcnt(5)
	v_mfma_f32_16x16x32_f16 v[116:119], v[128:131], v[176:179], v[116:119]
	v_mfma_f32_16x16x32_f16 v[112:115], v[136:139], v[176:179], v[112:115]
	s_waitcnt lgkmcnt(3)
	v_mfma_f32_16x16x32_f16 v[108:111], v[128:131], v[184:187], v[108:111]
	v_mfma_f32_16x16x32_f16 v[104:107], v[136:139], v[184:187], v[104:107]
	s_waitcnt lgkmcnt(1)
	v_mfma_f32_16x16x32_f16 v[100:103], v[128:131], v[192:195], v[100:103]
	v_mfma_f32_16x16x32_f16 v[96:99], v[136:139], v[192:195], v[96:99]
	v_mfma_f32_16x16x32_f16 v[124:127], v[132:135], v[172:175], v[124:127]
	v_mfma_f32_16x16x32_f16 v[120:123], v[148:151], v[172:175], v[120:123]
	v_mfma_f32_16x16x32_f16 v[116:119], v[132:135], v[180:183], v[116:119]
	v_mfma_f32_16x16x32_f16 v[112:115], v[148:151], v[180:183], v[112:115]
	v_mfma_f32_16x16x32_f16 v[108:111], v[132:135], v[188:191], v[108:111]
	v_mfma_f32_16x16x32_f16 v[104:107], v[148:151], v[188:191], v[104:107]
	s_waitcnt lgkmcnt(0)
	v_mfma_f32_16x16x32_f16 v[100:103], v[132:135], v[196:199], v[100:103]
	v_mfma_f32_16x16x32_f16 v[96:99], v[148:151], v[196:199], v[96:99]
	s_setprio 0
	s_setprio 1
	v_mfma_f32_16x16x32_f16 v[64:67], v[152:155], v[168:171], v[64:67]
	v_mfma_f32_16x16x32_f16 v[56:59], v[160:163], v[168:171], v[56:59]
	v_mfma_f32_16x16x32_f16 v[52:55], v[152:155], v[176:179], v[52:55]
	v_mfma_f32_16x16x32_f16 v[48:51], v[160:163], v[176:179], v[48:51]
	v_mfma_f32_16x16x32_f16 v[44:47], v[152:155], v[184:187], v[44:47]
	v_mfma_f32_16x16x32_f16 v[40:43], v[160:163], v[184:187], v[40:43]
	v_mfma_f32_16x16x32_f16 v[36:39], v[152:155], v[192:195], v[36:39]
	v_mfma_f32_16x16x32_f16 v[32:35], v[160:163], v[192:195], v[32:35]
	v_mfma_f32_16x16x32_f16 v[64:67], v[156:159], v[172:175], v[64:67]
	v_mfma_f32_16x16x32_f16 v[56:59], v[164:167], v[172:175], v[56:59]
	v_mfma_f32_16x16x32_f16 v[52:55], v[156:159], v[180:183], v[52:55]
	v_mfma_f32_16x16x32_f16 v[48:51], v[164:167], v[180:183], v[48:51]
	v_mfma_f32_16x16x32_f16 v[44:47], v[156:159], v[188:191], v[44:47]
	v_mfma_f32_16x16x32_f16 v[40:43], v[164:167], v[188:191], v[40:43]
	v_mfma_f32_16x16x32_f16 v[36:39], v[156:159], v[196:199], v[36:39]
	v_mfma_f32_16x16x32_f16 v[32:35], v[164:167], v[196:199], v[32:35]
	s_setprio 0
	s_barrier
; #define PG8_STAGE(bufoff, gbase, voff) do { _Pragma("unroll") for (int _i = 0; _i < 2; ++_i) glds16_s((gbase), (voff)[_i], ldsb + (unsigned)((bufoff) + _i * 8192)); } while (0)
; #define PG8_LDA(dst, b, h) do { _Pragma("unroll") for (int m = 0; m < 4; ++m) _Pragma("unroll") for (int k = 0; k < 2; ++k) dst[m][k] = *(const LAS h16x8*)(lds + PG8_SA(b, h) + aoff + m * 2048 + k * 1024); } while (0)
; #define PG8_MMA(ai, bj, At, Bt) do { __builtin_amdgcn_s_setprio(1); _Pragma("unroll") for (int m = 0; m < 4; ++m) _Pragma("unroll") for (int n = 0; n < 2; ++n) _Pragma("unroll") for (int k = 0; k < 2; ++k) \
;         acc[ai][bj][m][n] = mma_step<I8>(Bt[n][k], At[m][k], acc[ai][bj][m][n]); __builtin_amdgcn_s_setprio(0); } while (0)
; #define PG8_WAIT_V(n) asm volatile("s_waitcnt vmcnt(" #n ")" ::: "memory")
; #define PG8_WAIT_L(n) asm volatile("s_waitcnt lgkmcnt(" #n ")" ::: "memory")
; #define PG8_BAR __builtin_amdgcn_s_barrier()
; #define PG8_SCHED __builtin_amdgcn_sched_barrier(0)
; template <class Prob, class Epi, bool I8 = false, bool ALIGN_EPI = true, bool SP2 = true>
; __device__ __forceinline__ void gemm_phase(LAS unsigned char* lds, int wave, const Prob& P, const Epi& E) {
;     ...
;         for (int t = 0; t < nt; t += 2) {
;             const bool last = (t == nt - 2);
;             const char* a1 = cA + (size_t)(t + 1) * kstep;
;             const char* a2 = last ? nA : cA + (size_t)(t + 2) * kstep; const char* b2 = last ? nB : cB + (size_t)(t + 2) * kstep;
;             const char* a3 = a2 + kstep; const char* b3 = b2 + kstep;
;     ...
;             PG8_LDA(At, 1, 1); PG8_STAGE(PG8_SB(1, 0), b3, voffB); PG8_STAGE(PG8_SB(1, 1), b3 + hstepB, voffB); PG8_STAGE(PG8_SA(1, 0), a3, voffA);
;             PG8_WAIT_V(8); PG8_WAIT_L(0); PG8_BAR; PG8_MMA(1, 0, At, B0); PG8_MMA(1, 1, At, B1); PG8_BAR; PG8_SCHED;
	ds_read_b128 v[168:171], v147 offset:49152
	ds_read_b128 v[172:175], v147 offset:50176
	ds_read_b128 v[176:179], v147 offset:51200
	ds_read_b128 v[180:183], v147 offset:52224
	ds_read_b128 v[184:187], v147 offset:53248
	ds_read_b128 v[188:191], v147 offset:54272
	ds_read_b128 v[192:195], v147 offset:55296
	ds_read_b128 v[196:199], v147 offset:56320
	s_add_u32 s4, s44, 0x80
	s_addc_u32 s5, s45, 0
	s_mov_b32 s6, m0
	s_mov_b32 m0, s64
	s_nop 0
	global_load_lds_dwordx4 v143, s[4:5]
	s_mov_b32 m0, s6
	s_nop 0
	s_mov_b32 s6, m0
	s_mov_b32 m0, s68
	s_nop 0
	global_load_lds_dwordx4 v145, s[4:5]
	s_mov_b32 m0, s6
	s_add_u32 s4, s44, 0x80080
	s_addc_u32 s5, s45, 0
	s_mov_b32 s6, m0
	s_mov_b32 m0, s73
	s_nop 0
	global_load_lds_dwordx4 v143, s[4:5]
	s_mov_b32 m0, s6
	s_nop 0
	s_mov_b32 s6, m0
	s_mov_b32 m0, s74
	s_nop 0
	global_load_lds_dwordx4 v145, s[4:5]
	s_mov_b32 m0, s6
	s_mov_b32 s4, m0
	s_mov_b32 m0, s69
	s_nop 0
	global_load_lds_dwordx4 v142, s[42:43]
	s_mov_b32 m0, s4
	s_nop 0
	s_mov_b32 s4, m0
	s_mov_b32 m0, s72
	s_nop 0
	global_load_lds_dwordx4 v144, s[42:43]
	s_mov_b32 m0, s4
	s_waitcnt vmcnt(8)
	s_waitcnt lgkmcnt(0)
	s_barrier
	s_setprio 1
	s_waitcnt lgkmcnt(7)
	v_mfma_f32_16x16x32_f16 v[92:95], v[128:131], v[168:171], v[92:95]
	v_mfma_f32_16x16x32_f16 v[88:91], v[136:139], v[168:171], v[88:91]
	s_waitcnt lgkmcnt(5)
	v_mfma_f32_16x16x32_f16 v[84:87], v[128:131], v[176:179], v[84:87]
	v_mfma_f32_16x16x32_f16 v[80:83], v[136:139], v[176:179], v[80:83]
	s_waitcnt lgkmcnt(3)
	v_mfma_f32_16x16x32_f16 v[76:79], v[128:131], v[184:187], v[76:79]
	v_mfma_f32_16x16x32_f16 v[72:75], v[136:139], v[184:187], v[72:75]
	s_waitcnt lgkmcnt(1)
	v_mfma_f32_16x16x32_f16 v[68:71], v[128:131], v[192:195], v[68:71]
	v_mfma_f32_16x16x32_f16 v[60:63], v[136:139], v[192:195], v[60:63]
	v_mfma_f32_16x16x32_f16 v[92:95], v[132:135], v[172:175], v[92:95]
	v_mfma_f32_16x16x32_f16 v[88:91], v[148:151], v[172:175], v[88:91]
	v_mfma_f32_16x16x32_f16 v[84:87], v[132:135], v[180:183], v[84:87]
	v_mfma_f32_16x16x32_f16 v[80:83], v[148:151], v[180:183], v[80:83]
	v_mfma_f32_16x16x32_f16 v[76:79], v[132:135], v[188:191], v[76:79]
	v_mfma_f32_16x16x32_f16 v[72:75], v[148:151], v[188:191], v[72:75]
	s_waitcnt lgkmcnt(0)
	v_mfma_f32_16x16x32_f16 v[68:71], v[132:135], v[196:199], v[68:71]
	v_mfma_f32_16x16x32_f16 v[60:63], v[148:151], v[196:199], v[60:63]
	s_setprio 0
	s_setprio 1
	v_mfma_f32_16x16x32_f16 v[28:31], v[152:155], v[168:171], v[28:31]
	v_mfma_f32_16x16x32_f16 v[24:27], v[160:163], v[168:171], v[24:27]
	v_mfma_f32_16x16x32_f16 v[20:23], v[152:155], v[176:179], v[20:23]
	v_mfma_f32_16x16x32_f16 v[16:19], v[160:163], v[176:179], v[16:19]
	v_mfma_f32_16x16x32_f16 v[12:15], v[152:155], v[184:187], v[12:15]
	v_mfma_f32_16x16x32_f16 v[8:11], v[160:163], v[184:187], v[8:11]
	v_mfma_f32_16x16x32_f16 v[4:7], v[152:155], v[192:195], v[4:7]
	v_mfma_f32_16x16x32_f16 v[0:3], v[160:163], v[192:195], v[0:3]
	v_mfma_f32_16x16x32_f16 v[28:31], v[156:159], v[172:175], v[28:31]
	v_mfma_f32_16x16x32_f16 v[24:27], v[164:167], v[172:175], v[24:27]
	v_mfma_f32_16x16x32_f16 v[20:23], v[156:159], v[180:183], v[20:23]
	v_mfma_f32_16x16x32_f16 v[16:19], v[164:167], v[180:183], v[16:19]
	v_mfma_f32_16x16x32_f16 v[12:15], v[156:159], v[188:191], v[12:15]
	v_mfma_f32_16x16x32_f16 v[8:11], v[164:167], v[188:191], v[8:11]
	v_mfma_f32_16x16x32_f16 v[4:7], v[156:159], v[196:199], v[4:7]
	v_mfma_f32_16x16x32_f16 v[0:3], v[164:167], v[196:199], v[0:3]
	s_setprio 0
	s_barrier
	s_add_i32 s1, s1, 2
	s_add_u32 s85, s85, 0x100
	s_addc_u32 s86, s86, 0
	s_add_u32 s87, s87, 0x100
	s_addc_u32 s0, s0, 0
	s_add_u32 s40, s40, 0x100
	s_addc_u32 s41, s41, 0
	s_cmp_gt_u32 s1, 29

; #define PG8_STAGE(bufoff, gbase, voff) do { _Pragma("unroll") for (int _i = 0; _i < 2; ++_i) glds16_s((gbase), (voff)[_i], ldsb + (unsigned)((bufoff) + _i * 8192)); } while (0)
; #define PG8_LDA(dst, b, h) do { _Pragma("unroll") for (int m = 0; m < 4; ++m) _Pragma("unroll") for (int k = 0; k < 2; ++k) dst[m][k] = *(const LAS h16x8*)(lds + PG8_SA(b, h) + aoff + m * 2048 + k * 1024); } while (0)
; #define PG8_LDB(dst, b, h) do { _Pragma("unroll") for (int n = 0; n < 2; ++n) _Pragma("unroll") for (int k = 0; k < 2; ++k) dst[n][k] = *(const LAS h16x8*)(lds + PG8_SB(b, h) + boff + n * 2048 + k * 1024); } while (0)
; #define PG8_MMA(ai, bj, At, Bt) do { __builtin_amdgcn_s_setprio(1); _Pragma("unroll") for (int m = 0; m < 4; ++m) _Pragma("unroll") for (int n = 0; n < 2; ++n) _Pragma("unroll") for (int k = 0; k < 2; ++k) \
;         acc[ai][bj][m][n] = mma_step<I8>(Bt[n][k], At[m][k], acc[ai][bj][m][n]); __builtin_amdgcn_s_setprio(0); } while (0)
; #define PG8_WAIT_V(n) asm volatile("s_waitcnt vmcnt(" #n ")" ::: "memory")
; #define PG8_WAIT_L(n) asm volatile("s_waitcnt lgkmcnt(" #n ")" ::: "memory")
; template <class Prob, class Epi, bool I8 = false, bool ALIGN_EPI = true, bool SP2 = true>
; __device__ __forceinline__ void gemm_phase(LAS unsigned char* lds, int wave, const Prob& P, const Epi& E) {
;     ...
;     for (;;) {
;         const bool has_next = P.next(ui + 1, nxt);
;         const char* nA = has_next ? P.a_tile(nxt) : cA; const char* nB = has_next ? P.b_tile(nxt) : cB;
;         for (int t = 0; t < nt; t += 2) {
;             const bool last = (t == nt - 2);
;             const char* a1 = cA + (size_t)(t + 1) * kstep;
;             const char* a2 = last ? nA : cA + (size_t)(t + 2) * kstep; const char* b2 = last ? nB : cB + (size_t)(t + 2) * kstep;
;             const char* a3 = a2 + kstep; const char* b3 = b2 + kstep;
;             if constexpr (SP2) {
;             PG8_LDB(B0, 0, 0); PG8_LDB(B1, 0, 1); PG8_SCHED; PG8_LDA(At, 0, 0); PG8_STAGE(PG8_SA(1, 1), a1 + hstepA, voffA);
;             PG8_WAIT_V(8); PG8_WAIT_L(0); PG8_BAR; PG8_MMA(0, 0, At, B0); PG8_MMA(0, 1, At, B1); PG8_BAR; PG8_SCHED;
;             PG8_LDA(At, 0, 1); PG8_STAGE(PG8_SB(0, 0), b2, voffB); PG8_STAGE(PG8_SB(0, 1), b2 + hstepB, voffB); PG8_STAGE(PG8_SA(0, 0), a2, voffA);
;             PG8_WAIT_V(8); PG8_WAIT_L(0); PG8_BAR; PG8_MMA(1, 0, At, B0); PG8_MMA(1, 1, At, B1); PG8_BAR; PG8_SCHED;
.LBB0_994:
	s_ashr_i32 s29, s28, 31
	s_lshl_b64 s[0:1], s[28:29], 25
	s_add_u32 s0, s41, s0
	s_addc_u32 s1, s19, s1
	s_add_u32 s36, s0, 0xfffff800
	s_addc_u32 s37, s1, -1
	s_and_b64 s[0:1], s[46:47], exec
	s_cselect_b32 s29, s37, s51
	s_cselect_b32 s89, s36, s50
	s_ashr_i32 s23, s22, 31
	s_lshl_b64 s[0:1], s[22:23], 19
	s_add_u32 s48, s79, s0
	s_addc_u32 s49, s40, s1
	s_and_b64 s[0:1], s[46:47], exec
	s_cselect_b32 s23, s49, s45
	s_cselect_b32 s90, s48, s44
	s_add_u32 s91, s50, 0x100
	s_addc_u32 s92, s51, 0
	s_add_u32 s93, s44, 0x100
	s_addc_u32 s0, s45, 0
	s_add_u32 s44, s50, 0x1000080
	s_addc_u32 s45, s51, 0
	s_mov_b32 s1, -2
.Lpeel_995:
	v_add_u32_e32 v128, 0x10000, v133
	ds_read_b128 v[136:139], v128
	ds_read_b128 v[140:143], v128 offset:1024
	ds_read_b128 v[144:147], v128 offset:2048
	ds_read_b128 v[148:151], v128 offset:3072
	v_add_u32_e32 v128, 0x14000, v133
	ds_read_b128 v[152:155], v128
	ds_read_b128 v[156:159], v128 offset:1024
	ds_read_b128 v[160:163], v128 offset:2048
	ds_read_b128 v[164:167], v128 offset:3072
	s_cmp_eq_u32 s1, 12
	s_cselect_b32 s60, s89, s91
	s_cselect_b32 s61, s29, s92
	s_cselect_b32 s56, s90, s93
	s_cselect_b32 s57, s23, s0
	s_add_u32 s50, s60, 0x80
	s_addc_u32 s51, s61, 0
	ds_read_b128 v[168:171], v134
	ds_read_b128 v[172:175], v134 offset:1024
	ds_read_b128 v[176:179], v134 offset:2048
	ds_read_b128 v[180:183], v134 offset:3072
	ds_read_b128 v[184:187], v134 offset:4096
	ds_read_b128 v[188:191], v134 offset:5120
	ds_read_b128 v[192:195], v134 offset:6144
	ds_read_b128 v[196:199], v134 offset:7168
	s_mov_b32 s4, m0
	s_mov_b32 m0, s84
	s_nop 0
	global_load_lds_dwordx4 v129, s[44:45]
	s_mov_b32 m0, s4
	s_nop 0
	s_mov_b32 s4, m0
	s_mov_b32 m0, s85
	s_nop 0
	global_load_lds_dwordx4 v131, s[44:45]
	s_mov_b32 m0, s4
	s_waitcnt vmcnt(8)
	s_waitcnt lgkmcnt(0)
	s_barrier
	s_setprio 1
	s_waitcnt lgkmcnt(7)
	v_mfma_i32_16x16x64_i8 v[16:19], v[136:139], v[168:171], 0
	v_mfma_i32_16x16x64_i8 v[20:23], v[144:147], v[168:171], 0
	s_waitcnt lgkmcnt(5)
	v_mfma_i32_16x16x64_i8 v[48:51], v[136:139], v[176:179], 0
	v_mfma_i32_16x16x64_i8 v[52:55], v[144:147], v[176:179], 0
	s_waitcnt lgkmcnt(3)
	v_mfma_i32_16x16x64_i8 v[72:75], v[136:139], v[184:187], 0
	v_mfma_i32_16x16x64_i8 v[76:79], v[144:147], v[184:187], 0
	s_waitcnt lgkmcnt(1)
	v_mfma_i32_16x16x64_i8 v[96:99], v[136:139], v[192:195], 0
	v_mfma_i32_16x16x64_i8 v[100:103], v[144:147], v[192:195], 0
	v_mfma_i32_16x16x64_i8 v[16:19], v[140:143], v[172:175], v[16:19]
	v_mfma_i32_16x16x64_i8 v[20:23], v[148:151], v[172:175], v[20:23]
	v_mfma_i32_16x16x64_i8 v[48:51], v[140:143], v[180:183], v[48:51]
	v_mfma_i32_16x16x64_i8 v[52:55], v[148:151], v[180:183], v[52:55]
	v_mfma_i32_16x16x64_i8 v[72:75], v[140:143], v[188:191], v[72:75]
	v_mfma_i32_16x16x64_i8 v[76:79], v[148:151], v[188:191], v[76:79]
	s_waitcnt lgkmcnt(0)
	v_mfma_i32_16x16x64_i8 v[96:99], v[140:143], v[196:199], v[96:99]
	v_mfma_i32_16x16x64_i8 v[100:103], v[148:151], v[196:199], v[100:103]
	s_setprio 0
	s_setprio 1
	v_mfma_i32_16x16x64_i8 v[24:27], v[152:155], v[168:171], 0
	v_mfma_i32_16x16x64_i8 v[28:31], v[160:163], v[168:171], 0
	v_mfma_i32_16x16x64_i8 v[56:59], v[152:155], v[176:179], 0
	v_mfma_i32_16x16x64_i8 v[60:63], v[160:163], v[176:179], 0
	v_mfma_i32_16x16x64_i8 v[80:83], v[152:155], v[184:187], 0
	v_mfma_i32_16x16x64_i8 v[84:87], v[160:163], v[184:187], 0
	v_mfma_i32_16x16x64_i8 v[104:107], v[152:155], v[192:195], 0
	v_mfma_i32_16x16x64_i8 v[108:111], v[160:163], v[192:195], 0
	v_mfma_i32_16x16x64_i8 v[24:27], v[156:159], v[172:175], v[24:27]
	v_mfma_i32_16x16x64_i8 v[28:31], v[164:167], v[172:175], v[28:31]
	v_mfma_i32_16x16x64_i8 v[56:59], v[156:159], v[180:183], v[56:59]
	v_mfma_i32_16x16x64_i8 v[60:63], v[164:167], v[180:183], v[60:63]
	v_mfma_i32_16x16x64_i8 v[80:83], v[156:159], v[188:191], v[80:83]
	v_mfma_i32_16x16x64_i8 v[84:87], v[164:167], v[188:191], v[84:87]
	v_mfma_i32_16x16x64_i8 v[104:107], v[156:159], v[196:199], v[104:107]
	v_mfma_i32_16x16x64_i8 v[108:111], v[164:167], v[196:199], v[108:111]
	s_setprio 0
	s_barrier
	ds_read_b128 v[168:171], v134 offset:16384
	ds_read_b128 v[172:175], v134 offset:17408
	ds_read_b128 v[176:179], v134 offset:18432
	ds_read_b128 v[180:183], v134 offset:19456
	ds_read_b128 v[184:187], v134 offset:20480
	ds_read_b128 v[188:191], v134 offset:21504
	ds_read_b128 v[192:195], v134 offset:22528
	ds_read_b128 v[196:199], v134 offset:23552
	s_mov_b32 s4, m0
	s_mov_b32 m0, s62
	s_nop 0
	global_load_lds_dwordx4 v130, s[56:57]
	s_mov_b32 m0, s4
	s_nop 0
	s_mov_b32 s4, m0
	s_mov_b32 m0, s63
	s_nop 0
	global_load_lds_dwordx4 v132, s[56:57]
	s_mov_b32 m0, s4
	s_add_u32 s4, s56, 0x40000
	s_addc_u32 s5, s57, 0
	s_mov_b32 s6, m0
	s_mov_b32 m0, s64
	s_nop 0
	global_load_lds_dwordx4 v130, s[4:5]
	s_mov_b32 m0, s6
	s_nop 0
	s_mov_b32 s6, m0
	s_mov_b32 m0, s68
	s_nop 0
	global_load_lds_dwordx4 v132, s[4:5]
	s_mov_b32 m0, s6
	s_mov_b32 s4, m0
	s_mov_b32 m0, s2
	s_nop 0
	global_load_lds_dwordx4 v129, s[60:61]
	s_mov_b32 m0, s4
	s_nop 0
	s_mov_b32 s4, m0
	s_mov_b32 m0, s69
	s_nop 0
	global_load_lds_dwordx4 v131, s[60:61]
	s_mov_b32 m0, s4
	s_waitcnt vmcnt(8)
	s_waitcnt lgkmcnt(0)
	s_barrier
; #define PG8_STAGE(bufoff, gbase, voff) do { _Pragma("unroll") for (int _i = 0; _i < 2; ++_i) glds16_s((gbase), (voff)[_i], ldsb + (unsigned)((bufoff) + _i * 8192)); } while (0)
; #define PG8_LDA(dst, b, h) do { _Pragma("unroll") for (int m = 0; m < 4; ++m) _Pragma("unroll") for (int k = 0; k < 2; ++k) dst[m][k] = *(const LAS h16x8*)(lds + PG8_SA(b, h) + aoff + m * 2048 + k * 1024); } while (0)
; #define PG8_LDB(dst, b, h) do { _Pragma("unroll") for (int n = 0; n < 2; ++n) _Pragma("unroll") for (int k = 0; k < 2; ++k) dst[n][k] = *(const LAS h16x8*)(lds + PG8_SB(b, h) + boff + n * 2048 + k * 1024); } while (0)
; #define PG8_MMA(ai, bj, At, Bt) do { __builtin_amdgcn_s_setprio(1); _Pragma("unroll") for (int m = 0; m < 4; ++m) _Pragma("unroll") for (int n = 0; n < 2; ++n) _Pragma("unroll") for (int k = 0; k < 2; ++k) \
;         acc[ai][bj][m][n] = mma_step<I8>(Bt[n][k], At[m][k], acc[ai][bj][m][n]); __builtin_amdgcn_s_setprio(0); } while (0)
; #define PG8_WAIT_V(n) asm volatile("s_waitcnt vmcnt(" #n ")" ::: "memory")
; #define PG8_WAIT_L(n) asm volatile("s_waitcnt lgkmcnt(" #n ")" ::: "memory")
; #define PG8_BAR __builtin_amdgcn_s_barrier()
; #define PG8_SCHED __builtin_amdgcn_sched_barrier(0)
; template <class Prob, class Epi, bool I8 = false, bool ALIGN_EPI = true, bool SP2 = true>
; __device__ __forceinline__ void gemm_phase(LAS unsigned char* lds, int wave, const Prob& P, const Epi& E) {
;     ...
;             PG8_WAIT_V(8); PG8_WAIT_L(0); PG8_BAR; PG8_MMA(1, 0, At, B0); PG8_MMA(1, 1, At, B1); PG8_BAR; PG8_SCHED;
;             PG8_LDB(B0, 1, 0); PG8_LDB(B1, 1, 1); PG8_SCHED; PG8_LDA(At, 1, 0); PG8_STAGE(PG8_SA(0, 1), a2 + hstepA, voffA);
;             PG8_WAIT_V(8); PG8_WAIT_L(0); PG8_BAR; PG8_MMA(0, 0, At, B0); PG8_MMA(0, 1, At, B1); PG8_BAR; PG8_SCHED;
;             PG8_LDA(At, 1, 1); PG8_STAGE(PG8_SB(1, 0), b3, voffB); PG8_STAGE(PG8_SB(1, 1), b3 + hstepB, voffB); PG8_STAGE(PG8_SA(1, 0), a3, voffA);
	s_setprio 1
	s_waitcnt lgkmcnt(7)
	v_mfma_i32_16x16x64_i8 v[124:127], v[136:139], v[168:171], 0
	v_mfma_i32_16x16x64_i8 v[120:123], v[144:147], v[168:171], 0
	s_waitcnt lgkmcnt(5)
	v_mfma_i32_16x16x64_i8 v[92:95], v[136:139], v[176:179], 0
	v_mfma_i32_16x16x64_i8 v[88:91], v[144:147], v[176:179], 0
	s_waitcnt lgkmcnt(3)
	v_mfma_i32_16x16x64_i8 v[44:47], v[136:139], v[184:187], 0
	v_mfma_i32_16x16x64_i8 v[40:43], v[144:147], v[184:187], 0
	s_waitcnt lgkmcnt(1)
	v_mfma_i32_16x16x64_i8 v[12:15], v[136:139], v[192:195], 0
	v_mfma_i32_16x16x64_i8 v[8:11], v[144:147], v[192:195], 0
	v_mfma_i32_16x16x64_i8 v[124:127], v[140:143], v[172:175], v[124:127]
	v_mfma_i32_16x16x64_i8 v[120:123], v[148:151], v[172:175], v[120:123]
	v_mfma_i32_16x16x64_i8 v[92:95], v[140:143], v[180:183], v[92:95]
	v_mfma_i32_16x16x64_i8 v[88:91], v[148:151], v[180:183], v[88:91]
	v_mfma_i32_16x16x64_i8 v[44:47], v[140:143], v[188:191], v[44:47]
	v_mfma_i32_16x16x64_i8 v[40:43], v[148:151], v[188:191], v[40:43]
	s_waitcnt lgkmcnt(0)
	v_mfma_i32_16x16x64_i8 v[12:15], v[140:143], v[196:199], v[12:15]
	v_mfma_i32_16x16x64_i8 v[8:11], v[148:151], v[196:199], v[8:11]
	s_setprio 0
	s_setprio 1
	v_mfma_i32_16x16x64_i8 v[116:119], v[152:155], v[168:171], 0
	v_mfma_i32_16x16x64_i8 v[112:115], v[160:163], v[168:171], 0
	v_mfma_i32_16x16x64_i8 v[68:71], v[152:155], v[176:179], 0
	v_mfma_i32_16x16x64_i8 v[64:67], v[160:163], v[176:179], 0
	v_mfma_i32_16x16x64_i8 v[36:39], v[152:155], v[184:187], 0
	v_mfma_i32_16x16x64_i8 v[32:35], v[160:163], v[184:187], 0
	v_mfma_i32_16x16x64_i8 v[4:7], v[152:155], v[192:195], 0
	v_mfma_i32_16x16x64_i8 v[0:3], v[160:163], v[192:195], 0
	v_mfma_i32_16x16x64_i8 v[116:119], v[156:159], v[172:175], v[116:119]
	v_mfma_i32_16x16x64_i8 v[112:115], v[164:167], v[172:175], v[112:115]
	v_mfma_i32_16x16x64_i8 v[68:71], v[156:159], v[180:183], v[68:71]
	v_mfma_i32_16x16x64_i8 v[64:67], v[164:167], v[180:183], v[64:67]
	v_mfma_i32_16x16x64_i8 v[36:39], v[156:159], v[188:191], v[36:39]
	v_mfma_i32_16x16x64_i8 v[32:35], v[164:167], v[188:191], v[32:35]
	v_mfma_i32_16x16x64_i8 v[4:7], v[156:159], v[196:199], v[4:7]
	v_mfma_i32_16x16x64_i8 v[0:3], v[164:167], v[196:199], v[0:3]
	s_setprio 0
	s_barrier
	v_add_u32_e32 v128, 0x18000, v133
	ds_read_b128 v[136:139], v128
	ds_read_b128 v[140:143], v128 offset:1024
	ds_read_b128 v[144:147], v128 offset:2048
	ds_read_b128 v[148:151], v128 offset:3072
	v_add_u32_e32 v128, 0x1c000, v133
	ds_read_b128 v[152:155], v128
	ds_read_b128 v[156:159], v128 offset:1024
	ds_read_b128 v[160:163], v128 offset:2048
	ds_read_b128 v[164:167], v128 offset:3072
	ds_read_b128 v[168:171], v134 offset:32768
	ds_read_b128 v[172:175], v134 offset:33792
	ds_read_b128 v[176:179], v134 offset:34816
	ds_read_b128 v[180:183], v134 offset:35840
	ds_read_b128 v[184:187], v134 offset:36864
	ds_read_b128 v[188:191], v134 offset:37888
	ds_read_b128 v[192:195], v134 offset:38912
	ds_read_b128 v[196:199], v134 offset:39936
	s_add_u32 s4, s60, 0x1000000
	s_addc_u32 s5, s61, 0
	s_mov_b32 s6, m0
	s_mov_b32 m0, s72
	s_nop 0
	global_load_lds_dwordx4 v129, s[4:5]
	s_mov_b32 m0, s6
	s_nop 0
	s_mov_b32 s6, m0
	s_mov_b32 m0, s73
	s_nop 0
	global_load_lds_dwordx4 v131, s[4:5]
	s_mov_b32 m0, s6
	s_waitcnt vmcnt(8)
	s_waitcnt lgkmcnt(0)
	s_barrier
	s_setprio 1
	s_waitcnt lgkmcnt(7)
	v_mfma_i32_16x16x64_i8 v[16:19], v[136:139], v[168:171], v[16:19]
	v_mfma_i32_16x16x64_i8 v[20:23], v[144:147], v[168:171], v[20:23]
	s_waitcnt lgkmcnt(5)
	v_mfma_i32_16x16x64_i8 v[48:51], v[136:139], v[176:179], v[48:51]
	v_mfma_i32_16x16x64_i8 v[52:55], v[144:147], v[176:179], v[52:55]
	s_waitcnt lgkmcnt(3)
	v_mfma_i32_16x16x64_i8 v[72:75], v[136:139], v[184:187], v[72:75]
	v_mfma_i32_16x16x64_i8 v[76:79], v[144:147], v[184:187], v[76:79]
	s_waitcnt lgkmcnt(1)
	v_mfma_i32_16x16x64_i8 v[96:99], v[136:139], v[192:195], v[96:99]
	v_mfma_i32_16x16x64_i8 v[100:103], v[144:147], v[192:195], v[100:103]
	v_mfma_i32_16x16x64_i8 v[16:19], v[140:143], v[172:175], v[16:19]
	v_mfma_i32_16x16x64_i8 v[20:23], v[148:151], v[172:175], v[20:23]
	v_mfma_i32_16x16x64_i8 v[48:51], v[140:143], v[180:183], v[48:51]
	v_mfma_i32_16x16x64_i8 v[52:55], v[148:151], v[180:183], v[52:55]
	v_mfma_i32_16x16x64_i8 v[72:75], v[140:143], v[188:191], v[72:75]
	v_mfma_i32_16x16x64_i8 v[76:79], v[148:151], v[188:191], v[76:79]
	s_waitcnt lgkmcnt(0)
	v_mfma_i32_16x16x64_i8 v[96:99], v[140:143], v[196:199], v[96:99]
	v_mfma_i32_16x16x64_i8 v[100:103], v[148:151], v[196:199], v[100:103]
	s_setprio 0
	s_setprio 1
	v_mfma_i32_16x16x64_i8 v[24:27], v[152:155], v[168:171], v[24:27]
	v_mfma_i32_16x16x64_i8 v[28:31], v[160:163], v[168:171], v[28:31]
	v_mfma_i32_16x16x64_i8 v[56:59], v[152:155], v[176:179], v[56:59]
	v_mfma_i32_16x16x64_i8 v[60:63], v[160:163], v[176:179], v[60:63]
	v_mfma_i32_16x16x64_i8 v[80:83], v[152:155], v[184:187], v[80:83]
	v_mfma_i32_16x16x64_i8 v[84:87], v[160:163], v[184:187], v[84:87]
	v_mfma_i32_16x16x64_i8 v[104:107], v[152:155], v[192:195], v[104:107]
	v_mfma_i32_16x16x64_i8 v[108:111], v[160:163], v[192:195], v[108:111]
	v_mfma_i32_16x16x64_i8 v[24:27], v[156:159], v[172:175], v[24:27]
	v_mfma_i32_16x16x64_i8 v[28:31], v[164:167], v[172:175], v[28:31]
	v_mfma_i32_16x16x64_i8 v[56:59], v[156:159], v[180:183], v[56:59]
	v_mfma_i32_16x16x64_i8 v[60:63], v[164:167], v[180:183], v[60:63]
	v_mfma_i32_16x16x64_i8 v[80:83], v[156:159], v[188:191], v[80:83]
	v_mfma_i32_16x16x64_i8 v[84:87], v[164:167], v[188:191], v[84:87]
	v_mfma_i32_16x16x64_i8 v[104:107], v[156:159], v[196:199], v[104:107]
	v_mfma_i32_16x16x64_i8 v[108:111], v[164:167], v[196:199], v[108:111]
	s_setprio 0
	s_barrier
; #define PG8_STAGE(bufoff, gbase, voff) do { _Pragma("unroll") for (int _i = 0; _i < 2; ++_i) glds16_s((gbase), (voff)[_i], ldsb + (unsigned)((bufoff) + _i * 8192)); } while (0)
; #define PG8_LDA(dst, b, h) do { _Pragma("unroll") for (int m = 0; m < 4; ++m) _Pragma("unroll") for (int k = 0; k < 2; ++k) dst[m][k] = *(const LAS h16x8*)(lds + PG8_SA(b, h) + aoff + m * 2048 + k * 1024); } while (0)
; #define PG8_MMA(ai, bj, At, Bt) do { __builtin_amdgcn_s_setprio(1); _Pragma("unroll") for (int m = 0; m < 4; ++m) _Pragma("unroll") for (int n = 0; n < 2; ++n) _Pragma("unroll") for (int k = 0; k < 2; ++k) \
;         acc[ai][bj][m][n] = mma_step<I8>(Bt[n][k], At[m][k], acc[ai][bj][m][n]); __builtin_amdgcn_s_setprio(0); } while (0)
; #define PG8_WAIT_V(n) asm volatile("s_waitcnt vmcnt(" #n ")" ::: "memory")
; #define PG8_WAIT_L(n) asm volatile("s_waitcnt lgkmcnt(" #n ")" ::: "memory")
; #define PG8_BAR __builtin_amdgcn_s_barrier()
; #define PG8_SCHED __builtin_amdgcn_sched_barrier(0)
; template <class Prob, class Epi, bool I8 = false, bool ALIGN_EPI = true, bool SP2 = true>
; __device__ __forceinline__ void gemm_phase(LAS unsigned char* lds, int wave, const Prob& P, const Epi& E) {
;     ...
;         for (int t = 0; t < nt; t += 2) {
;             const bool last = (t == nt - 2);
;             const char* a1 = cA + (size_t)(t + 1) * kstep;
;             const char* a2 = last ? nA : cA + (size_t)(t + 2) * kstep; const char* b2 = last ? nB : cB + (size_t)(t + 2) * kstep;
;             const char* a3 = a2 + kstep; const char* b3 = b2 + kstep;
;     ...
;             PG8_LDA(At, 1, 1); PG8_STAGE(PG8_SB(1, 0), b3, voffB); PG8_STAGE(PG8_SB(1, 1), b3 + hstepB, voffB); PG8_STAGE(PG8_SA(1, 0), a3, voffA);
;             PG8_WAIT_V(8); PG8_WAIT_L(0); PG8_BAR; PG8_MMA(1, 0, At, B0); PG8_MMA(1, 1, At, B1); PG8_BAR; PG8_SCHED;
	ds_read_b128 v[168:171], v134 offset:49152
	ds_read_b128 v[172:175], v134 offset:50176
	ds_read_b128 v[176:179], v134 offset:51200
	ds_read_b128 v[180:183], v134 offset:52224
	ds_read_b128 v[184:187], v134 offset:53248
	ds_read_b128 v[188:191], v134 offset:54272
	ds_read_b128 v[192:195], v134 offset:55296
	ds_read_b128 v[196:199], v134 offset:56320
	s_add_u32 s4, s56, 0x80
	s_addc_u32 s5, s57, 0
	s_mov_b32 s6, m0
	s_mov_b32 m0, s76
	s_nop 0
	global_load_lds_dwordx4 v130, s[4:5]
	s_mov_b32 m0, s6
	s_nop 0
	s_mov_b32 s6, m0
	s_mov_b32 m0, s77
	s_nop 0
	global_load_lds_dwordx4 v132, s[4:5]
	s_mov_b32 m0, s6
	s_add_u32 s4, s56, 0x40080
	s_addc_u32 s5, s57, 0
	s_mov_b32 s6, m0
	s_mov_b32 m0, s82
	s_nop 0
	global_load_lds_dwordx4 v130, s[4:5]
	s_mov_b32 m0, s6
	s_nop 0
	s_mov_b32 s6, m0
	s_mov_b32 m0, s83
	s_nop 0
	global_load_lds_dwordx4 v132, s[4:5]
	s_mov_b32 m0, s6
	s_mov_b32 s4, m0
	s_mov_b32 m0, s80
	s_nop 0
	global_load_lds_dwordx4 v129, s[50:51]
	s_mov_b32 m0, s4
	s_nop 0
	s_mov_b32 s4, m0
	s_mov_b32 m0, s81
	s_nop 0
	global_load_lds_dwordx4 v131, s[50:51]
	s_mov_b32 m0, s4
	s_waitcnt vmcnt(8)
	s_waitcnt lgkmcnt(0)
	s_barrier
	s_setprio 1
	s_waitcnt lgkmcnt(7)
	v_mfma_i32_16x16x64_i8 v[124:127], v[136:139], v[168:171], v[124:127]
	v_mfma_i32_16x16x64_i8 v[120:123], v[144:147], v[168:171], v[120:123]
	s_waitcnt lgkmcnt(5)
	v_mfma_i32_16x16x64_i8 v[92:95], v[136:139], v[176:179], v[92:95]
	v_mfma_i32_16x16x64_i8 v[88:91], v[144:147], v[176:179], v[88:91]
	s_waitcnt lgkmcnt(3)
	v_mfma_i32_16x16x64_i8 v[44:47], v[136:139], v[184:187], v[44:47]
	v_mfma_i32_16x16x64_i8 v[40:43], v[144:147], v[184:187], v[40:43]
	s_waitcnt lgkmcnt(1)
	v_mfma_i32_16x16x64_i8 v[12:15], v[136:139], v[192:195], v[12:15]
	v_mfma_i32_16x16x64_i8 v[8:11], v[144:147], v[192:195], v[8:11]
	v_mfma_i32_16x16x64_i8 v[124:127], v[140:143], v[172:175], v[124:127]
	v_mfma_i32_16x16x64_i8 v[120:123], v[148:151], v[172:175], v[120:123]
	v_mfma_i32_16x16x64_i8 v[92:95], v[140:143], v[180:183], v[92:95]
	v_mfma_i32_16x16x64_i8 v[88:91], v[148:151], v[180:183], v[88:91]
	v_mfma_i32_16x16x64_i8 v[44:47], v[140:143], v[188:191], v[44:47]
	v_mfma_i32_16x16x64_i8 v[40:43], v[148:151], v[188:191], v[40:43]
	s_waitcnt lgkmcnt(0)
	v_mfma_i32_16x16x64_i8 v[12:15], v[140:143], v[196:199], v[12:15]
	v_mfma_i32_16x16x64_i8 v[8:11], v[148:151], v[196:199], v[8:11]
	s_setprio 0
	s_setprio 1
	v_mfma_i32_16x16x64_i8 v[116:119], v[152:155], v[168:171], v[116:119]
	v_mfma_i32_16x16x64_i8 v[112:115], v[160:163], v[168:171], v[112:115]
	v_mfma_i32_16x16x64_i8 v[68:71], v[152:155], v[176:179], v[68:71]
	v_mfma_i32_16x16x64_i8 v[64:67], v[160:163], v[176:179], v[64:67]
	v_mfma_i32_16x16x64_i8 v[36:39], v[152:155], v[184:187], v[36:39]
	v_mfma_i32_16x16x64_i8 v[32:35], v[160:163], v[184:187], v[32:35]
	v_mfma_i32_16x16x64_i8 v[4:7], v[152:155], v[192:195], v[4:7]
	v_mfma_i32_16x16x64_i8 v[0:3], v[160:163], v[192:195], v[0:3]
	v_mfma_i32_16x16x64_i8 v[116:119], v[156:159], v[172:175], v[116:119]
	v_mfma_i32_16x16x64_i8 v[112:115], v[164:167], v[172:175], v[112:115]
	v_mfma_i32_16x16x64_i8 v[68:71], v[156:159], v[180:183], v[68:71]
	v_mfma_i32_16x16x64_i8 v[64:67], v[164:167], v[180:183], v[64:67]
	v_mfma_i32_16x16x64_i8 v[36:39], v[156:159], v[188:191], v[36:39]
	v_mfma_i32_16x16x64_i8 v[32:35], v[164:167], v[188:191], v[32:35]
	v_mfma_i32_16x16x64_i8 v[4:7], v[156:159], v[196:199], v[4:7]
	v_mfma_i32_16x16x64_i8 v[0:3], v[164:167], v[196:199], v[0:3]
	s_setprio 0
	s_barrier
	s_add_i32 s1, s1, 2
	s_add_u32 s91, s91, 0x100
	s_addc_u32 s92, s92, 0
	s_add_u32 s93, s93, 0x100
	s_addc_u32 s0, s0, 0
	s_add_u32 s44, s44, 0x100
	s_addc_u32 s45, s45, 0
	s_cmp_gt_u32 s1, 13

; #define PG8_STAGE(bufoff, gbase, voff) do { _Pragma("unroll") for (int _i = 0; _i < 2; ++_i) glds16_s((gbase), (voff)[_i], ldsb + (unsigned)((bufoff) + _i * 8192)); } while (0)
; #define PG8_LDA(dst, b, h) do { _Pragma("unroll") for (int m = 0; m < 4; ++m) _Pragma("unroll") for (int k = 0; k < 2; ++k) dst[m][k] = *(const LAS h16x8*)(lds + PG8_SA(b, h) + aoff + m * 2048 + k * 1024); } while (0)
; #define PG8_LDB(dst, b, h) do { _Pragma("unroll") for (int n = 0; n < 2; ++n) _Pragma("unroll") for (int k = 0; k < 2; ++k) dst[n][k] = *(const LAS h16x8*)(lds + PG8_SB(b, h) + boff + n * 2048 + k * 1024); } while (0)
; #define PG8_MMA(ai, bj, At, Bt) do { __builtin_amdgcn_s_setprio(1); _Pragma("unroll") for (int m = 0; m < 4; ++m) _Pragma("unroll") for (int n = 0; n < 2; ++n) _Pragma("unroll") for (int k = 0; k < 2; ++k) \
;         acc[ai][bj][m][n] = mma_step<I8>(Bt[n][k], At[m][k], acc[ai][bj][m][n]); __builtin_amdgcn_s_setprio(0); } while (0)
; #define PG8_WAIT_V(n) asm volatile("s_waitcnt vmcnt(" #n ")" ::: "memory")
; #define PG8_WAIT_L(n) asm volatile("s_waitcnt lgkmcnt(" #n ")" ::: "memory")
; template <class Prob, class Epi, bool I8 = false, bool ALIGN_EPI = true, bool SP2 = true>
; __device__ __forceinline__ void gemm_phase(LAS unsigned char* lds, int wave, const Prob& P, const Epi& E) {
;     ...
;     for (;;) {
;         const bool has_next = P.next(ui + 1, nxt);
;         const char* nA = has_next ? P.a_tile(nxt) : cA; const char* nB = has_next ? P.b_tile(nxt) : cB;
;         for (int t = 0; t < nt; t += 2) {
;             const bool last = (t == nt - 2);
;             const char* a1 = cA + (size_t)(t + 1) * kstep;
;             const char* a2 = last ? nA : cA + (size_t)(t + 2) * kstep; const char* b2 = last ? nB : cB + (size_t)(t + 2) * kstep;
;             const char* a3 = a2 + kstep; const char* b3 = b2 + kstep;
;             if constexpr (SP2) {
;             PG8_LDB(B0, 0, 0); PG8_LDB(B1, 0, 1); PG8_SCHED; PG8_LDA(At, 0, 0); PG8_STAGE(PG8_SA(1, 1), a1 + hstepA, voffA);
;             PG8_WAIT_V(8); PG8_WAIT_L(0); PG8_BAR; PG8_MMA(0, 0, At, B0); PG8_MMA(0, 1, At, B1); PG8_BAR; PG8_SCHED;
;             PG8_LDA(At, 0, 1); PG8_STAGE(PG8_SB(0, 0), b2, voffB); PG8_STAGE(PG8_SB(0, 1), b2 + hstepB, voffB); PG8_STAGE(PG8_SA(0, 0), a2, voffA);
;             PG8_WAIT_V(8); PG8_WAIT_L(0); PG8_BAR; PG8_MMA(1, 0, At, B0); PG8_MMA(1, 1, At, B1); PG8_BAR; PG8_SCHED;
.LBB0_1064:
	s_ashr_i32 s51, s50, 31
	s_lshl_b64 s[0:1], s[50:51], 19
	s_add_u32 s56, s41, s0
	s_addc_u32 s57, s19, s1
	s_and_b64 s[0:1], s[36:37], exec
	s_cselect_b32 s51, s57, s61
	s_cselect_b32 s96, s56, s60
	s_ashr_i32 s49, s48, 31
	s_lshl_b64 s[0:1], s[48:49], 19
	s_add_u32 s76, s79, s0
	s_addc_u32 s77, s40, s1
	s_and_b64 s[0:1], s[36:37], exec
	s_cselect_b32 s49, s77, s45
	s_cselect_b32 s97, s76, s44
	s_add_u32 vcc_lo, s60, 0x100
	s_addc_u32 vcc_hi, s61, 0
	s_add_u32 s0, s44, 0x100
	s_addc_u32 s1, s45, 0
	s_add_u32 s44, s60, 0x2080
	s_addc_u32 s45, s61, 0
	s_mov_b32 s4, -2
.Lpeel_1065:
	v_add_u32_e32 v124, 0x10000, v210
	v_add_u32_e32 v140, 0x14000, v210
	ds_read_b128 v[104:107], v124
	ds_read_b128 v[112:115], v124 offset:1024
	ds_read_b128 v[120:123], v124 offset:2048
	ds_read_b128 v[124:127], v124 offset:3072
	ds_read_b128 v[128:131], v140
	ds_read_b128 v[132:135], v140 offset:1024
	ds_read_b128 v[136:139], v140 offset:2048
	ds_read_b128 v[140:143], v140 offset:3072
	s_cmp_eq_u32 s4, 12
	s_cselect_b32 s62, s96, vcc_lo
	s_cselect_b32 s63, s51, vcc_hi
	s_cselect_b32 s68, s97, s0
	s_cselect_b32 s69, s49, s1
	s_add_u32 s60, s62, 0x80
	s_addc_u32 s61, s63, 0
	ds_read_b128 v[144:147], v211
	ds_read_b128 v[164:167], v211 offset:1024
	ds_read_b128 v[168:171], v211 offset:2048
	ds_read_b128 v[172:175], v211 offset:3072
	ds_read_b128 v[176:179], v211 offset:4096
	ds_read_b128 v[180:183], v211 offset:5120
	ds_read_b128 v[184:187], v211 offset:6144
	ds_read_b128 v[188:191], v211 offset:7168
	s_mov_b32 s5, m0
	s_mov_b32 m0, s90
	s_nop 0
	global_load_lds_dwordx4 v250, s[44:45]
	s_mov_b32 m0, s5
	s_nop 0
	s_mov_b32 s5, m0
	s_mov_b32 m0, s92
	s_nop 0
	global_load_lds_dwordx4 v247, s[44:45]
	s_mov_b32 m0, s5
	s_waitcnt vmcnt(8)
	s_waitcnt lgkmcnt(0)
	s_barrier
	s_setprio 1
	s_waitcnt lgkmcnt(7)
	v_mfma_i32_16x16x64_i8 v[160:163], v[104:107], v[144:147], 0
	v_mfma_i32_16x16x64_i8 v[152:155], v[120:123], v[144:147], 0
	s_waitcnt lgkmcnt(5)
	v_mfma_i32_16x16x64_i8 v[52:55], v[104:107], v[168:171], 0
	v_mfma_i32_16x16x64_i8 v[80:83], v[120:123], v[168:171], 0
	s_waitcnt lgkmcnt(3)
	v_mfma_i32_16x16x64_i8 v[48:51], v[104:107], v[176:179], 0
	v_mfma_i32_16x16x64_i8 v[72:75], v[120:123], v[176:179], 0
	s_waitcnt lgkmcnt(1)
	v_mfma_i32_16x16x64_i8 v[44:47], v[104:107], v[184:187], 0
	v_mfma_i32_16x16x64_i8 v[68:71], v[120:123], v[184:187], 0
	v_mfma_i32_16x16x64_i8 v[160:163], v[112:115], v[164:167], v[160:163]
	v_mfma_i32_16x16x64_i8 v[152:155], v[124:127], v[164:167], v[152:155]
	v_mfma_i32_16x16x64_i8 v[52:55], v[112:115], v[172:175], v[52:55]
	v_mfma_i32_16x16x64_i8 v[80:83], v[124:127], v[172:175], v[80:83]
	v_mfma_i32_16x16x64_i8 v[48:51], v[112:115], v[180:183], v[48:51]
	v_mfma_i32_16x16x64_i8 v[72:75], v[124:127], v[180:183], v[72:75]
	s_waitcnt lgkmcnt(0)
	v_mfma_i32_16x16x64_i8 v[44:47], v[112:115], v[188:191], v[44:47]
	v_mfma_i32_16x16x64_i8 v[68:71], v[124:127], v[188:191], v[68:71]
	s_setprio 0
	s_setprio 1
	v_mfma_i32_16x16x64_i8 v[116:119], v[128:131], v[144:147], 0
	v_mfma_i32_16x16x64_i8 v[28:31], v[136:139], v[144:147], 0
	v_mfma_i32_16x16x64_i8 v[100:103], v[128:131], v[168:171], 0
	v_mfma_i32_16x16x64_i8 v[24:27], v[136:139], v[168:171], 0
	v_mfma_i32_16x16x64_i8 v[96:99], v[128:131], v[176:179], 0
	v_mfma_i32_16x16x64_i8 v[20:23], v[136:139], v[176:179], 0
	v_mfma_i32_16x16x64_i8 v[92:95], v[128:131], v[184:187], 0
	v_mfma_i32_16x16x64_i8 v[16:19], v[136:139], v[184:187], 0
	v_mfma_i32_16x16x64_i8 v[116:119], v[132:135], v[164:167], v[116:119]
	v_mfma_i32_16x16x64_i8 v[28:31], v[140:143], v[164:167], v[28:31]
	v_mfma_i32_16x16x64_i8 v[100:103], v[132:135], v[172:175], v[100:103]
	v_mfma_i32_16x16x64_i8 v[24:27], v[140:143], v[172:175], v[24:27]
	v_mfma_i32_16x16x64_i8 v[96:99], v[132:135], v[180:183], v[96:99]
	v_mfma_i32_16x16x64_i8 v[20:23], v[140:143], v[180:183], v[20:23]
	v_mfma_i32_16x16x64_i8 v[92:95], v[132:135], v[188:191], v[92:95]
	v_mfma_i32_16x16x64_i8 v[16:19], v[140:143], v[188:191], v[16:19]
	s_setprio 0
	s_barrier
	ds_read_b128 v[144:147], v211 offset:16384
	ds_read_b128 v[164:167], v211 offset:17408
	ds_read_b128 v[168:171], v211 offset:18432
	ds_read_b128 v[172:175], v211 offset:19456
	ds_read_b128 v[176:179], v211 offset:20480
	ds_read_b128 v[180:183], v211 offset:21504
	ds_read_b128 v[184:187], v211 offset:22528
	ds_read_b128 v[188:191], v211 offset:23552
	s_mov_b32 s5, m0
	s_mov_b32 m0, s73
	s_nop 0
	global_load_lds_dwordx4 v217, s[68:69]
	s_mov_b32 m0, s5
	s_add_u32 s6, s68, 0x40000
	s_mov_b32 s5, m0
	s_mov_b32 m0, s74
	s_nop 0
	global_load_lds_dwordx4 v248, s[68:69]
	s_mov_b32 m0, s5
	s_addc_u32 s7, s69, 0
	s_mov_b32 s5, m0
	s_mov_b32 m0, s75
	s_nop 0
	global_load_lds_dwordx4 v217, s[6:7]
	s_mov_b32 m0, s5
	s_nop 0
	s_mov_b32 s5, m0
	s_mov_b32 m0, s80
	s_nop 0
	global_load_lds_dwordx4 v248, s[6:7]
	s_mov_b32 m0, s5
	s_nop 0
	s_mov_b32 s5, m0
	s_mov_b32 m0, s72
	s_nop 0
	global_load_lds_dwordx4 v250, s[62:63]
	s_mov_b32 m0, s5
	s_nop 0
	s_mov_b32 s5, m0
	s_mov_b32 m0, s81
	s_nop 0
	global_load_lds_dwordx4 v247, s[62:63]
	s_mov_b32 m0, s5
	s_waitcnt vmcnt(8)
	s_waitcnt lgkmcnt(0)
	s_barrier
; #define PG8_STAGE(bufoff, gbase, voff) do { _Pragma("unroll") for (int _i = 0; _i < 2; ++_i) glds16_s((gbase), (voff)[_i], ldsb + (unsigned)((bufoff) + _i * 8192)); } while (0)
; #define PG8_LDA(dst, b, h) do { _Pragma("unroll") for (int m = 0; m < 4; ++m) _Pragma("unroll") for (int k = 0; k < 2; ++k) dst[m][k] = *(const LAS h16x8*)(lds + PG8_SA(b, h) + aoff + m * 2048 + k * 1024); } while (0)
; #define PG8_LDB(dst, b, h) do { _Pragma("unroll") for (int n = 0; n < 2; ++n) _Pragma("unroll") for (int k = 0; k < 2; ++k) dst[n][k] = *(const LAS h16x8*)(lds + PG8_SB(b, h) + boff + n * 2048 + k * 1024); } while (0)
; #define PG8_MMA(ai, bj, At, Bt) do { __builtin_amdgcn_s_setprio(1); _Pragma("unroll") for (int m = 0; m < 4; ++m) _Pragma("unroll") for (int n = 0; n < 2; ++n) _Pragma("unroll") for (int k = 0; k < 2; ++k) \
;         acc[ai][bj][m][n] = mma_step<I8>(Bt[n][k], At[m][k], acc[ai][bj][m][n]); __builtin_amdgcn_s_setprio(0); } while (0)
; #define PG8_WAIT_V(n) asm volatile("s_waitcnt vmcnt(" #n ")" ::: "memory")
; #define PG8_WAIT_L(n) asm volatile("s_waitcnt lgkmcnt(" #n ")" ::: "memory")
; #define PG8_BAR __builtin_amdgcn_s_barrier()
; #define PG8_SCHED __builtin_amdgcn_sched_barrier(0)
; template <class Prob, class Epi, bool I8 = false, bool ALIGN_EPI = true, bool SP2 = true>
; __device__ __forceinline__ void gemm_phase(LAS unsigned char* lds, int wave, const Prob& P, const Epi& E) {
;     ...
;             PG8_WAIT_V(8); PG8_WAIT_L(0); PG8_BAR; PG8_MMA(1, 0, At, B0); PG8_MMA(1, 1, At, B1); PG8_BAR; PG8_SCHED;
;             PG8_LDB(B0, 1, 0); PG8_LDB(B1, 1, 1); PG8_SCHED; PG8_LDA(At, 1, 0); PG8_STAGE(PG8_SA(0, 1), a2 + hstepA, voffA);
;             PG8_WAIT_V(8); PG8_WAIT_L(0); PG8_BAR; PG8_MMA(0, 0, At, B0); PG8_MMA(0, 1, At, B1); PG8_BAR; PG8_SCHED;
;             PG8_LDA(At, 1, 1); PG8_STAGE(PG8_SB(1, 0), b3, voffB); PG8_STAGE(PG8_SB(1, 1), b3 + hstepB, voffB); PG8_STAGE(PG8_SA(1, 0), a3, voffA);
	s_setprio 1
	s_waitcnt lgkmcnt(7)
	v_mfma_i32_16x16x64_i8 v[40:43], v[104:107], v[144:147], 0
	v_mfma_i32_16x16x64_i8 v[64:67], v[120:123], v[144:147], 0
	s_waitcnt lgkmcnt(5)
	v_mfma_i32_16x16x64_i8 v[36:39], v[104:107], v[168:171], 0
	v_mfma_i32_16x16x64_i8 v[60:63], v[120:123], v[168:171], 0
	s_waitcnt lgkmcnt(3)
	v_mfma_i32_16x16x64_i8 v[32:35], v[104:107], v[176:179], 0
	v_mfma_i32_16x16x64_i8 v[56:59], v[120:123], v[176:179], 0
	s_waitcnt lgkmcnt(1)
	v_mfma_i32_16x16x64_i8 v[104:107], v[104:107], v[184:187], 0
	v_mfma_i32_16x16x64_i8 v[40:43], v[112:115], v[164:167], v[40:43]
	v_mfma_i32_16x16x64_i8 v[64:67], v[124:127], v[164:167], v[64:67]
	v_mfma_i32_16x16x64_i8 v[36:39], v[112:115], v[172:175], v[36:39]
	v_mfma_i32_16x16x64_i8 v[60:63], v[124:127], v[172:175], v[60:63]
	v_mfma_i32_16x16x64_i8 v[32:35], v[112:115], v[180:183], v[32:35]
	v_mfma_i32_16x16x64_i8 v[56:59], v[124:127], v[180:183], v[56:59]
	s_waitcnt lgkmcnt(0)
	v_mfma_i32_16x16x64_i8 v[104:107], v[112:115], v[188:191], v[104:107]
	v_mfma_i32_16x16x64_i8 v[112:115], v[120:123], v[184:187], 0
	v_mfma_i32_16x16x64_i8 v[112:115], v[124:127], v[188:191], v[112:115]
	s_setprio 0
	s_setprio 1
	v_mfma_i32_16x16x64_i8 v[88:91], v[128:131], v[144:147], 0
	v_mfma_i32_16x16x64_i8 v[12:15], v[136:139], v[144:147], 0
	v_mfma_i32_16x16x64_i8 v[84:87], v[128:131], v[168:171], 0
	v_mfma_i32_16x16x64_i8 v[8:11], v[136:139], v[168:171], 0
	v_mfma_i32_16x16x64_i8 v[76:79], v[128:131], v[176:179], 0
	v_mfma_i32_16x16x64_i8 v[4:7], v[136:139], v[176:179], 0
	v_mfma_i32_16x16x64_i8 v[108:111], v[128:131], v[184:187], 0
	v_mfma_i32_16x16x64_i8 v[0:3], v[136:139], v[184:187], 0
	v_mfma_i32_16x16x64_i8 v[88:91], v[132:135], v[164:167], v[88:91]
	v_mfma_i32_16x16x64_i8 v[12:15], v[140:143], v[164:167], v[12:15]
	v_mfma_i32_16x16x64_i8 v[84:87], v[132:135], v[172:175], v[84:87]
	v_mfma_i32_16x16x64_i8 v[8:11], v[140:143], v[172:175], v[8:11]
	v_mfma_i32_16x16x64_i8 v[76:79], v[132:135], v[180:183], v[76:79]
	v_mfma_i32_16x16x64_i8 v[4:7], v[140:143], v[180:183], v[4:7]
	v_mfma_i32_16x16x64_i8 v[108:111], v[132:135], v[188:191], v[108:111]
	v_mfma_i32_16x16x64_i8 v[0:3], v[140:143], v[188:191], v[0:3]
	s_setprio 0
	s_barrier
	v_add_u32_e32 v132, 0x18000, v210
	v_add_u32_e32 v148, 0x1c000, v210
	ds_read_b128 v[120:123], v132
	ds_read_b128 v[124:127], v132 offset:1024
	ds_read_b128 v[128:131], v132 offset:2048
	ds_read_b128 v[132:135], v132 offset:3072
	ds_read_b128 v[136:139], v148
	ds_read_b128 v[140:143], v148 offset:1024
	ds_read_b128 v[144:147], v148 offset:2048
	ds_read_b128 v[164:167], v148 offset:3072
	ds_read_b128 v[148:151], v211 offset:32768
	ds_read_b128 v[156:159], v211 offset:33792
	ds_read_b128 v[168:171], v211 offset:34816
	ds_read_b128 v[172:175], v211 offset:35840
	ds_read_b128 v[176:179], v211 offset:36864
	ds_read_b128 v[180:183], v211 offset:37888
	ds_read_b128 v[184:187], v211 offset:38912
	ds_read_b128 v[188:191], v211 offset:39936
	s_add_u32 s6, s62, 0x2000
	s_addc_u32 s7, s63, 0
	s_mov_b32 s5, m0
	s_mov_b32 m0, s82
	s_nop 0
	global_load_lds_dwordx4 v250, s[6:7]
	s_mov_b32 m0, s5
	s_nop 0
	s_mov_b32 s5, m0
	s_mov_b32 m0, s83
	s_nop 0
	global_load_lds_dwordx4 v247, s[6:7]
	s_mov_b32 m0, s5
	s_waitcnt vmcnt(8)
	s_waitcnt lgkmcnt(0)
	s_barrier
	s_setprio 1
	s_waitcnt lgkmcnt(7)
	v_mfma_i32_16x16x64_i8 v[160:163], v[120:123], v[148:151], v[160:163]
	v_mfma_i32_16x16x64_i8 v[152:155], v[128:131], v[148:151], v[152:155]
	s_waitcnt lgkmcnt(5)
	v_mfma_i32_16x16x64_i8 v[52:55], v[120:123], v[168:171], v[52:55]
	v_mfma_i32_16x16x64_i8 v[80:83], v[128:131], v[168:171], v[80:83]
	s_waitcnt lgkmcnt(3)
	v_mfma_i32_16x16x64_i8 v[48:51], v[120:123], v[176:179], v[48:51]
	v_mfma_i32_16x16x64_i8 v[72:75], v[128:131], v[176:179], v[72:75]
	s_waitcnt lgkmcnt(1)
	v_mfma_i32_16x16x64_i8 v[44:47], v[120:123], v[184:187], v[44:47]
	v_mfma_i32_16x16x64_i8 v[68:71], v[128:131], v[184:187], v[68:71]
	v_mfma_i32_16x16x64_i8 v[160:163], v[124:127], v[156:159], v[160:163]
	v_mfma_i32_16x16x64_i8 v[152:155], v[132:135], v[156:159], v[152:155]
	v_mfma_i32_16x16x64_i8 v[52:55], v[124:127], v[172:175], v[52:55]
	v_mfma_i32_16x16x64_i8 v[80:83], v[132:135], v[172:175], v[80:83]
	v_mfma_i32_16x16x64_i8 v[48:51], v[124:127], v[180:183], v[48:51]
	v_mfma_i32_16x16x64_i8 v[72:75], v[132:135], v[180:183], v[72:75]
	s_waitcnt lgkmcnt(0)
	v_mfma_i32_16x16x64_i8 v[44:47], v[124:127], v[188:191], v[44:47]
	v_mfma_i32_16x16x64_i8 v[68:71], v[132:135], v[188:191], v[68:71]
	s_setprio 0
	s_setprio 1
	v_mfma_i32_16x16x64_i8 v[116:119], v[136:139], v[148:151], v[116:119]
	v_mfma_i32_16x16x64_i8 v[28:31], v[144:147], v[148:151], v[28:31]
	v_mfma_i32_16x16x64_i8 v[100:103], v[136:139], v[168:171], v[100:103]
	v_mfma_i32_16x16x64_i8 v[24:27], v[144:147], v[168:171], v[24:27]
	v_mfma_i32_16x16x64_i8 v[96:99], v[136:139], v[176:179], v[96:99]
	v_mfma_i32_16x16x64_i8 v[20:23], v[144:147], v[176:179], v[20:23]
	v_mfma_i32_16x16x64_i8 v[92:95], v[136:139], v[184:187], v[92:95]
	v_mfma_i32_16x16x64_i8 v[16:19], v[144:147], v[184:187], v[16:19]
	v_mfma_i32_16x16x64_i8 v[116:119], v[140:143], v[156:159], v[116:119]
	v_mfma_i32_16x16x64_i8 v[28:31], v[164:167], v[156:159], v[28:31]
	v_mfma_i32_16x16x64_i8 v[100:103], v[140:143], v[172:175], v[100:103]
	v_mfma_i32_16x16x64_i8 v[24:27], v[164:167], v[172:175], v[24:27]
	v_mfma_i32_16x16x64_i8 v[96:99], v[140:143], v[180:183], v[96:99]
	v_mfma_i32_16x16x64_i8 v[20:23], v[164:167], v[180:183], v[20:23]
	v_mfma_i32_16x16x64_i8 v[92:95], v[140:143], v[188:191], v[92:95]
	v_mfma_i32_16x16x64_i8 v[16:19], v[164:167], v[188:191], v[16:19]
	s_setprio 0
	s_barrier
; #define PG8_STAGE(bufoff, gbase, voff) do { _Pragma("unroll") for (int _i = 0; _i < 2; ++_i) glds16_s((gbase), (voff)[_i], ldsb + (unsigned)((bufoff) + _i * 8192)); } while (0)
; #define PG8_LDA(dst, b, h) do { _Pragma("unroll") for (int m = 0; m < 4; ++m) _Pragma("unroll") for (int k = 0; k < 2; ++k) dst[m][k] = *(const LAS h16x8*)(lds + PG8_SA(b, h) + aoff + m * 2048 + k * 1024); } while (0)
; #define PG8_MMA(ai, bj, At, Bt) do { __builtin_amdgcn_s_setprio(1); _Pragma("unroll") for (int m = 0; m < 4; ++m) _Pragma("unroll") for (int n = 0; n < 2; ++n) _Pragma("unroll") for (int k = 0; k < 2; ++k) \
;         acc[ai][bj][m][n] = mma_step<I8>(Bt[n][k], At[m][k], acc[ai][bj][m][n]); __builtin_amdgcn_s_setprio(0); } while (0)
; #define PG8_WAIT_V(n) asm volatile("s_waitcnt vmcnt(" #n ")" ::: "memory")
; #define PG8_WAIT_L(n) asm volatile("s_waitcnt lgkmcnt(" #n ")" ::: "memory")
; #define PG8_BAR __builtin_amdgcn_s_barrier()
; #define PG8_SCHED __builtin_amdgcn_sched_barrier(0)
; template <class Prob, class Epi, bool I8 = false, bool ALIGN_EPI = true, bool SP2 = true>
; __device__ __forceinline__ void gemm_phase(LAS unsigned char* lds, int wave, const Prob& P, const Epi& E) {
;     ...
;         for (int t = 0; t < nt; t += 2) {
;             const bool last = (t == nt - 2);
;             const char* a1 = cA + (size_t)(t + 1) * kstep;
;             const char* a2 = last ? nA : cA + (size_t)(t + 2) * kstep; const char* b2 = last ? nB : cB + (size_t)(t + 2) * kstep;
;             const char* a3 = a2 + kstep; const char* b3 = b2 + kstep;
;     ...
;             PG8_LDA(At, 1, 1); PG8_STAGE(PG8_SB(1, 0), b3, voffB); PG8_STAGE(PG8_SB(1, 1), b3 + hstepB, voffB); PG8_STAGE(PG8_SA(1, 0), a3, voffA);
;             PG8_WAIT_V(8); PG8_WAIT_L(0); PG8_BAR; PG8_MMA(1, 0, At, B0); PG8_MMA(1, 1, At, B1); PG8_BAR; PG8_SCHED;
	ds_read_b128 v[168:171], v211 offset:49152
	ds_read_b128 v[172:175], v211 offset:50176
	ds_read_b128 v[176:179], v211 offset:51200
	ds_read_b128 v[180:183], v211 offset:52224
	ds_read_b128 v[184:187], v211 offset:53248
	ds_read_b128 v[188:191], v211 offset:54272
	ds_read_b128 v[192:195], v211 offset:55296
	ds_read_b128 v[196:199], v211 offset:56320
	s_add_u32 s6, s68, 0x80
	s_addc_u32 s7, s69, 0
	s_mov_b32 s5, m0
	s_mov_b32 m0, s2
	s_nop 0
	global_load_lds_dwordx4 v217, s[6:7]
	s_mov_b32 m0, s5
	s_nop 0
	s_mov_b32 s5, m0
	s_mov_b32 m0, s85
	s_nop 0
	global_load_lds_dwordx4 v248, s[6:7]
	s_mov_b32 m0, s5
	s_add_u32 s6, s68, 0x40080
	s_addc_u32 s7, s69, 0
	s_mov_b32 s5, m0
	s_mov_b32 m0, s88
	s_nop 0
	global_load_lds_dwordx4 v217, s[6:7]
	s_mov_b32 m0, s5
	s_nop 0
	s_mov_b32 s5, m0
	s_mov_b32 m0, s89
	s_nop 0
	global_load_lds_dwordx4 v248, s[6:7]
	s_mov_b32 m0, s5
	s_nop 0
	s_mov_b32 s5, m0
	s_mov_b32 m0, s86
	s_nop 0
	global_load_lds_dwordx4 v250, s[60:61]
	s_mov_b32 m0, s5
	s_nop 0
	s_mov_b32 s5, m0
	s_mov_b32 m0, s87
	s_nop 0
	global_load_lds_dwordx4 v247, s[60:61]
	s_mov_b32 m0, s5
	s_waitcnt vmcnt(8)
	s_waitcnt lgkmcnt(0)
	s_barrier
	s_setprio 1
	s_waitcnt lgkmcnt(1)
	v_mfma_i32_16x16x64_i8 v[104:107], v[120:123], v[192:195], v[104:107]
	v_mfma_i32_16x16x64_i8 v[40:43], v[120:123], v[168:171], v[40:43]
	v_mfma_i32_16x16x64_i8 v[64:67], v[128:131], v[168:171], v[64:67]
	v_mfma_i32_16x16x64_i8 v[36:39], v[120:123], v[176:179], v[36:39]
	v_mfma_i32_16x16x64_i8 v[60:63], v[128:131], v[176:179], v[60:63]
	v_mfma_i32_16x16x64_i8 v[32:35], v[120:123], v[184:187], v[32:35]
	v_mfma_i32_16x16x64_i8 v[56:59], v[128:131], v[184:187], v[56:59]
	s_waitcnt lgkmcnt(0)
	v_mfma_i32_16x16x64_i8 v[156:159], v[124:127], v[196:199], v[104:107]
	v_mfma_i32_16x16x64_i8 v[104:107], v[128:131], v[192:195], v[112:115]
	v_mfma_i32_16x16x64_i8 v[40:43], v[124:127], v[172:175], v[40:43]
	v_mfma_i32_16x16x64_i8 v[64:67], v[132:135], v[172:175], v[64:67]
	v_mfma_i32_16x16x64_i8 v[36:39], v[124:127], v[180:183], v[36:39]
	v_mfma_i32_16x16x64_i8 v[60:63], v[132:135], v[180:183], v[60:63]
	v_mfma_i32_16x16x64_i8 v[32:35], v[124:127], v[188:191], v[32:35]
	v_mfma_i32_16x16x64_i8 v[56:59], v[132:135], v[188:191], v[56:59]
	v_mfma_i32_16x16x64_i8 v[148:151], v[132:135], v[196:199], v[104:107]
	s_setprio 0
	s_setprio 1
	v_mfma_i32_16x16x64_i8 v[88:91], v[136:139], v[168:171], v[88:91]
	v_mfma_i32_16x16x64_i8 v[12:15], v[144:147], v[168:171], v[12:15]
	v_mfma_i32_16x16x64_i8 v[84:87], v[136:139], v[176:179], v[84:87]
	v_mfma_i32_16x16x64_i8 v[8:11], v[144:147], v[176:179], v[8:11]
	v_mfma_i32_16x16x64_i8 v[76:79], v[136:139], v[184:187], v[76:79]
	v_mfma_i32_16x16x64_i8 v[4:7], v[144:147], v[184:187], v[4:7]
	v_mfma_i32_16x16x64_i8 v[104:107], v[136:139], v[192:195], v[108:111]
	v_mfma_i32_16x16x64_i8 v[0:3], v[144:147], v[192:195], v[0:3]
	v_mfma_i32_16x16x64_i8 v[88:91], v[140:143], v[172:175], v[88:91]
	v_mfma_i32_16x16x64_i8 v[12:15], v[164:167], v[172:175], v[12:15]
	v_mfma_i32_16x16x64_i8 v[84:87], v[140:143], v[180:183], v[84:87]
	v_mfma_i32_16x16x64_i8 v[8:11], v[164:167], v[180:183], v[8:11]
	v_mfma_i32_16x16x64_i8 v[76:79], v[140:143], v[188:191], v[76:79]
	v_mfma_i32_16x16x64_i8 v[4:7], v[164:167], v[188:191], v[4:7]
	v_mfma_i32_16x16x64_i8 v[108:111], v[140:143], v[196:199], v[104:107]
	v_mfma_i32_16x16x64_i8 v[0:3], v[164:167], v[196:199], v[0:3]
	s_setprio 0
	s_barrier
	s_add_i32 s4, s4, 2
	s_add_u32 vcc_lo, vcc_lo, 0x100
	s_addc_u32 vcc_hi, vcc_hi, 0
	s_add_u32 s0, s0, 0x100
	s_addc_u32 s1, s1, 0
	s_add_u32 s44, s44, 0x100
	s_addc_u32 s45, s45, 0
	s_cmp_gt_u32 s4, 13

; #define PG8_STAGE(bufoff, gbase, voff) do { _Pragma("unroll") for (int _i = 0; _i < 2; ++_i) glds16_s((gbase), (voff)[_i], ldsb + (unsigned)((bufoff) + _i * 8192)); } while (0)
; #define PG8_LDA(dst, b, h) do { _Pragma("unroll") for (int m = 0; m < 4; ++m) _Pragma("unroll") for (int k = 0; k < 2; ++k) dst[m][k] = *(const LAS h16x8*)(lds + PG8_SA(b, h) + aoff + m * 2048 + k * 1024); } while (0)
; #define PG8_LDB(dst, b, h) do { _Pragma("unroll") for (int n = 0; n < 2; ++n) _Pragma("unroll") for (int k = 0; k < 2; ++k) dst[n][k] = *(const LAS h16x8*)(lds + PG8_SB(b, h) + boff + n * 2048 + k * 1024); } while (0)
; #define PG8_MMA(ai, bj, At, Bt) do { __builtin_amdgcn_s_setprio(1); _Pragma("unroll") for (int m = 0; m < 4; ++m) _Pragma("unroll") for (int n = 0; n < 2; ++n) _Pragma("unroll") for (int k = 0; k < 2; ++k) \
;         acc[ai][bj][m][n] = mma_step<I8>(Bt[n][k], At[m][k], acc[ai][bj][m][n]); __builtin_amdgcn_s_setprio(0); } while (0)
; #define PG8_WAIT_V(n) asm volatile("s_waitcnt vmcnt(" #n ")" ::: "memory")
; #define PG8_WAIT_L(n) asm volatile("s_waitcnt lgkmcnt(" #n ")" ::: "memory")
; template <class Prob, class Epi, bool I8 = false, bool ALIGN_EPI = true, bool SP2 = true>
; __device__ __forceinline__ void gemm_phase(LAS unsigned char* lds, int wave, const Prob& P, const Epi& E) {
;     ...
;     for (;;) {
;         const bool has_next = P.next(ui + 1, nxt);
;         const char* nA = has_next ? P.a_tile(nxt) : cA; const char* nB = has_next ? P.b_tile(nxt) : cB;
;         for (int t = 0; t < nt; t += 2) {
;             const bool last = (t == nt - 2);
;             const char* a1 = cA + (size_t)(t + 1) * kstep;
;             const char* a2 = last ? nA : cA + (size_t)(t + 2) * kstep; const char* b2 = last ? nB : cB + (size_t)(t + 2) * kstep;
;             const char* a3 = a2 + kstep; const char* b3 = b2 + kstep;
;             if constexpr (SP2) {
;             PG8_LDB(B0, 0, 0); PG8_LDB(B1, 0, 1); PG8_SCHED; PG8_LDA(At, 0, 0); PG8_STAGE(PG8_SA(1, 1), a1 + hstepA, voffA);
;             PG8_WAIT_V(8); PG8_WAIT_L(0); PG8_BAR; PG8_MMA(0, 0, At, B0); PG8_MMA(0, 1, At, B1); PG8_BAR; PG8_SCHED;
;             PG8_LDA(At, 0, 1); PG8_STAGE(PG8_SB(0, 0), b2, voffB); PG8_STAGE(PG8_SB(0, 1), b2 + hstepB, voffB); PG8_STAGE(PG8_SA(0, 0), a2, voffA);
;             PG8_WAIT_V(8); PG8_WAIT_L(0); PG8_BAR; PG8_MMA(1, 0, At, B0); PG8_MMA(1, 1, At, B1); PG8_BAR; PG8_SCHED;
.LBB0_1215:
	s_add_u32 s74, s44, 0x100
	s_addc_u32 s75, s45, 0
	s_add_u32 s0, s14, 0x100
	s_addc_u32 s1, s15, 0
	s_add_u32 s14, s44, 0xb0080
	s_addc_u32 s15, s45, 0
	s_mov_b32 s4, -2
.Lpeel_1216:
	v_add_u32_e32 v140, 0x10000, v179
	v_add_u32_e32 v156, 0x14000, v179
	ds_read_b128 v[100:103], v140
	ds_read_b128 v[108:111], v140 offset:1024
	ds_read_b128 v[136:139], v140 offset:2048
	ds_read_b128 v[140:143], v140 offset:3072
	ds_read_b128 v[144:147], v156
	ds_read_b128 v[148:151], v156 offset:1024
	ds_read_b128 v[152:155], v156 offset:2048
	ds_read_b128 v[156:159], v156 offset:3072
	s_cmp_eq_u32 s4, 40
	s_cselect_b32 s60, s38, s74
	s_cselect_b32 s61, s39, s75
	s_cselect_b32 s56, s50, s0
	s_cselect_b32 s57, s51, s1
	s_add_u32 s44, s60, 0x80
	s_addc_u32 s45, s61, 0
	ds_read_b128 v[164:167], v185
	ds_read_b128 v[168:171], v185 offset:1024
	ds_read_b128 v[172:175], v185 offset:2048
	ds_read_b128 v[180:183], v185 offset:3072
	ds_read_b128 v[186:189], v185 offset:4096
	ds_read_b128 v[190:193], v185 offset:5120
	ds_read_b128 v[194:197], v185 offset:6144
	ds_read_b128 v[198:201], v185 offset:7168
	s_mov_b32 s5, m0
	s_mov_b32 m0, s86
	s_nop 0
	global_load_lds_dwordx4 v160, s[14:15]
	s_mov_b32 m0, s5
	s_nop 0
	s_mov_b32 s5, m0
	s_mov_b32 m0, s87
	s_nop 0
	global_load_lds_dwordx4 v162, s[14:15]
	s_mov_b32 m0, s5
	s_waitcnt vmcnt(8)
	s_waitcnt lgkmcnt(0)
	s_barrier
	s_setprio 1
	s_waitcnt lgkmcnt(7)
	v_mfma_i32_16x16x64_i8 v[132:135], v[100:103], v[164:167], 0
	v_mfma_i32_16x16x64_i8 v[128:131], v[136:139], v[164:167], 0
	s_waitcnt lgkmcnt(5)
	v_mfma_i32_16x16x64_i8 v[124:127], v[100:103], v[172:175], 0
	v_mfma_i32_16x16x64_i8 v[120:123], v[136:139], v[172:175], 0
	s_waitcnt lgkmcnt(3)
	v_mfma_i32_16x16x64_i8 v[116:119], v[100:103], v[186:189], 0
	v_mfma_i32_16x16x64_i8 v[112:115], v[136:139], v[186:189], 0
	s_waitcnt lgkmcnt(1)
	v_mfma_i32_16x16x64_i8 v[104:107], v[100:103], v[194:197], 0
	v_mfma_i32_16x16x64_i8 v[96:99], v[136:139], v[194:197], 0
	v_mfma_i32_16x16x64_i8 v[132:135], v[108:111], v[168:171], v[132:135]
	v_mfma_i32_16x16x64_i8 v[128:131], v[140:143], v[168:171], v[128:131]
	v_mfma_i32_16x16x64_i8 v[124:127], v[108:111], v[180:183], v[124:127]
	v_mfma_i32_16x16x64_i8 v[120:123], v[140:143], v[180:183], v[120:123]
	v_mfma_i32_16x16x64_i8 v[116:119], v[108:111], v[190:193], v[116:119]
	v_mfma_i32_16x16x64_i8 v[112:115], v[140:143], v[190:193], v[112:115]
	s_waitcnt lgkmcnt(0)
	v_mfma_i32_16x16x64_i8 v[104:107], v[108:111], v[198:201], v[104:107]
	v_mfma_i32_16x16x64_i8 v[96:99], v[140:143], v[198:201], v[96:99]
	s_setprio 0
	s_setprio 1
	v_mfma_i32_16x16x64_i8 v[60:63], v[144:147], v[164:167], 0
	v_mfma_i32_16x16x64_i8 v[56:59], v[152:155], v[164:167], 0
	v_mfma_i32_16x16x64_i8 v[52:55], v[144:147], v[172:175], 0
	v_mfma_i32_16x16x64_i8 v[48:51], v[152:155], v[172:175], 0
	v_mfma_i32_16x16x64_i8 v[44:47], v[144:147], v[186:189], 0
	v_mfma_i32_16x16x64_i8 v[40:43], v[152:155], v[186:189], 0
	v_mfma_i32_16x16x64_i8 v[36:39], v[144:147], v[194:197], 0
	v_mfma_i32_16x16x64_i8 v[32:35], v[152:155], v[194:197], 0
	v_mfma_i32_16x16x64_i8 v[60:63], v[148:151], v[168:171], v[60:63]
	v_mfma_i32_16x16x64_i8 v[56:59], v[156:159], v[168:171], v[56:59]
	v_mfma_i32_16x16x64_i8 v[52:55], v[148:151], v[180:183], v[52:55]
	v_mfma_i32_16x16x64_i8 v[48:51], v[156:159], v[180:183], v[48:51]
	v_mfma_i32_16x16x64_i8 v[44:47], v[148:151], v[190:193], v[44:47]
	v_mfma_i32_16x16x64_i8 v[40:43], v[156:159], v[190:193], v[40:43]
	v_mfma_i32_16x16x64_i8 v[36:39], v[148:151], v[198:201], v[36:39]
	v_mfma_i32_16x16x64_i8 v[32:35], v[156:159], v[198:201], v[32:35]
	s_setprio 0
	s_barrier
	ds_read_b128 v[164:167], v185 offset:16384
	ds_read_b128 v[168:171], v185 offset:17408
	ds_read_b128 v[172:175], v185 offset:18432
	ds_read_b128 v[180:183], v185 offset:19456
	ds_read_b128 v[186:189], v185 offset:20480
	ds_read_b128 v[190:193], v185 offset:21504
	ds_read_b128 v[194:197], v185 offset:22528
	ds_read_b128 v[198:201], v185 offset:23552
	s_mov_b32 s5, m0
	s_mov_b32 m0, s41
	s_nop 0
	global_load_lds_dwordx4 v161, s[56:57]
	s_mov_b32 m0, s5
	s_add_u32 s6, s56, 0xb0000
	s_mov_b32 s5, m0
	s_mov_b32 m0, s62
	s_nop 0
	global_load_lds_dwordx4 v163, s[56:57]
	s_mov_b32 m0, s5
	s_addc_u32 s7, s57, 0
	s_mov_b32 s5, m0
	s_mov_b32 m0, s63
	s_nop 0
	global_load_lds_dwordx4 v161, s[6:7]
	s_mov_b32 m0, s5
	s_nop 0
	s_mov_b32 s5, m0
	s_mov_b32 m0, s64
	s_nop 0
	global_load_lds_dwordx4 v163, s[6:7]
	s_mov_b32 m0, s5
	s_nop 0
	s_mov_b32 s5, m0
	s_mov_b32 m0, s40
	s_nop 0
	global_load_lds_dwordx4 v160, s[60:61]
	s_mov_b32 m0, s5
	s_nop 0
	s_mov_b32 s5, m0
	s_mov_b32 m0, s68
	s_nop 0
	global_load_lds_dwordx4 v162, s[60:61]
	s_mov_b32 m0, s5
	s_waitcnt vmcnt(8)
	s_waitcnt lgkmcnt(0)
	s_barrier
; #define PG8_STAGE(bufoff, gbase, voff) do { _Pragma("unroll") for (int _i = 0; _i < 2; ++_i) glds16_s((gbase), (voff)[_i], ldsb + (unsigned)((bufoff) + _i * 8192)); } while (0)
; #define PG8_LDA(dst, b, h) do { _Pragma("unroll") for (int m = 0; m < 4; ++m) _Pragma("unroll") for (int k = 0; k < 2; ++k) dst[m][k] = *(const LAS h16x8*)(lds + PG8_SA(b, h) + aoff + m * 2048 + k * 1024); } while (0)
; #define PG8_LDB(dst, b, h) do { _Pragma("unroll") for (int n = 0; n < 2; ++n) _Pragma("unroll") for (int k = 0; k < 2; ++k) dst[n][k] = *(const LAS h16x8*)(lds + PG8_SB(b, h) + boff + n * 2048 + k * 1024); } while (0)
; #define PG8_MMA(ai, bj, At, Bt) do { __builtin_amdgcn_s_setprio(1); _Pragma("unroll") for (int m = 0; m < 4; ++m) _Pragma("unroll") for (int n = 0; n < 2; ++n) _Pragma("unroll") for (int k = 0; k < 2; ++k) \
;         acc[ai][bj][m][n] = mma_step<I8>(Bt[n][k], At[m][k], acc[ai][bj][m][n]); __builtin_amdgcn_s_setprio(0); } while (0)
; #define PG8_WAIT_V(n) asm volatile("s_waitcnt vmcnt(" #n ")" ::: "memory")
; #define PG8_WAIT_L(n) asm volatile("s_waitcnt lgkmcnt(" #n ")" ::: "memory")
; #define PG8_BAR __builtin_amdgcn_s_barrier()
; #define PG8_SCHED __builtin_amdgcn_sched_barrier(0)
; template <class Prob, class Epi, bool I8 = false, bool ALIGN_EPI = true, bool SP2 = true>
; __device__ __forceinline__ void gemm_phase(LAS unsigned char* lds, int wave, const Prob& P, const Epi& E) {
;     ...
;             PG8_WAIT_V(8); PG8_WAIT_L(0); PG8_BAR; PG8_MMA(1, 0, At, B0); PG8_MMA(1, 1, At, B1); PG8_BAR; PG8_SCHED;
;             PG8_LDB(B0, 1, 0); PG8_LDB(B1, 1, 1); PG8_SCHED; PG8_LDA(At, 1, 0); PG8_STAGE(PG8_SA(0, 1), a2 + hstepA, voffA);
;             PG8_WAIT_V(8); PG8_WAIT_L(0); PG8_BAR; PG8_MMA(0, 0, At, B0); PG8_MMA(0, 1, At, B1); PG8_BAR; PG8_SCHED;
;             PG8_LDA(At, 1, 1); PG8_STAGE(PG8_SB(1, 0), b3, voffB); PG8_STAGE(PG8_SB(1, 1), b3 + hstepB, voffB); PG8_STAGE(PG8_SA(1, 0), a3, voffA);
	s_setprio 1
	s_waitcnt lgkmcnt(7)
	v_mfma_i32_16x16x64_i8 v[92:95], v[100:103], v[164:167], 0
	v_mfma_i32_16x16x64_i8 v[88:91], v[136:139], v[164:167], 0
	s_waitcnt lgkmcnt(5)
	v_mfma_i32_16x16x64_i8 v[84:87], v[100:103], v[172:175], 0
	v_mfma_i32_16x16x64_i8 v[80:83], v[136:139], v[172:175], 0
	s_waitcnt lgkmcnt(3)
	v_mfma_i32_16x16x64_i8 v[76:79], v[100:103], v[186:189], 0
	v_mfma_i32_16x16x64_i8 v[72:75], v[136:139], v[186:189], 0
	s_waitcnt lgkmcnt(1)
	v_mfma_i32_16x16x64_i8 v[68:71], v[100:103], v[194:197], 0
	v_mfma_i32_16x16x64_i8 v[64:67], v[136:139], v[194:197], 0
	v_mfma_i32_16x16x64_i8 v[92:95], v[108:111], v[168:171], v[92:95]
	v_mfma_i32_16x16x64_i8 v[88:91], v[140:143], v[168:171], v[88:91]
	v_mfma_i32_16x16x64_i8 v[84:87], v[108:111], v[180:183], v[84:87]
	v_mfma_i32_16x16x64_i8 v[80:83], v[140:143], v[180:183], v[80:83]
	v_mfma_i32_16x16x64_i8 v[76:79], v[108:111], v[190:193], v[76:79]
	v_mfma_i32_16x16x64_i8 v[72:75], v[140:143], v[190:193], v[72:75]
	s_waitcnt lgkmcnt(0)
	v_mfma_i32_16x16x64_i8 v[68:71], v[108:111], v[198:201], v[68:71]
	v_mfma_i32_16x16x64_i8 v[64:67], v[140:143], v[198:201], v[64:67]
	s_setprio 0
	s_setprio 1
	v_mfma_i32_16x16x64_i8 v[28:31], v[144:147], v[164:167], 0
	v_mfma_i32_16x16x64_i8 v[24:27], v[152:155], v[164:167], 0
	v_mfma_i32_16x16x64_i8 v[20:23], v[144:147], v[172:175], 0
	v_mfma_i32_16x16x64_i8 v[16:19], v[152:155], v[172:175], 0
	v_mfma_i32_16x16x64_i8 v[12:15], v[144:147], v[186:189], 0
	v_mfma_i32_16x16x64_i8 v[8:11], v[152:155], v[186:189], 0
	v_mfma_i32_16x16x64_i8 v[4:7], v[144:147], v[194:197], 0
	v_mfma_i32_16x16x64_i8 v[0:3], v[152:155], v[194:197], 0
	v_mfma_i32_16x16x64_i8 v[28:31], v[148:151], v[168:171], v[28:31]
	v_mfma_i32_16x16x64_i8 v[24:27], v[156:159], v[168:171], v[24:27]
	v_mfma_i32_16x16x64_i8 v[20:23], v[148:151], v[180:183], v[20:23]
	v_mfma_i32_16x16x64_i8 v[16:19], v[156:159], v[180:183], v[16:19]
	v_mfma_i32_16x16x64_i8 v[12:15], v[148:151], v[190:193], v[12:15]
	v_mfma_i32_16x16x64_i8 v[8:11], v[156:159], v[190:193], v[8:11]
	v_mfma_i32_16x16x64_i8 v[4:7], v[148:151], v[198:201], v[4:7]
	v_mfma_i32_16x16x64_i8 v[0:3], v[156:159], v[198:201], v[0:3]
	s_setprio 0
	s_barrier
	v_add_u32_e32 v140, 0x18000, v179
	v_add_u32_e32 v156, 0x1c000, v179
	ds_read_b128 v[100:103], v140
	ds_read_b128 v[108:111], v140 offset:1024
	ds_read_b128 v[136:139], v140 offset:2048
	ds_read_b128 v[140:143], v140 offset:3072
	ds_read_b128 v[144:147], v156
	ds_read_b128 v[148:151], v156 offset:1024
	ds_read_b128 v[152:155], v156 offset:2048
	ds_read_b128 v[156:159], v156 offset:3072
	ds_read_b128 v[164:167], v185 offset:32768
	ds_read_b128 v[168:171], v185 offset:33792
	ds_read_b128 v[172:175], v185 offset:34816
	ds_read_b128 v[180:183], v185 offset:35840
	ds_read_b128 v[186:189], v185 offset:36864
	ds_read_b128 v[190:193], v185 offset:37888
	ds_read_b128 v[194:197], v185 offset:38912
	ds_read_b128 v[198:201], v185 offset:39936
	s_add_u32 s6, s60, 0xb0000
	s_addc_u32 s7, s61, 0
	s_mov_b32 s5, m0
	s_mov_b32 m0, s69
	s_nop 0
	global_load_lds_dwordx4 v160, s[6:7]
	s_mov_b32 m0, s5
	s_nop 0
	s_mov_b32 s5, m0
	s_mov_b32 m0, s76
	s_nop 0
	global_load_lds_dwordx4 v162, s[6:7]
	s_mov_b32 m0, s5
	s_waitcnt vmcnt(8)
	s_waitcnt lgkmcnt(0)
	s_barrier
	s_setprio 1
	s_waitcnt lgkmcnt(7)
	v_mfma_i32_16x16x64_i8 v[132:135], v[100:103], v[164:167], v[132:135]
	v_mfma_i32_16x16x64_i8 v[128:131], v[136:139], v[164:167], v[128:131]
	s_waitcnt lgkmcnt(5)
	v_mfma_i32_16x16x64_i8 v[124:127], v[100:103], v[172:175], v[124:127]
	v_mfma_i32_16x16x64_i8 v[120:123], v[136:139], v[172:175], v[120:123]
	s_waitcnt lgkmcnt(3)
	v_mfma_i32_16x16x64_i8 v[116:119], v[100:103], v[186:189], v[116:119]
	v_mfma_i32_16x16x64_i8 v[112:115], v[136:139], v[186:189], v[112:115]
	s_waitcnt lgkmcnt(1)
	v_mfma_i32_16x16x64_i8 v[104:107], v[100:103], v[194:197], v[104:107]
	v_mfma_i32_16x16x64_i8 v[96:99], v[136:139], v[194:197], v[96:99]
	v_mfma_i32_16x16x64_i8 v[132:135], v[108:111], v[168:171], v[132:135]
	v_mfma_i32_16x16x64_i8 v[128:131], v[140:143], v[168:171], v[128:131]
	v_mfma_i32_16x16x64_i8 v[124:127], v[108:111], v[180:183], v[124:127]
	v_mfma_i32_16x16x64_i8 v[120:123], v[140:143], v[180:183], v[120:123]
	v_mfma_i32_16x16x64_i8 v[116:119], v[108:111], v[190:193], v[116:119]
	v_mfma_i32_16x16x64_i8 v[112:115], v[140:143], v[190:193], v[112:115]
	s_waitcnt lgkmcnt(0)
	v_mfma_i32_16x16x64_i8 v[104:107], v[108:111], v[198:201], v[104:107]
	v_mfma_i32_16x16x64_i8 v[96:99], v[140:143], v[198:201], v[96:99]
	s_setprio 0
	s_setprio 1
	v_mfma_i32_16x16x64_i8 v[60:63], v[144:147], v[164:167], v[60:63]
	v_mfma_i32_16x16x64_i8 v[56:59], v[152:155], v[164:167], v[56:59]
	v_mfma_i32_16x16x64_i8 v[52:55], v[144:147], v[172:175], v[52:55]
	v_mfma_i32_16x16x64_i8 v[48:51], v[152:155], v[172:175], v[48:51]
	v_mfma_i32_16x16x64_i8 v[44:47], v[144:147], v[186:189], v[44:47]
	v_mfma_i32_16x16x64_i8 v[40:43], v[152:155], v[186:189], v[40:43]
	v_mfma_i32_16x16x64_i8 v[36:39], v[144:147], v[194:197], v[36:39]
	v_mfma_i32_16x16x64_i8 v[32:35], v[152:155], v[194:197], v[32:35]
	v_mfma_i32_16x16x64_i8 v[60:63], v[148:151], v[168:171], v[60:63]
	v_mfma_i32_16x16x64_i8 v[56:59], v[156:159], v[168:171], v[56:59]
	v_mfma_i32_16x16x64_i8 v[52:55], v[148:151], v[180:183], v[52:55]
	v_mfma_i32_16x16x64_i8 v[48:51], v[156:159], v[180:183], v[48:51]
	v_mfma_i32_16x16x64_i8 v[44:47], v[148:151], v[190:193], v[44:47]
	v_mfma_i32_16x16x64_i8 v[40:43], v[156:159], v[190:193], v[40:43]
	v_mfma_i32_16x16x64_i8 v[36:39], v[148:151], v[198:201], v[36:39]
	v_mfma_i32_16x16x64_i8 v[32:35], v[156:159], v[198:201], v[32:35]
	s_setprio 0
	s_barrier
; #define PG8_STAGE(bufoff, gbase, voff) do { _Pragma("unroll") for (int _i = 0; _i < 2; ++_i) glds16_s((gbase), (voff)[_i], ldsb + (unsigned)((bufoff) + _i * 8192)); } while (0)
; #define PG8_LDA(dst, b, h) do { _Pragma("unroll") for (int m = 0; m < 4; ++m) _Pragma("unroll") for (int k = 0; k < 2; ++k) dst[m][k] = *(const LAS h16x8*)(lds + PG8_SA(b, h) + aoff + m * 2048 + k * 1024); } while (0)
; #define PG8_MMA(ai, bj, At, Bt) do { __builtin_amdgcn_s_setprio(1); _Pragma("unroll") for (int m = 0; m < 4; ++m) _Pragma("unroll") for (int n = 0; n < 2; ++n) _Pragma("unroll") for (int k = 0; k < 2; ++k) \
;         acc[ai][bj][m][n] = mma_step<I8>(Bt[n][k], At[m][k], acc[ai][bj][m][n]); __builtin_amdgcn_s_setprio(0); } while (0)
; #define PG8_WAIT_V(n) asm volatile("s_waitcnt vmcnt(" #n ")" ::: "memory")
; #define PG8_WAIT_L(n) asm volatile("s_waitcnt lgkmcnt(" #n ")" ::: "memory")
; #define PG8_BAR __builtin_amdgcn_s_barrier()
; #define PG8_SCHED __builtin_amdgcn_sched_barrier(0)
; template <class Prob, class Epi, bool I8 = false, bool ALIGN_EPI = true, bool SP2 = true>
; __device__ __forceinline__ void gemm_phase(LAS unsigned char* lds, int wave, const Prob& P, const Epi& E) {
;     ...
;         for (int t = 0; t < nt; t += 2) {
;             const bool last = (t == nt - 2);
;             const char* a1 = cA + (size_t)(t + 1) * kstep;
;             const char* a2 = last ? nA : cA + (size_t)(t + 2) * kstep; const char* b2 = last ? nB : cB + (size_t)(t + 2) * kstep;
;             const char* a3 = a2 + kstep; const char* b3 = b2 + kstep;
;     ...
;             PG8_LDA(At, 1, 1); PG8_STAGE(PG8_SB(1, 0), b3, voffB); PG8_STAGE(PG8_SB(1, 1), b3 + hstepB, voffB); PG8_STAGE(PG8_SA(1, 0), a3, voffA);
;             PG8_WAIT_V(8); PG8_WAIT_L(0); PG8_BAR; PG8_MMA(1, 0, At, B0); PG8_MMA(1, 1, At, B1); PG8_BAR; PG8_SCHED;
	ds_read_b128 v[164:167], v185 offset:49152
	ds_read_b128 v[168:171], v185 offset:50176
	ds_read_b128 v[172:175], v185 offset:51200
	ds_read_b128 v[180:183], v185 offset:52224
	ds_read_b128 v[186:189], v185 offset:53248
	ds_read_b128 v[190:193], v185 offset:54272
	ds_read_b128 v[194:197], v185 offset:55296
	ds_read_b128 v[198:201], v185 offset:56320
	s_add_u32 s6, s56, 0x80
	s_addc_u32 s7, s57, 0
	s_mov_b32 s5, m0
	s_mov_b32 m0, s80
	s_nop 0
	global_load_lds_dwordx4 v161, s[6:7]
	s_mov_b32 m0, s5
	s_nop 0
	s_mov_b32 s5, m0
	s_mov_b32 m0, s81
	s_nop 0
	global_load_lds_dwordx4 v163, s[6:7]
	s_mov_b32 m0, s5
	s_add_u32 s6, s56, 0xb0080
	s_addc_u32 s7, s57, 0
	s_mov_b32 s5, m0
	s_mov_b32 m0, s84
	s_nop 0
	global_load_lds_dwordx4 v161, s[6:7]
	s_mov_b32 m0, s5
	s_nop 0
	s_mov_b32 s5, m0
	s_mov_b32 m0, s85
	s_nop 0
	global_load_lds_dwordx4 v163, s[6:7]
	s_mov_b32 m0, s5
	s_nop 0
	s_mov_b32 s5, m0
	s_mov_b32 m0, s82
	s_nop 0
	global_load_lds_dwordx4 v160, s[44:45]
	s_mov_b32 m0, s5
	s_nop 0
	s_mov_b32 s5, m0
	s_mov_b32 m0, s83
	s_nop 0
	global_load_lds_dwordx4 v162, s[44:45]
	s_mov_b32 m0, s5
	s_waitcnt vmcnt(8)
	s_waitcnt lgkmcnt(0)
	s_barrier
	s_setprio 1
	s_waitcnt lgkmcnt(7)
	v_mfma_i32_16x16x64_i8 v[92:95], v[100:103], v[164:167], v[92:95]
	v_mfma_i32_16x16x64_i8 v[88:91], v[136:139], v[164:167], v[88:91]
	s_waitcnt lgkmcnt(5)
	v_mfma_i32_16x16x64_i8 v[84:87], v[100:103], v[172:175], v[84:87]
	v_mfma_i32_16x16x64_i8 v[80:83], v[136:139], v[172:175], v[80:83]
	s_waitcnt lgkmcnt(3)
	v_mfma_i32_16x16x64_i8 v[76:79], v[100:103], v[186:189], v[76:79]
	v_mfma_i32_16x16x64_i8 v[72:75], v[136:139], v[186:189], v[72:75]
	s_waitcnt lgkmcnt(1)
	v_mfma_i32_16x16x64_i8 v[68:71], v[100:103], v[194:197], v[68:71]
	v_mfma_i32_16x16x64_i8 v[64:67], v[136:139], v[194:197], v[64:67]
	v_mfma_i32_16x16x64_i8 v[92:95], v[108:111], v[168:171], v[92:95]
	v_mfma_i32_16x16x64_i8 v[88:91], v[140:143], v[168:171], v[88:91]
	v_mfma_i32_16x16x64_i8 v[84:87], v[108:111], v[180:183], v[84:87]
	v_mfma_i32_16x16x64_i8 v[80:83], v[140:143], v[180:183], v[80:83]
	v_mfma_i32_16x16x64_i8 v[76:79], v[108:111], v[190:193], v[76:79]
	v_mfma_i32_16x16x64_i8 v[72:75], v[140:143], v[190:193], v[72:75]
	s_waitcnt lgkmcnt(0)
	v_mfma_i32_16x16x64_i8 v[68:71], v[108:111], v[198:201], v[68:71]
	v_mfma_i32_16x16x64_i8 v[64:67], v[140:143], v[198:201], v[64:67]
	s_setprio 0
	s_setprio 1
	v_mfma_i32_16x16x64_i8 v[28:31], v[144:147], v[164:167], v[28:31]
	v_mfma_i32_16x16x64_i8 v[24:27], v[152:155], v[164:167], v[24:27]
	v_mfma_i32_16x16x64_i8 v[20:23], v[144:147], v[172:175], v[20:23]
	v_mfma_i32_16x16x64_i8 v[16:19], v[152:155], v[172:175], v[16:19]
	v_mfma_i32_16x16x64_i8 v[12:15], v[144:147], v[186:189], v[12:15]
	v_mfma_i32_16x16x64_i8 v[8:11], v[152:155], v[186:189], v[8:11]
	v_mfma_i32_16x16x64_i8 v[4:7], v[144:147], v[194:197], v[4:7]
	v_mfma_i32_16x16x64_i8 v[0:3], v[152:155], v[194:197], v[0:3]
	v_mfma_i32_16x16x64_i8 v[28:31], v[148:151], v[168:171], v[28:31]
	v_mfma_i32_16x16x64_i8 v[24:27], v[156:159], v[168:171], v[24:27]
	v_mfma_i32_16x16x64_i8 v[20:23], v[148:151], v[180:183], v[20:23]
	v_mfma_i32_16x16x64_i8 v[16:19], v[156:159], v[180:183], v[16:19]
	v_mfma_i32_16x16x64_i8 v[12:15], v[148:151], v[190:193], v[12:15]
	v_mfma_i32_16x16x64_i8 v[8:11], v[156:159], v[190:193], v[8:11]
	v_mfma_i32_16x16x64_i8 v[4:7], v[148:151], v[198:201], v[4:7]
	v_mfma_i32_16x16x64_i8 v[0:3], v[156:159], v[198:201], v[0:3]
	s_setprio 0
	s_barrier
	s_add_i32 s4, s4, 2
	s_add_u32 s74, s74, 0x100
	s_addc_u32 s75, s75, 0
	s_add_u32 s0, s0, 0x100
	s_addc_u32 s1, s1, 0
	s_add_u32 s14, s14, 0x100
	s_addc_u32 s15, s15, 0
	s_cmp_gt_u32 s4, 41
